# nt on more read-once loads: kv_prep K/V rows, GLU and fourier-map epilogue gates, latent-attention Q rows
# speedup vs baseline: 1.0136x; 1.0029x over previous
.LBB0_282:
	s_add_i32 s22, s51, s52
	s_ashr_i32 s23, s22, 31
	s_lshl_b64 s[24:25], s[22:23], 12
	v_cmp_ne_u32_e64 s[4:5], 1, v215
	s_andn2_b64 vcc, exec, s[18:19]
	s_mov_b64 s[26:27], -1
	s_cbranch_vccnz .LBB0_291
	v_lshl_add_u64 v[0:1], s[24:25], 1, v[154:155]
	global_load_dwordx4 v[4:7], v[0:1], off nt
	global_load_dwordx4 v[12:15], v[0:1], off offset:1024 nt
	global_load_dwordx4 v[20:23], v[0:1], off offset:2048 nt
	global_load_dwordx4 v[24:27], v[0:1], off offset:3072 nt
	v_add_co_u32_e32 v0, vcc, s46, v0
	s_nop 1
	v_addc_co_u32_e32 v1, vcc, 0, v1, vcc
	global_load_dwordx4 v[32:35], v[0:1], off nt
	global_load_dwordx4 v[40:43], v[0:1], off offset:1024 nt
	global_load_dwordx4 v[44:47], v[0:1], off offset:2048 nt
	global_load_dwordx4 v[48:51], v[0:1], off offset:3072 nt
	s_waitcnt vmcnt(0)
	v_lshlrev_b32_e32 v0, 16, v4
	v_and_b32_e32 v1, 0xffff0000, v4
	v_lshlrev_b32_e32 v2, 16, v5
	v_and_b32_e32 v3, 0xffff0000, v5
	v_lshlrev_b32_e32 v4, 16, v6
	v_and_b32_e32 v5, 0xffff0000, v6
	v_lshlrev_b32_e32 v6, 16, v7
	v_and_b32_e32 v7, 0xffff0000, v7
	s_waitcnt vmcnt(6)
	v_lshlrev_b32_e32 v8, 16, v12
	v_and_b32_e32 v9, 0xffff0000, v12
	v_lshlrev_b32_e32 v10, 16, v13
	v_and_b32_e32 v11, 0xffff0000, v13
	v_lshlrev_b32_e32 v12, 16, v14
	v_and_b32_e32 v13, 0xffff0000, v14
	v_lshlrev_b32_e32 v14, 16, v15
	v_and_b32_e32 v15, 0xffff0000, v15
	s_waitcnt vmcnt(5)
	v_lshlrev_b32_e32 v16, 16, v20
	v_and_b32_e32 v17, 0xffff0000, v20
	v_lshlrev_b32_e32 v18, 16, v21
	v_and_b32_e32 v19, 0xffff0000, v21
	v_lshlrev_b32_e32 v20, 16, v22
	v_and_b32_e32 v21, 0xffff0000, v22
	v_lshlrev_b32_e32 v22, 16, v23
	v_and_b32_e32 v23, 0xffff0000, v23
	s_waitcnt vmcnt(4)
	v_lshlrev_b32_e32 v28, 16, v24
	v_and_b32_e32 v29, 0xffff0000, v24
	v_lshlrev_b32_e32 v30, 16, v25
	v_and_b32_e32 v31, 0xffff0000, v25
	v_lshlrev_b32_e32 v24, 16, v26
	v_and_b32_e32 v25, 0xffff0000, v26
	v_lshlrev_b32_e32 v26, 16, v27
	v_and_b32_e32 v27, 0xffff0000, v27
	s_waitcnt vmcnt(3)
	v_lshlrev_b32_e32 v36, 16, v32
	v_and_b32_e32 v37, 0xffff0000, v32
	v_lshlrev_b32_e32 v38, 16, v33
	v_and_b32_e32 v39, 0xffff0000, v33
	v_lshlrev_b32_e32 v52, 16, v34
	v_and_b32_e32 v53, 0xffff0000, v34
	v_lshlrev_b32_e32 v54, 16, v35
	v_and_b32_e32 v55, 0xffff0000, v35
	s_waitcnt vmcnt(2)
	v_lshlrev_b32_e32 v32, 16, v40
	v_and_b32_e32 v33, 0xffff0000, v40
	v_lshlrev_b32_e32 v34, 16, v41
	v_and_b32_e32 v35, 0xffff0000, v41
	v_lshlrev_b32_e32 v40, 16, v42
	v_and_b32_e32 v41, 0xffff0000, v42
	v_lshlrev_b32_e32 v42, 16, v43
	v_and_b32_e32 v43, 0xffff0000, v43
	s_waitcnt vmcnt(1)
	v_lshlrev_b32_e32 v64, 16, v44
	v_and_b32_e32 v65, 0xffff0000, v44
	v_lshlrev_b32_e32 v66, 16, v45
	v_and_b32_e32 v67, 0xffff0000, v45
	v_lshlrev_b32_e32 v56, 16, v46
	v_and_b32_e32 v57, 0xffff0000, v46
	v_lshlrev_b32_e32 v58, 16, v47
	v_and_b32_e32 v59, 0xffff0000, v47
	s_waitcnt vmcnt(0)
	v_lshlrev_b32_e32 v60, 16, v48
	v_and_b32_e32 v61, 0xffff0000, v48
	v_lshlrev_b32_e32 v62, 16, v49
	v_and_b32_e32 v63, 0xffff0000, v49
	v_lshlrev_b32_e32 v68, 16, v50
	v_and_b32_e32 v69, 0xffff0000, v50
	v_lshlrev_b32_e32 v70, 16, v51
	v_and_b32_e32 v71, 0xffff0000, v51
	s_cbranch_execz .LBB0_292

.LBB0_285:
	s_lshl_b64 s[10:11], s[24:25], 1
	s_add_u32 s26, s35, s10
	s_addc_u32 s27, s48, s11
	s_add_u32 s28, s49, s10
	s_addc_u32 s29, s50, s11
	v_lshl_add_u64 v[80:81], s[28:29], 0, v[176:177]
	global_load_dwordx4 v[44:47], v[80:81], off nt
	v_lshl_add_u64 v[100:101], s[26:27], 0, v[176:177]
	v_lshl_add_u64 v[108:109], s[28:29], 0, v[152:153]
	v_lshl_add_u64 v[128:129], s[26:27], 0, v[152:153]
	s_waitcnt vmcnt(0)
	v_lshlrev_b32_e32 v48, 16, v44
	v_and_b32_e32 v49, 0xffff0000, v44
	v_lshlrev_b32_e32 v44, 16, v45
	v_and_b32_e32 v45, 0xffff0000, v45
	v_pk_add_f32 v[50:51], v[2:3], v[44:45]
	v_lshlrev_b32_e32 v44, 16, v46
	v_and_b32_e32 v45, 0xffff0000, v46
	v_lshlrev_b32_e32 v46, 16, v47
	v_and_b32_e32 v47, 0xffff0000, v47
	v_pk_add_f32 v[48:49], v[0:1], v[48:49]
	v_pk_add_f32 v[46:47], v[6:7], v[46:47]
	v_pk_add_f32 v[44:45], v[4:5], v[44:45]
	v_cvt_pk_bf16_f32 v72, v48, v49
	v_cvt_pk_bf16_f32 v73, v50, v51
	v_mov_b32_e32 v191, v51
	v_cvt_pk_bf16_f32 v74, v44, v45
	v_cvt_pk_bf16_f32 v75, v46, v47
	global_store_dwordx4 v[100:101], v[72:75], off nt
	global_load_dwordx4 v[72:75], v[80:81], off offset:1024 nt
	v_mov_b32_e32 v190, v49
	v_mov_b32_e32 v195, v50
	v_mov_b32_e32 v194, v48
	v_mov_b32_e32 v193, v47
	v_mov_b32_e32 v192, v45
	v_mov_b32_e32 v197, v46
	v_mov_b32_e32 v196, v44
	s_waitcnt vmcnt(0)
	v_lshlrev_b32_e32 v76, 16, v72
	v_and_b32_e32 v77, 0xffff0000, v72
	v_lshlrev_b32_e32 v72, 16, v73
	v_and_b32_e32 v73, 0xffff0000, v73
	v_pk_add_f32 v[94:95], v[10:11], v[72:73]
	v_lshlrev_b32_e32 v72, 16, v74
	v_and_b32_e32 v73, 0xffff0000, v74
	v_lshlrev_b32_e32 v74, 16, v75
	v_and_b32_e32 v75, 0xffff0000, v75
	v_pk_add_f32 v[92:93], v[8:9], v[76:77]
	v_pk_add_f32 v[74:75], v[14:15], v[74:75]
	v_pk_add_f32 v[72:73], v[12:13], v[72:73]
	v_cvt_pk_bf16_f32 v76, v92, v93
	v_cvt_pk_bf16_f32 v77, v94, v95
	v_mov_b64_e32 v[146:147], v[94:95]
	v_cvt_pk_bf16_f32 v78, v72, v73
	v_cvt_pk_bf16_f32 v79, v74, v75
	global_store_dwordx4 v[100:101], v[76:79], off offset:1024 nt
	global_load_dwordx4 v[82:85], v[80:81], off offset:2048 nt
	v_mov_b64_e32 v[144:145], v[92:93]
	v_mov_b32_e32 v200, v72
	v_mov_b32_e32 v217, v73
	v_mov_b32_e32 v205, v74
	v_mov_b32_e32 v199, v75
	s_waitcnt vmcnt(0)
	v_lshlrev_b32_e32 v76, 16, v82
	v_and_b32_e32 v77, 0xffff0000, v82
	v_lshlrev_b32_e32 v78, 16, v83
	v_and_b32_e32 v79, 0xffff0000, v83
	v_lshlrev_b32_e32 v82, 16, v84
	v_and_b32_e32 v83, 0xffff0000, v84
	v_lshlrev_b32_e32 v84, 16, v85
	v_and_b32_e32 v85, 0xffff0000, v85
	v_pk_add_f32 v[78:79], v[18:19], v[78:79]
	v_pk_add_f32 v[76:77], v[16:17], v[76:77]
	v_pk_add_f32 v[98:99], v[22:23], v[84:85]
	v_pk_add_f32 v[96:97], v[20:21], v[82:83]
	v_cvt_pk_bf16_f32 v82, v76, v77
	v_cvt_pk_bf16_f32 v83, v78, v79
	v_mov_b32_e32 v175, v79
	v_cvt_pk_bf16_f32 v84, v96, v97
	v_cvt_pk_bf16_f32 v85, v98, v99
	global_store_dwordx4 v[100:101], v[82:85], off offset:2048 nt
	global_load_dwordx4 v[80:83], v[80:81], off offset:3072 nt
	v_mov_b64_e32 v[142:143], v[98:99]
	v_mov_b32_e32 v174, v77
	v_mov_b32_e32 v189, v78
	v_mov_b32_e32 v188, v76
	v_mov_b64_e32 v[140:141], v[96:97]
	s_waitcnt vmcnt(0)
	v_lshlrev_b32_e32 v84, 16, v80
	v_and_b32_e32 v85, 0xffff0000, v80
	v_lshlrev_b32_e32 v80, 16, v81
	v_and_b32_e32 v81, 0xffff0000, v81
	v_pk_add_f32 v[86:87], v[30:31], v[80:81]
	v_lshlrev_b32_e32 v80, 16, v82
	v_and_b32_e32 v81, 0xffff0000, v82
	v_lshlrev_b32_e32 v82, 16, v83
	v_and_b32_e32 v83, 0xffff0000, v83
	v_pk_add_f32 v[84:85], v[28:29], v[84:85]
	v_pk_add_f32 v[82:83], v[26:27], v[82:83]
	v_pk_add_f32 v[80:81], v[24:25], v[80:81]
	v_cvt_pk_bf16_f32 v88, v84, v85
	v_cvt_pk_bf16_f32 v89, v86, v87
	v_mov_b32_e32 v171, v83
	v_cvt_pk_bf16_f32 v90, v80, v81
	v_cvt_pk_bf16_f32 v91, v82, v83
	global_store_dwordx4 v[100:101], v[88:91], off offset:3072 nt
	global_load_dwordx4 v[88:91], v[108:109], off nt
	v_mov_b32_e32 v170, v81
	v_mov_b32_e32 v173, v82
	v_mov_b32_e32 v172, v80
	v_mov_b32_e32 v204, v84
	v_mov_b32_e32 v229, v85
	v_mov_b32_e32 v228, v86
	v_mov_b32_e32 v227, v87
	s_waitcnt vmcnt(0)
	v_lshlrev_b32_e32 v100, 16, v88
	v_and_b32_e32 v101, 0xffff0000, v88
	v_lshlrev_b32_e32 v88, 16, v89
	v_and_b32_e32 v89, 0xffff0000, v89
	v_pk_add_f32 v[118:119], v[38:39], v[88:89]
	v_lshlrev_b32_e32 v88, 16, v90
	v_and_b32_e32 v89, 0xffff0000, v90
	v_lshlrev_b32_e32 v90, 16, v91
	v_and_b32_e32 v91, 0xffff0000, v91
	v_pk_add_f32 v[116:117], v[36:37], v[100:101]
	v_pk_add_f32 v[90:91], v[54:55], v[90:91]
	v_pk_add_f32 v[88:89], v[52:53], v[88:89]
	v_cvt_pk_bf16_f32 v100, v116, v117
	v_cvt_pk_bf16_f32 v101, v118, v119
	v_mov_b64_e32 v[134:135], v[118:119]
	v_cvt_pk_bf16_f32 v102, v88, v89
	v_cvt_pk_bf16_f32 v103, v90, v91
	global_store_dwordx4 v[128:129], v[100:103], off nt
	global_load_dwordx4 v[102:105], v[108:109], off offset:1024 nt
	v_mov_b64_e32 v[132:133], v[116:117]
	v_mov_b32_e32 v198, v88
	v_mov_b32_e32 v216, v89
	v_mov_b32_e32 v207, v90
	v_mov_b32_e32 v203, v91
	s_waitcnt vmcnt(0)
	v_lshlrev_b32_e32 v100, 16, v102
	v_and_b32_e32 v101, 0xffff0000, v102
	v_lshlrev_b32_e32 v102, 16, v103
	v_and_b32_e32 v103, 0xffff0000, v103
	v_lshlrev_b32_e32 v106, 16, v104
	v_and_b32_e32 v107, 0xffff0000, v104
	v_lshlrev_b32_e32 v104, 16, v105
	v_and_b32_e32 v105, 0xffff0000, v105
	v_pk_add_f32 v[102:103], v[34:35], v[102:103]
	v_pk_add_f32 v[100:101], v[32:33], v[100:101]
	v_pk_add_f32 v[126:127], v[42:43], v[104:105]
	v_pk_add_f32 v[124:125], v[40:41], v[106:107]
	v_cvt_pk_bf16_f32 v104, v100, v101
	v_cvt_pk_bf16_f32 v105, v102, v103
	v_mov_b32_e32 v163, v103
	v_cvt_pk_bf16_f32 v106, v124, v125
	v_cvt_pk_bf16_f32 v107, v126, v127
	global_store_dwordx4 v[128:129], v[104:107], off offset:1024 nt
	global_load_dwordx4 v[110:113], v[108:109], off offset:2048 nt
	v_mov_b32_e32 v162, v101
	v_mov_b32_e32 v165, v102
	v_mov_b32_e32 v164, v100
	s_waitcnt vmcnt(0)
	v_lshlrev_b32_e32 v104, 16, v110
	v_and_b32_e32 v105, 0xffff0000, v110
	v_lshlrev_b32_e32 v106, 16, v111
	v_and_b32_e32 v107, 0xffff0000, v111
	v_lshlrev_b32_e32 v110, 16, v112
	v_and_b32_e32 v111, 0xffff0000, v112
	v_lshlrev_b32_e32 v112, 16, v113
	v_and_b32_e32 v113, 0xffff0000, v113
	v_pk_add_f32 v[106:107], v[66:67], v[106:107]
	v_pk_add_f32 v[104:105], v[64:65], v[104:105]
	v_pk_add_f32 v[114:115], v[58:59], v[112:113]
	v_pk_add_f32 v[112:113], v[56:57], v[110:111]
	v_cvt_pk_bf16_f32 v120, v104, v105
	v_cvt_pk_bf16_f32 v121, v106, v107
	v_mov_b32_e32 v167, v115
	v_cvt_pk_bf16_f32 v122, v112, v113
	v_cvt_pk_bf16_f32 v123, v114, v115
	global_store_dwordx4 v[128:129], v[120:123], off offset:2048 nt
	global_load_dwordx4 v[108:111], v[108:109], off offset:3072 nt
	v_mov_b32_e32 v166, v113
	v_mov_b32_e32 v169, v114
	v_mov_b32_e32 v168, v112
	v_mov_b32_e32 v202, v104
	v_mov_b32_e32 v226, v105
	v_mov_b32_e32 v219, v106
	v_mov_b32_e32 v218, v107
	s_waitcnt vmcnt(0)
	v_lshlrev_b32_e32 v120, 16, v108
	v_and_b32_e32 v121, 0xffff0000, v108
	v_lshlrev_b32_e32 v108, 16, v109
	v_and_b32_e32 v109, 0xffff0000, v109
	v_pk_add_f32 v[138:139], v[62:63], v[108:109]
	v_lshlrev_b32_e32 v108, 16, v110
	v_and_b32_e32 v109, 0xffff0000, v110
	v_lshlrev_b32_e32 v110, 16, v111
	v_and_b32_e32 v111, 0xffff0000, v111
	v_pk_add_f32 v[136:137], v[60:61], v[120:121]
	v_pk_add_f32 v[110:111], v[70:71], v[110:111]
	v_pk_add_f32 v[108:109], v[68:69], v[108:109]
	v_cvt_pk_bf16_f32 v120, v136, v137
	v_cvt_pk_bf16_f32 v121, v138, v139
	v_mov_b32_e32 v230, v110
	v_cvt_pk_bf16_f32 v122, v108, v109
	v_cvt_pk_bf16_f32 v123, v110, v111
	global_store_dwordx4 v[128:129], v[120:123], off offset:3072 nt
	v_mov_b64_e32 v[130:131], v[126:127]
	v_mov_b64_e32 v[128:129], v[124:125]
	v_mov_b64_e32 v[120:121], v[136:137]
	v_mov_b64_e32 v[122:123], v[138:139]
	v_mov_b32_e32 v206, v108
	v_mov_b32_e32 v231, v109
	v_mov_b32_e32 v232, v111
	s_cbranch_execnz .LBB0_287

.LBB0_287:
	v_pk_mul_f32 v[0:1], v[190:191], v[190:191]
	v_pk_mul_f32 v[2:3], v[192:193], v[192:193]
	v_pk_fma_f32 v[0:1], v[194:195], v[194:195], v[0:1]
	v_pk_fma_f32 v[2:3], v[196:197], v[196:197], v[2:3]
	v_pk_add_f32 v[0:1], v[0:1], v[0:1] op_sel_hi:[0,1]
	v_mul_f32_e32 v201, v92, v92
	v_mul_f32_e32 v5, v93, v93
	v_mul_f32_e32 v0, v94, v94
	v_mov_b32_e32 v4, v200
	v_pk_add_f32 v[2:3], v[2:3], v[2:3] op_sel_hi:[0,1]
	v_pk_fma_f32 v[6:7], v[94:95], v[94:95], v[0:1] op_sel_hi:[1,1,0]
	v_pk_add_f32 v[4:5], v[200:201], v[4:5]
	v_mul_f32_e32 v6, v217, v217
	v_mul_f32_e32 v2, v205, v205
	v_mul_f32_e32 v0, v199, v199
	v_mul_f32_e32 v8, v200, v200
	v_mov_b32_e32 v9, v5
	v_pk_add_f32 v[4:5], v[8:9], v[6:7]
	v_pk_add_f32 v[0:1], v[2:3], v[0:1]
	v_pk_mul_f32 v[2:3], v[174:175], v[174:175]
	v_pk_add_f32 v[0:1], v[4:5], v[0:1]
	v_pk_fma_f32 v[2:3], v[188:189], v[188:189], v[2:3]
	v_pk_add_f32 v[0:1], v[0:1], v[0:1] op_sel_hi:[0,1]
	v_mul_f32_e32 v205, v96, v96
	v_mul_f32_e32 v5, v97, v97
	v_mul_f32_e32 v0, v98, v98
	v_mov_b32_e32 v4, v204
	v_pk_add_f32 v[2:3], v[2:3], v[2:3] op_sel_hi:[0,1]
	v_pk_fma_f32 v[6:7], v[98:99], v[98:99], v[0:1] op_sel_hi:[1,1,0]
	v_pk_add_f32 v[4:5], v[204:205], v[4:5]
	v_mul_f32_e32 v6, v229, v229
	v_mul_f32_e32 v2, v228, v228
	v_mul_f32_e32 v0, v227, v227
	v_mul_f32_e32 v8, v204, v204
	v_mov_b32_e32 v9, v5
	v_pk_add_f32 v[4:5], v[8:9], v[6:7]
	v_pk_add_f32 v[0:1], v[2:3], v[0:1]
	v_pk_mul_f32 v[2:3], v[170:171], v[170:171]
	v_pk_add_f32 v[0:1], v[4:5], v[0:1]
	v_pk_fma_f32 v[2:3], v[172:173], v[172:173], v[2:3]
	v_pk_add_f32 v[0:1], v[0:1], v[0:1] op_sel_hi:[0,1]
	v_mul_f32_e32 v199, v116, v116
	v_mul_f32_e32 v5, v117, v117
	v_mul_f32_e32 v0, v118, v118
	v_mov_b32_e32 v4, v198
	v_pk_add_f32 v[2:3], v[2:3], v[2:3] op_sel_hi:[0,1]
	v_pk_fma_f32 v[6:7], v[118:119], v[118:119], v[0:1] op_sel_hi:[1,1,0]
	v_pk_add_f32 v[4:5], v[198:199], v[4:5]
	v_mul_f32_e32 v6, v216, v216
	v_mul_f32_e32 v2, v207, v207
	v_mul_f32_e32 v0, v203, v203
	v_mul_f32_e32 v8, v198, v198
	v_mov_b32_e32 v9, v5
	v_pk_add_f32 v[4:5], v[8:9], v[6:7]
	v_pk_add_f32 v[0:1], v[2:3], v[0:1]
	v_pk_mul_f32 v[2:3], v[162:163], v[162:163]
	v_pk_add_f32 v[0:1], v[4:5], v[0:1]
	v_pk_fma_f32 v[2:3], v[164:165], v[164:165], v[2:3]
	v_pk_add_f32 v[0:1], v[0:1], v[0:1] op_sel_hi:[0,1]
	v_mul_f32_e32 v203, v124, v124
	v_mul_f32_e32 v5, v125, v125
	v_mul_f32_e32 v0, v126, v126
	v_mov_b32_e32 v4, v202
	v_pk_add_f32 v[2:3], v[2:3], v[2:3] op_sel_hi:[0,1]
	v_pk_fma_f32 v[6:7], v[126:127], v[126:127], v[0:1] op_sel_hi:[1,1,0]
	v_pk_add_f32 v[4:5], v[202:203], v[4:5]
	v_mul_f32_e32 v6, v226, v226
	v_mul_f32_e32 v2, v219, v219
	v_mul_f32_e32 v0, v218, v218
	v_mul_f32_e32 v8, v202, v202
	v_mov_b32_e32 v9, v5
	v_pk_add_f32 v[4:5], v[8:9], v[6:7]
	v_pk_add_f32 v[0:1], v[2:3], v[0:1]
	v_pk_mul_f32 v[2:3], v[166:167], v[166:167]
	v_pk_add_f32 v[0:1], v[4:5], v[0:1]
	v_pk_fma_f32 v[2:3], v[168:169], v[168:169], v[2:3]
	v_pk_add_f32 v[0:1], v[0:1], v[0:1] op_sel_hi:[0,1]
	v_mul_f32_e32 v207, v136, v136
	v_mul_f32_e32 v5, v137, v137
	v_mul_f32_e32 v0, v138, v138
	v_mov_b32_e32 v4, v206
	v_pk_add_f32 v[2:3], v[2:3], v[2:3] op_sel_hi:[0,1]
	v_pk_fma_f32 v[6:7], v[138:139], v[138:139], v[0:1] op_sel_hi:[1,1,0]
	v_pk_add_f32 v[4:5], v[206:207], v[4:5]
	v_mul_f32_e32 v6, v231, v231
	v_mul_f32_e32 v2, v230, v230
	v_mul_f32_e32 v0, v232, v232
	v_mul_f32_e32 v8, v206, v206
	v_mov_b32_e32 v9, v5
	v_pk_add_f32 v[4:5], v[8:9], v[6:7]
	v_pk_add_f32 v[0:1], v[2:3], v[0:1]
	s_add_i32 s26, s22, 1
	v_pk_add_f32 v[0:1], v[4:5], v[0:1]
	ds_read_b128 v[2:5], v214
	ds_read_b128 v[6:9], v214 offset:16384
	v_add_f32_e32 v0, v0, v1
	ds_bpermute_b32 v1, v208, v0
	ds_read_b128 v[10:13], v214 offset:1024
	ds_read_b128 v[14:17], v214 offset:17408
	s_ashr_i32 s27, s26, 31
	s_waitcnt lgkmcnt(2)
	v_add_f32_e32 v0, v0, v1
	ds_bpermute_b32 v1, v209, v0
	s_waitcnt lgkmcnt(0)
	v_add_f32_e32 v0, v0, v1
	ds_bpermute_b32 v1, v210, v0
	s_waitcnt lgkmcnt(0)
	v_add_f32_e32 v0, v0, v1
	ds_bpermute_b32 v1, v211, v0
	s_waitcnt lgkmcnt(0)
	v_add_f32_e32 v0, v0, v1
	ds_bpermute_b32 v1, v212, v0
	s_waitcnt lgkmcnt(0)
	v_add_f32_e32 v0, v0, v1
	ds_bpermute_b32 v1, v213, v0
	s_waitcnt lgkmcnt(0)
	v_add_f32_e32 v0, v0, v1
	v_fmamk_f32 v0, v0, 0x39800000, v221
	v_mul_f32_e32 v1, 0x4b800000, v0
	v_cmp_gt_f32_e32 vcc, s42, v0
	s_nop 1
	v_cndmask_b32_e32 v0, v0, v1, vcc
	v_rsq_f32_e32 v0, v0
	s_nop 0
	v_mul_f32_e32 v1, 0x45800000, v0
	v_cndmask_b32_e32 v0, v0, v1, vcc
	v_pk_mul_f32 v[18:19], v[48:49], v[0:1] op_sel_hi:[1,0]
	v_pk_mul_f32 v[20:21], v[50:51], v[0:1] op_sel_hi:[1,0]
	v_pk_fma_f32 v[2:3], v[2:3], v[18:19], v[6:7]
	v_pk_fma_f32 v[4:5], v[4:5], v[20:21], v[8:9]
	v_pk_mul_f32 v[6:7], v[44:45], v[0:1] op_sel_hi:[1,0]
	v_pk_mul_f32 v[8:9], v[46:47], v[0:1] op_sel_hi:[1,0]
	v_lshl_add_u64 v[18:19], s[24:25], 1, v[156:157]
	v_pk_fma_f32 v[8:9], v[12:13], v[8:9], v[16:17]
	v_pk_fma_f32 v[6:7], v[10:11], v[6:7], v[14:15]
	v_cvt_pk_bf16_f32 v2, v2, v3
	v_cvt_pk_bf16_f32 v3, v4, v5
	v_pk_mul_f32 v[20:21], v[144:145], v[0:1] op_sel_hi:[1,0]
	v_cvt_pk_bf16_f32 v4, v6, v7
	v_cvt_pk_bf16_f32 v5, v8, v9
	global_store_dwordx4 v[18:19], v[2:5], off
	ds_read_b128 v[2:5], v214 offset:2048
	ds_read_b128 v[6:9], v214 offset:18432
	ds_read_b128 v[10:13], v214 offset:3072
	ds_read_b128 v[14:17], v214 offset:19456
	v_pk_mul_f32 v[22:23], v[146:147], v[0:1] op_sel_hi:[1,0]
	s_lshl_b64 s[24:25], s[26:27], 12
	s_waitcnt lgkmcnt(2)
	v_pk_fma_f32 v[4:5], v[4:5], v[22:23], v[8:9]
	v_pk_fma_f32 v[2:3], v[2:3], v[20:21], v[6:7]
	v_pk_mul_f32 v[6:7], v[72:73], v[0:1] op_sel_hi:[1,0]
	v_pk_mul_f32 v[8:9], v[74:75], v[0:1] op_sel_hi:[1,0]
	s_waitcnt lgkmcnt(0)
	v_pk_fma_f32 v[6:7], v[10:11], v[6:7], v[14:15]
	v_pk_fma_f32 v[8:9], v[12:13], v[8:9], v[16:17]
	v_cvt_pk_bf16_f32 v2, v2, v3
	v_cvt_pk_bf16_f32 v3, v4, v5
	v_cvt_pk_bf16_f32 v4, v6, v7
	v_pk_mul_f32 v[20:21], v[76:77], v[0:1] op_sel_hi:[1,0]
	v_cvt_pk_bf16_f32 v5, v8, v9
	global_store_dwordx4 v[18:19], v[2:5], off offset:1024
	ds_read_b128 v[2:5], v214 offset:4096
	ds_read_b128 v[6:9], v214 offset:20480
	ds_read_b128 v[10:13], v214 offset:5120
	ds_read_b128 v[14:17], v214 offset:21504
	v_pk_mul_f32 v[22:23], v[78:79], v[0:1] op_sel_hi:[1,0]
	s_waitcnt lgkmcnt(2)
	v_pk_fma_f32 v[2:3], v[2:3], v[20:21], v[6:7]
	v_pk_fma_f32 v[4:5], v[4:5], v[22:23], v[8:9]
	v_pk_mul_f32 v[6:7], v[140:141], v[0:1] op_sel_hi:[1,0]
	v_pk_mul_f32 v[8:9], v[142:143], v[0:1] op_sel_hi:[1,0]
	s_waitcnt lgkmcnt(0)
	v_pk_fma_f32 v[6:7], v[10:11], v[6:7], v[14:15]
	v_pk_fma_f32 v[8:9], v[12:13], v[8:9], v[16:17]
	v_cvt_pk_bf16_f32 v2, v2, v3
	v_cvt_pk_bf16_f32 v3, v4, v5
	v_cvt_pk_bf16_f32 v4, v6, v7
	v_pk_mul_f32 v[20:21], v[84:85], v[0:1] op_sel_hi:[1,0]
	v_cvt_pk_bf16_f32 v5, v8, v9
	global_store_dwordx4 v[18:19], v[2:5], off offset:2048
	ds_read_b128 v[2:5], v214 offset:6144
	ds_read_b128 v[6:9], v214 offset:22528
	ds_read_b128 v[10:13], v214 offset:7168
	ds_read_b128 v[14:17], v214 offset:23552
	v_pk_mul_f32 v[22:23], v[86:87], v[0:1] op_sel_hi:[1,0]
	s_waitcnt lgkmcnt(2)
	v_pk_fma_f32 v[2:3], v[20:21], v[2:3], v[6:7]
	v_pk_fma_f32 v[4:5], v[22:23], v[4:5], v[8:9]
	v_pk_mul_f32 v[6:7], v[80:81], v[0:1] op_sel_hi:[1,0]
	v_pk_mul_f32 v[8:9], v[82:83], v[0:1] op_sel_hi:[1,0]
	s_waitcnt lgkmcnt(0)
	v_pk_fma_f32 v[6:7], v[6:7], v[10:11], v[14:15]
	v_pk_fma_f32 v[8:9], v[8:9], v[12:13], v[16:17]
	v_cvt_pk_bf16_f32 v2, v2, v3
	v_cvt_pk_bf16_f32 v3, v4, v5
	v_cvt_pk_bf16_f32 v4, v6, v7
	v_pk_mul_f32 v[20:21], v[132:133], v[0:1] op_sel_hi:[1,0]
	v_cvt_pk_bf16_f32 v5, v8, v9
	global_store_dwordx4 v[18:19], v[2:5], off offset:3072
	ds_read_b128 v[2:5], v214 offset:8192
	ds_read_b128 v[6:9], v214 offset:24576
	ds_read_b128 v[10:13], v214 offset:9216
	ds_read_b128 v[14:17], v214 offset:25600
	v_pk_mul_f32 v[22:23], v[134:135], v[0:1] op_sel_hi:[1,0]
	v_add_co_u32_e32 v18, vcc, s46, v18
	s_waitcnt lgkmcnt(2)
	v_pk_fma_f32 v[4:5], v[22:23], v[4:5], v[8:9]
	v_pk_fma_f32 v[2:3], v[20:21], v[2:3], v[6:7]
	v_pk_mul_f32 v[6:7], v[88:89], v[0:1] op_sel_hi:[1,0]
	v_pk_mul_f32 v[8:9], v[90:91], v[0:1] op_sel_hi:[1,0]
	v_addc_co_u32_e32 v19, vcc, 0, v19, vcc
	s_waitcnt lgkmcnt(0)
	v_pk_fma_f32 v[8:9], v[8:9], v[12:13], v[16:17]
	v_pk_fma_f32 v[6:7], v[6:7], v[10:11], v[14:15]
	v_cvt_pk_bf16_f32 v2, v2, v3
	v_cvt_pk_bf16_f32 v3, v4, v5
	v_pk_mul_f32 v[20:21], v[100:101], v[0:1] op_sel_hi:[1,0]
	v_cvt_pk_bf16_f32 v4, v6, v7
	v_cvt_pk_bf16_f32 v5, v8, v9
	global_store_dwordx4 v[18:19], v[2:5], off
	ds_read_b128 v[2:5], v214 offset:10240
	ds_read_b128 v[6:9], v214 offset:26624
	ds_read_b128 v[10:13], v214 offset:11264
	ds_read_b128 v[14:17], v214 offset:27648
	v_pk_mul_f32 v[22:23], v[102:103], v[0:1] op_sel_hi:[1,0]
	s_and_b64 vcc, exec, s[4:5]
	s_mov_b64 s[4:5], -1
	s_waitcnt lgkmcnt(2)
	v_pk_fma_f32 v[4:5], v[22:23], v[4:5], v[8:9]
	v_pk_fma_f32 v[2:3], v[20:21], v[2:3], v[6:7]
	v_pk_mul_f32 v[6:7], v[128:129], v[0:1] op_sel_hi:[1,0]
	v_pk_mul_f32 v[8:9], v[130:131], v[0:1] op_sel_hi:[1,0]
	s_waitcnt lgkmcnt(0)
	v_pk_fma_f32 v[6:7], v[6:7], v[10:11], v[14:15]
	v_pk_fma_f32 v[8:9], v[8:9], v[12:13], v[16:17]
	v_cvt_pk_bf16_f32 v2, v2, v3
	v_cvt_pk_bf16_f32 v3, v4, v5
	v_cvt_pk_bf16_f32 v4, v6, v7
	v_pk_mul_f32 v[20:21], v[104:105], v[0:1] op_sel_hi:[1,0]
	v_cvt_pk_bf16_f32 v5, v8, v9
	global_store_dwordx4 v[18:19], v[2:5], off offset:1024
	ds_read_b128 v[2:5], v214 offset:12288
	ds_read_b128 v[6:9], v214 offset:28672
	ds_read_b128 v[10:13], v214 offset:13312
	ds_read_b128 v[14:17], v214 offset:29696
	v_pk_mul_f32 v[22:23], v[106:107], v[0:1] op_sel_hi:[1,0]
	s_waitcnt lgkmcnt(2)
	v_pk_fma_f32 v[2:3], v[20:21], v[2:3], v[6:7]
	v_pk_fma_f32 v[4:5], v[22:23], v[4:5], v[8:9]
	v_pk_mul_f32 v[6:7], v[112:113], v[0:1] op_sel_hi:[1,0]
	v_pk_mul_f32 v[8:9], v[114:115], v[0:1] op_sel_hi:[1,0]
	s_waitcnt lgkmcnt(0)
	v_pk_fma_f32 v[6:7], v[6:7], v[10:11], v[14:15]
	v_pk_fma_f32 v[8:9], v[8:9], v[12:13], v[16:17]
	v_cvt_pk_bf16_f32 v2, v2, v3
	v_cvt_pk_bf16_f32 v3, v4, v5
	v_cvt_pk_bf16_f32 v4, v6, v7
	v_pk_mul_f32 v[20:21], v[120:121], v[0:1] op_sel_hi:[1,0]
	v_cvt_pk_bf16_f32 v5, v8, v9
	global_store_dwordx4 v[18:19], v[2:5], off offset:2048
	ds_read_b128 v[2:5], v214 offset:14336
	ds_read_b128 v[6:9], v214 offset:30720
	ds_read_b128 v[10:13], v214 offset:15360
	ds_read_b128 v[14:17], v214 offset:31744
	v_pk_mul_f32 v[22:23], v[122:123], v[0:1] op_sel_hi:[1,0]
	s_waitcnt lgkmcnt(2)
	v_pk_fma_f32 v[2:3], v[20:21], v[2:3], v[6:7]
	v_pk_mul_f32 v[6:7], v[108:109], v[0:1] op_sel_hi:[1,0]
	v_pk_mul_f32 v[0:1], v[110:111], v[0:1] op_sel_hi:[1,0]
	v_pk_fma_f32 v[4:5], v[22:23], v[4:5], v[8:9]
	s_waitcnt lgkmcnt(0)
	v_pk_fma_f32 v[8:9], v[0:1], v[12:13], v[16:17]
	v_pk_fma_f32 v[6:7], v[6:7], v[10:11], v[14:15]
	v_cvt_pk_bf16_f32 v0, v2, v3
	v_cvt_pk_bf16_f32 v1, v4, v5
	s_nop 0
	v_cvt_pk_bf16_f32 v2, v6, v7
	v_cvt_pk_bf16_f32 v3, v8, v9
	global_store_dwordx4 v[18:19], v[0:3], off offset:3072
	s_cbranch_vccnz .LBB0_298
	s_nop 0
	v_lshl_add_u64 v[0:1], s[24:25], 1, v[154:155]
	global_load_dwordx4 v[4:7], v[0:1], off nt
	global_load_dwordx4 v[12:15], v[0:1], off offset:1024 nt
	global_load_dwordx4 v[20:23], v[0:1], off offset:2048 nt
	global_load_dwordx4 v[24:27], v[0:1], off offset:3072 nt
	v_add_co_u32_e32 v0, vcc, s46, v0
	s_nop 1
	v_addc_co_u32_e32 v1, vcc, 0, v1, vcc
	global_load_dwordx4 v[32:35], v[0:1], off nt
	global_load_dwordx4 v[48:51], v[0:1], off offset:1024 nt
	global_load_dwordx4 v[56:59], v[0:1], off offset:2048 nt
	global_load_dwordx4 v[68:71], v[0:1], off offset:3072 nt
	s_waitcnt vmcnt(7)
	v_lshlrev_b32_e32 v0, 16, v4
	v_and_b32_e32 v1, 0xffff0000, v4
	v_lshlrev_b32_e32 v2, 16, v5
	v_and_b32_e32 v3, 0xffff0000, v5
	v_lshlrev_b32_e32 v4, 16, v6
	v_and_b32_e32 v5, 0xffff0000, v6
	v_lshlrev_b32_e32 v6, 16, v7
	v_and_b32_e32 v7, 0xffff0000, v7
	s_waitcnt vmcnt(6)
	v_lshlrev_b32_e32 v8, 16, v12
	v_and_b32_e32 v9, 0xffff0000, v12
	v_lshlrev_b32_e32 v10, 16, v13
	v_and_b32_e32 v11, 0xffff0000, v13
	v_lshlrev_b32_e32 v12, 16, v14
	v_and_b32_e32 v13, 0xffff0000, v14
	v_lshlrev_b32_e32 v14, 16, v15
	v_and_b32_e32 v15, 0xffff0000, v15
	s_waitcnt vmcnt(5)
	v_lshlrev_b32_e32 v16, 16, v20
	v_and_b32_e32 v17, 0xffff0000, v20
	v_lshlrev_b32_e32 v18, 16, v21
	v_and_b32_e32 v19, 0xffff0000, v21
	v_lshlrev_b32_e32 v20, 16, v22
	v_and_b32_e32 v21, 0xffff0000, v22
	v_lshlrev_b32_e32 v22, 16, v23
	v_and_b32_e32 v23, 0xffff0000, v23
	s_waitcnt vmcnt(4)
	v_lshlrev_b32_e32 v36, 16, v24
	v_and_b32_e32 v37, 0xffff0000, v24
	v_lshlrev_b32_e32 v38, 16, v25
	v_and_b32_e32 v39, 0xffff0000, v25
	v_lshlrev_b32_e32 v28, 16, v26
	v_and_b32_e32 v29, 0xffff0000, v26
	v_lshlrev_b32_e32 v30, 16, v27
	v_and_b32_e32 v31, 0xffff0000, v27
	s_waitcnt vmcnt(3)
	v_lshlrev_b32_e32 v44, 16, v32
	v_and_b32_e32 v45, 0xffff0000, v32
	v_lshlrev_b32_e32 v46, 16, v33
	v_and_b32_e32 v47, 0xffff0000, v33
	v_lshlrev_b32_e32 v52, 16, v34
	v_and_b32_e32 v53, 0xffff0000, v34
	v_lshlrev_b32_e32 v54, 16, v35
	v_and_b32_e32 v55, 0xffff0000, v35
	s_waitcnt vmcnt(2)
	v_lshlrev_b32_e32 v40, 16, v48
	v_and_b32_e32 v41, 0xffff0000, v48
	v_lshlrev_b32_e32 v42, 16, v49
	v_and_b32_e32 v43, 0xffff0000, v49
	v_lshlrev_b32_e32 v48, 16, v50
	v_and_b32_e32 v49, 0xffff0000, v50
	v_lshlrev_b32_e32 v50, 16, v51
	v_and_b32_e32 v51, 0xffff0000, v51
	s_waitcnt vmcnt(1)
	v_lshlrev_b32_e32 v64, 16, v56
	v_and_b32_e32 v65, 0xffff0000, v56
	v_lshlrev_b32_e32 v66, 16, v57
	v_and_b32_e32 v67, 0xffff0000, v57
	v_lshlrev_b32_e32 v56, 16, v58
	v_and_b32_e32 v57, 0xffff0000, v58
	v_lshlrev_b32_e32 v58, 16, v59
	v_and_b32_e32 v59, 0xffff0000, v59
	s_waitcnt vmcnt(0)
	v_lshlrev_b32_e32 v60, 16, v68
	v_and_b32_e32 v61, 0xffff0000, v68
	v_lshlrev_b32_e32 v62, 16, v69
	v_and_b32_e32 v63, 0xffff0000, v69
	v_lshlrev_b32_e32 v68, 16, v70
	v_and_b32_e32 v69, 0xffff0000, v70
	v_lshlrev_b32_e32 v70, 16, v71
	v_and_b32_e32 v71, 0xffff0000, v71
	s_cbranch_execz .LBB0_299

.LBB0_290:
	s_lshl_b64 s[10:11], s[24:25], 1
	s_add_u32 s4, s35, s10
	s_addc_u32 s5, s48, s11
	s_add_u32 s22, s49, s10
	s_addc_u32 s23, s50, s11
	v_lshl_add_u64 v[80:81], s[22:23], 0, v[176:177]
	global_load_dwordx4 v[24:27], v[80:81], off nt
	v_lshl_add_u64 v[96:97], s[4:5], 0, v[176:177]
	v_lshl_add_u64 v[108:109], s[22:23], 0, v[152:153]
	v_lshl_add_u64 v[124:125], s[4:5], 0, v[152:153]
	s_waitcnt vmcnt(0)
	v_lshlrev_b32_e32 v32, 16, v24
	v_and_b32_e32 v33, 0xffff0000, v24
	v_lshlrev_b32_e32 v24, 16, v25
	v_and_b32_e32 v25, 0xffff0000, v25
	v_pk_add_f32 v[34:35], v[2:3], v[24:25]
	v_lshlrev_b32_e32 v24, 16, v26
	v_and_b32_e32 v25, 0xffff0000, v26
	v_lshlrev_b32_e32 v26, 16, v27
	v_and_b32_e32 v27, 0xffff0000, v27
	v_pk_add_f32 v[32:33], v[0:1], v[32:33]
	v_pk_add_f32 v[26:27], v[6:7], v[26:27]
	v_pk_add_f32 v[24:25], v[4:5], v[24:25]
	v_cvt_pk_bf16_f32 v72, v32, v33
	v_cvt_pk_bf16_f32 v73, v34, v35
	v_mov_b32_e32 v191, v35
	v_cvt_pk_bf16_f32 v74, v24, v25
	v_cvt_pk_bf16_f32 v75, v26, v27
	global_store_dwordx4 v[96:97], v[72:75], off nt
	global_load_dwordx4 v[72:75], v[80:81], off offset:1024 nt
	v_mov_b32_e32 v190, v33
	v_mov_b32_e32 v195, v34
	v_mov_b32_e32 v194, v32
	v_mov_b32_e32 v193, v27
	v_mov_b32_e32 v192, v25
	v_mov_b32_e32 v197, v26
	v_mov_b32_e32 v196, v24
	s_waitcnt vmcnt(0)
	v_lshlrev_b32_e32 v76, 16, v72
	v_and_b32_e32 v77, 0xffff0000, v72
	v_lshlrev_b32_e32 v72, 16, v73
	v_and_b32_e32 v73, 0xffff0000, v73
	v_pk_add_f32 v[94:95], v[10:11], v[72:73]
	v_lshlrev_b32_e32 v72, 16, v74
	v_and_b32_e32 v73, 0xffff0000, v74
	v_lshlrev_b32_e32 v74, 16, v75
	v_and_b32_e32 v75, 0xffff0000, v75
	v_pk_add_f32 v[92:93], v[8:9], v[76:77]
	v_pk_add_f32 v[74:75], v[14:15], v[74:75]
	v_pk_add_f32 v[72:73], v[12:13], v[72:73]
	v_cvt_pk_bf16_f32 v76, v92, v93
	v_cvt_pk_bf16_f32 v77, v94, v95
	v_mov_b64_e32 v[146:147], v[94:95]
	v_cvt_pk_bf16_f32 v78, v72, v73
	v_cvt_pk_bf16_f32 v79, v74, v75
	global_store_dwordx4 v[96:97], v[76:79], off offset:1024 nt
	global_load_dwordx4 v[82:85], v[80:81], off offset:2048 nt
	v_mov_b64_e32 v[144:145], v[92:93]
	v_mov_b32_e32 v200, v72
	v_mov_b32_e32 v217, v73
	v_mov_b32_e32 v205, v74
	v_mov_b32_e32 v199, v75
	s_waitcnt vmcnt(0)
	v_lshlrev_b32_e32 v76, 16, v82
	v_and_b32_e32 v77, 0xffff0000, v82
	v_lshlrev_b32_e32 v78, 16, v83
	v_and_b32_e32 v79, 0xffff0000, v83
	v_lshlrev_b32_e32 v82, 16, v84
	v_and_b32_e32 v83, 0xffff0000, v84
	v_lshlrev_b32_e32 v84, 16, v85
	v_and_b32_e32 v85, 0xffff0000, v85
	v_pk_add_f32 v[78:79], v[18:19], v[78:79]
	v_pk_add_f32 v[76:77], v[16:17], v[76:77]
	v_pk_add_f32 v[106:107], v[22:23], v[84:85]
	v_pk_add_f32 v[104:105], v[20:21], v[82:83]
	v_cvt_pk_bf16_f32 v82, v76, v77
	v_cvt_pk_bf16_f32 v83, v78, v79
	v_mov_b32_e32 v175, v79
	v_cvt_pk_bf16_f32 v84, v104, v105
	v_cvt_pk_bf16_f32 v85, v106, v107
	global_store_dwordx4 v[96:97], v[82:85], off offset:2048 nt
	global_load_dwordx4 v[80:83], v[80:81], off offset:3072 nt
	v_mov_b64_e32 v[142:143], v[106:107]
	v_mov_b32_e32 v174, v77
	v_mov_b32_e32 v189, v78
	v_mov_b32_e32 v188, v76
	v_mov_b64_e32 v[140:141], v[104:105]
	s_waitcnt vmcnt(0)
	v_lshlrev_b32_e32 v84, 16, v80
	v_and_b32_e32 v85, 0xffff0000, v80
	v_lshlrev_b32_e32 v80, 16, v81
	v_and_b32_e32 v81, 0xffff0000, v81
	v_pk_add_f32 v[86:87], v[38:39], v[80:81]
	v_lshlrev_b32_e32 v80, 16, v82
	v_and_b32_e32 v81, 0xffff0000, v82
	v_lshlrev_b32_e32 v82, 16, v83
	v_and_b32_e32 v83, 0xffff0000, v83
	v_pk_add_f32 v[84:85], v[36:37], v[84:85]
	v_pk_add_f32 v[82:83], v[30:31], v[82:83]
	v_pk_add_f32 v[80:81], v[28:29], v[80:81]
	v_cvt_pk_bf16_f32 v88, v84, v85
	v_cvt_pk_bf16_f32 v89, v86, v87
	v_mov_b32_e32 v171, v83
	v_cvt_pk_bf16_f32 v90, v80, v81
	v_cvt_pk_bf16_f32 v91, v82, v83
	global_store_dwordx4 v[96:97], v[88:91], off offset:3072 nt
	global_load_dwordx4 v[88:91], v[108:109], off nt
	v_mov_b32_e32 v170, v81
	v_mov_b32_e32 v173, v82
	v_mov_b32_e32 v172, v80
	v_mov_b32_e32 v204, v84
	v_mov_b32_e32 v229, v85
	v_mov_b32_e32 v228, v86
	v_mov_b32_e32 v227, v87
	s_waitcnt vmcnt(0)
	v_lshlrev_b32_e32 v96, 16, v88
	v_and_b32_e32 v97, 0xffff0000, v88
	v_lshlrev_b32_e32 v88, 16, v89
	v_and_b32_e32 v89, 0xffff0000, v89
	v_pk_add_f32 v[118:119], v[46:47], v[88:89]
	v_lshlrev_b32_e32 v88, 16, v90
	v_and_b32_e32 v89, 0xffff0000, v90
	v_lshlrev_b32_e32 v90, 16, v91
	v_and_b32_e32 v91, 0xffff0000, v91
	v_pk_add_f32 v[116:117], v[44:45], v[96:97]
	v_pk_add_f32 v[90:91], v[54:55], v[90:91]
	v_pk_add_f32 v[88:89], v[52:53], v[88:89]
	v_cvt_pk_bf16_f32 v96, v116, v117
	v_cvt_pk_bf16_f32 v97, v118, v119
	v_mov_b64_e32 v[134:135], v[118:119]
	v_cvt_pk_bf16_f32 v98, v88, v89
	v_cvt_pk_bf16_f32 v99, v90, v91
	global_store_dwordx4 v[124:125], v[96:99], off nt
	global_load_dwordx4 v[98:101], v[108:109], off offset:1024 nt
	v_mov_b64_e32 v[132:133], v[116:117]
	v_mov_b32_e32 v198, v88
	v_mov_b32_e32 v216, v89
	v_mov_b32_e32 v207, v90
	v_mov_b32_e32 v203, v91
	s_waitcnt vmcnt(0)
	v_lshlrev_b32_e32 v96, 16, v98
	v_and_b32_e32 v97, 0xffff0000, v98
	v_lshlrev_b32_e32 v98, 16, v99
	v_and_b32_e32 v99, 0xffff0000, v99
	v_lshlrev_b32_e32 v102, 16, v100
	v_and_b32_e32 v103, 0xffff0000, v100
	v_lshlrev_b32_e32 v100, 16, v101
	v_and_b32_e32 v101, 0xffff0000, v101
	v_pk_add_f32 v[98:99], v[42:43], v[98:99]
	v_pk_add_f32 v[96:97], v[40:41], v[96:97]
	v_pk_add_f32 v[130:131], v[50:51], v[100:101]
	v_pk_add_f32 v[128:129], v[48:49], v[102:103]
	v_cvt_pk_bf16_f32 v100, v96, v97
	v_cvt_pk_bf16_f32 v101, v98, v99
	v_mov_b32_e32 v163, v99
	v_cvt_pk_bf16_f32 v102, v128, v129
	v_cvt_pk_bf16_f32 v103, v130, v131
	global_store_dwordx4 v[124:125], v[100:103], off offset:1024 nt
	global_load_dwordx4 v[110:113], v[108:109], off offset:2048 nt
	v_mov_b32_e32 v162, v97
	v_mov_b32_e32 v165, v98
	v_mov_b32_e32 v164, v96
	s_waitcnt vmcnt(0)
	v_lshlrev_b32_e32 v100, 16, v110
	v_and_b32_e32 v101, 0xffff0000, v110
	v_lshlrev_b32_e32 v102, 16, v111
	v_and_b32_e32 v103, 0xffff0000, v111
	v_lshlrev_b32_e32 v110, 16, v112
	v_and_b32_e32 v111, 0xffff0000, v112
	v_lshlrev_b32_e32 v112, 16, v113
	v_and_b32_e32 v113, 0xffff0000, v113
	v_pk_add_f32 v[102:103], v[66:67], v[102:103]
	v_pk_add_f32 v[100:101], v[64:65], v[100:101]
	v_pk_add_f32 v[114:115], v[58:59], v[112:113]
	v_pk_add_f32 v[112:113], v[56:57], v[110:111]
	v_cvt_pk_bf16_f32 v120, v100, v101
	v_cvt_pk_bf16_f32 v121, v102, v103
	v_mov_b32_e32 v167, v115
	v_cvt_pk_bf16_f32 v122, v112, v113
	v_cvt_pk_bf16_f32 v123, v114, v115
	global_store_dwordx4 v[124:125], v[120:123], off offset:2048 nt
	global_load_dwordx4 v[108:111], v[108:109], off offset:3072 nt
	v_mov_b32_e32 v166, v113
	v_mov_b32_e32 v169, v114
	v_mov_b32_e32 v168, v112
	v_mov_b32_e32 v202, v100
	v_mov_b32_e32 v226, v101
	v_mov_b32_e32 v219, v102
	v_mov_b32_e32 v218, v103
	s_waitcnt vmcnt(0)
	v_lshlrev_b32_e32 v120, 16, v108
	v_and_b32_e32 v121, 0xffff0000, v108
	v_lshlrev_b32_e32 v108, 16, v109
	v_and_b32_e32 v109, 0xffff0000, v109
	v_pk_add_f32 v[138:139], v[62:63], v[108:109]
	v_lshlrev_b32_e32 v108, 16, v110
	v_and_b32_e32 v109, 0xffff0000, v110
	v_lshlrev_b32_e32 v110, 16, v111
	v_and_b32_e32 v111, 0xffff0000, v111
	v_pk_add_f32 v[136:137], v[60:61], v[120:121]
	v_pk_add_f32 v[110:111], v[70:71], v[110:111]
	v_pk_add_f32 v[108:109], v[68:69], v[108:109]
	v_cvt_pk_bf16_f32 v120, v136, v137
	v_cvt_pk_bf16_f32 v121, v138, v139
	v_mov_b32_e32 v230, v110
	v_cvt_pk_bf16_f32 v122, v108, v109
	v_cvt_pk_bf16_f32 v123, v110, v111
	global_store_dwordx4 v[124:125], v[120:123], off offset:3072 nt
	v_mov_b64_e32 v[124:125], v[128:129]
	v_mov_b64_e32 v[126:127], v[130:131]
	v_mov_b64_e32 v[120:121], v[136:137]
	v_mov_b64_e32 v[122:123], v[138:139]
	v_mov_b32_e32 v206, v108
	v_mov_b32_e32 v231, v109
	v_mov_b32_e32 v232, v111
	s_cbranch_execnz .LBB0_281
	s_branch .LBB0_280

.LBB0_296:
	v_lshl_add_u64 v[44:45], s[26:27], 0, v[150:151]
	v_add_co_u32_e32 v24, vcc, 0x1000, v44
	global_load_dwordx4 v[4:7], v[44:45], off offset:16 nt
	global_load_dwordx4 v[0:3], v[44:45], off nt
	global_load_dwordx4 v[12:15], v[44:45], off offset:2064 nt
	global_load_dwordx4 v[8:11], v[44:45], off offset:2048 nt
	v_addc_co_u32_e32 v25, vcc, 0, v45, vcc
	v_add_co_u32_e32 v34, vcc, 0x2000, v44
	v_lshl_add_u64 v[20:21], v[44:45], 0, s[64:65]
	s_nop 0
	v_addc_co_u32_e32 v35, vcc, 0, v45, vcc
	v_add_co_u32_e32 v48, vcc, s47, v44
	v_lshl_add_u64 v[26:27], v[44:45], 0, s[66:67]
	v_lshl_add_u64 v[32:33], v[44:45], 0, s[62:63]
	v_lshl_add_u64 v[40:41], v[44:45], 0, s[68:69]
	v_addc_co_u32_e32 v49, vcc, 0, v45, vcc
	global_load_dwordx4 v[16:19], v[24:25], off nt
	s_nop 0
	global_load_dwordx4 v[20:23], v[20:21], off offset:16 nt
	s_nop 0
	global_load_dwordx4 v[28:31], v[24:25], off offset:2048 nt
	s_nop 0
	global_load_dwordx4 v[24:27], v[26:27], off offset:16 nt
	s_nop 0
	global_load_dwordx4 v[36:39], v[34:35], off nt
	global_load_dwordx4 v[52:55], v[32:33], off offset:16 nt
	s_nop 0
	global_load_dwordx4 v[32:35], v[34:35], off offset:2048 nt
	s_nop 0
	global_load_dwordx4 v[40:43], v[40:41], off offset:16 nt
	v_lshl_add_u64 v[46:47], v[44:45], 0, s[70:71]
	global_load_dwordx4 v[64:67], v[48:49], off nt
	global_load_dwordx4 v[56:59], v[46:47], off offset:16 nt
	v_lshl_add_u64 v[44:45], v[44:45], 0, s[72:73]
	global_load_dwordx4 v[60:63], v[48:49], off offset:2048 nt
	global_load_dwordx4 v[68:71], v[44:45], off offset:16 nt
	s_and_b64 vcc, exec, s[20:21]
	s_cbranch_vccnz .LBB0_285

.LBB0_303:
	v_lshl_add_u64 v[24:25], s[4:5], 0, v[150:151]
	v_add_co_u32_e32 v26, vcc, 0x1000, v24
	v_lshl_add_u64 v[20:21], v[24:25], 0, s[64:65]
	s_nop 0
	v_addc_co_u32_e32 v27, vcc, 0, v25, vcc
	v_lshl_add_u64 v[28:29], v[24:25], 0, s[66:67]
	v_add_co_u32_e32 v32, vcc, 0x2000, v24
	global_load_dwordx4 v[4:7], v[24:25], off offset:16 nt
	global_load_dwordx4 v[0:3], v[24:25], off nt
	global_load_dwordx4 v[12:15], v[24:25], off offset:2064 nt
	global_load_dwordx4 v[8:11], v[24:25], off offset:2048 nt
	global_load_dwordx4 v[16:19], v[26:27], off nt
	s_nop 0
	global_load_dwordx4 v[20:23], v[20:21], off offset:16 nt
	s_nop 0
	global_load_dwordx4 v[36:39], v[26:27], off offset:2048 nt
	s_nop 0
	global_load_dwordx4 v[28:31], v[28:29], off offset:16 nt
	v_lshl_add_u64 v[26:27], v[24:25], 0, s[62:63]
	v_addc_co_u32_e32 v33, vcc, 0, v25, vcc
	global_load_dwordx4 v[44:47], v[32:33], off nt
	global_load_dwordx4 v[52:55], v[26:27], off offset:16 nt
	v_lshl_add_u64 v[26:27], v[24:25], 0, s[68:69]
	global_load_dwordx4 v[40:43], v[32:33], off offset:2048 nt
	global_load_dwordx4 v[48:51], v[26:27], off offset:16 nt
	v_add_co_u32_e32 v32, vcc, s47, v24
	v_lshl_add_u64 v[26:27], v[24:25], 0, s[70:71]
	s_nop 0
	v_addc_co_u32_e32 v33, vcc, 0, v25, vcc
	global_load_dwordx4 v[64:67], v[32:33], off nt
	global_load_dwordx4 v[56:59], v[26:27], off offset:16 nt
	v_lshl_add_u64 v[24:25], v[24:25], 0, s[72:73]
	global_load_dwordx4 v[60:63], v[32:33], off offset:2048 nt
	global_load_dwordx4 v[68:71], v[24:25], off offset:16 nt
	s_andn2_b64 vcc, exec, s[20:21]
	s_cbranch_vccz .LBB0_290

.LBB0_542:
	s_ashr_i32 s23, s22, 31
	s_mul_i32 s8, s22, 0x4800
	s_mul_hi_i32 s3, s22, 0x4800
	s_add_u32 s2, s15, s8
	s_addc_u32 s3, s16, s3
	v_lshlrev_b32_e32 v176, 1, v44
	v_lshl_add_u64 v[8:9], s[2:3], 0, v[176:177]
	v_add_co_u32_e32 v8, vcc, s46, v8
	s_add_i32 s28, s22, 1
	s_nop 0
	v_addc_co_u32_e32 v9, vcc, 0, v9, vcc
	global_load_dwordx4 v[36:39], v[8:9], off nt
	global_load_dwordx4 v[32:35], v[8:9], off offset:1024 nt
	s_add_i32 s2, s8, 0x4800
	s_mul_hi_i32 s3, s28, 0x4800
	s_add_u32 s2, s15, s2
	s_addc_u32 s3, s16, s3
	v_lshl_add_u64 v[8:9], s[2:3], 0, v[176:177]
	s_add_i32 s26, s22, 2
	s_add_i32 s2, s8, 0x9000
	v_add_co_u32_e32 v8, vcc, s46, v8
	s_mul_hi_i32 s3, s26, 0x4800
	s_add_u32 s2, s15, s2
	v_addc_co_u32_e32 v9, vcc, 0, v9, vcc
	s_addc_u32 s3, s16, s3
	global_load_dwordx4 v[28:31], v[8:9], off nt
	global_load_dwordx4 v[24:27], v[8:9], off offset:1024 nt
	v_lshl_add_u64 v[8:9], s[2:3], 0, v[176:177]
	s_add_i32 s24, s22, 3
	s_add_i32 s8, s8, 0xd800
	v_add_co_u32_e32 v8, vcc, s46, v8
	s_mul_hi_i32 s3, s24, 0x4800
	s_add_u32 s2, s15, s8
	v_addc_co_u32_e32 v9, vcc, 0, v9, vcc
	s_addc_u32 s3, s16, s3
	global_load_dwordx4 v[20:23], v[8:9], off nt
	global_load_dwordx4 v[12:15], v[8:9], off offset:1024 nt
	v_lshl_add_u64 v[8:9], s[2:3], 0, v[176:177]
	v_add_co_u32_e32 v8, vcc, s46, v8
	s_cmpk_gt_i32 s10, 0x7ff
	s_nop 0
	v_addc_co_u32_e32 v9, vcc, 0, v9, vcc
	global_load_dwordx4 v[16:19], v[8:9], off nt
	s_nop 0
	global_load_dwordx4 v[8:11], v[8:9], off offset:1024 nt
	s_cselect_b64 s[30:31], -1, 0
	s_lshr_b32 s37, s22, 6
	s_mov_b64 s[8:9], -1
	s_waitcnt vmcnt(0)
	v_lshlrev_b32_e32 v54, 16, v36
	v_and_b32_e32 v55, 0xffff0000, v36
	v_pk_mul_f32 v[56:57], v[54:55], v[54:55]
	v_lshlrev_b32_e32 v58, 16, v37
	v_and_b32_e32 v59, 0xffff0000, v37
	v_pk_mul_f32 v[36:37], v[58:59], v[58:59]
	v_add_f32_e32 v56, v56, v57
	v_lshlrev_b32_e32 v42, 16, v38
	v_and_b32_e32 v43, 0xffff0000, v38
	v_add_f32_e32 v36, v36, v56
	v_pk_mul_f32 v[40:41], v[42:43], v[42:43]
	v_add_f32_e32 v36, v37, v36
	v_lshlrev_b32_e32 v38, 16, v39
	v_and_b32_e32 v39, 0xffff0000, v39
	v_add_f32_e32 v36, v40, v36
	v_pk_mul_f32 v[52:53], v[38:39], v[38:39]
	v_add_f32_e32 v36, v41, v36
	v_add_f32_e32 v36, v52, v36
	v_add_f32_e32 v36, v53, v36
	ds_bpermute_b32 v37, v45, v36
	s_waitcnt lgkmcnt(0)
	v_add_f32_e32 v36, v36, v37
	ds_bpermute_b32 v37, v62, v36
	s_waitcnt lgkmcnt(0)
	v_add_f32_e32 v36, v36, v37
	ds_bpermute_b32 v37, v63, v36
	s_waitcnt lgkmcnt(0)
	v_add_f32_e32 v36, v36, v37
	ds_bpermute_b32 v37, v64, v36
	s_waitcnt lgkmcnt(0)
	v_add_f32_e32 v36, v36, v37
	v_fmamk_f32 v36, v36, 0x3c000000, v221
	v_cmp_gt_f32_e32 vcc, s42, v36
	v_mul_f32_e32 v37, 0x4b800000, v36
	s_nop 0
	v_cndmask_b32_e32 v36, v36, v37, vcc
	v_rsq_f32_e32 v36, v36
	s_nop 0
	v_mul_f32_e32 v37, 0x45800000, v36
	v_cndmask_b32_e32 v52, v36, v37, vcc
	v_pk_mul_f32 v[36:37], v[0:1], v[52:53] op_sel_hi:[1,0]
	v_pk_mul_f32 v[56:57], v[4:5], v[52:53] op_sel_hi:[1,0]
	v_pk_mul_f32 v[40:41], v[36:37], v[54:55]
	v_pk_mul_f32 v[36:37], v[56:57], v[42:43]
	v_pk_mul_f32 v[42:43], v[2:3], v[52:53] op_sel_hi:[1,0]
	v_pk_mul_f32 v[52:53], v[6:7], v[52:53] op_sel_hi:[1,0]
	v_pk_mul_f32 v[42:43], v[42:43], v[58:59]
	v_pk_mul_f32 v[38:39], v[52:53], v[38:39]
	s_and_b64 vcc, exec, s[30:31]
	s_cbranch_vccz .LBB0_544
	v_mov_b32_e32 v52, s22
	v_mov_b32_e32 v53, s37
	v_cndmask_b32_e64 v52, v52, v53, s[4:5]
	v_lshlrev_b32_e32 v52, 8, v52
	v_and_b32_e32 v176, 0x3f00, v52
	v_lshl_add_u64 v[52:53], v[46:47], 0, v[176:177]
	global_load_dwordx4 v[66:69], v[52:53], off offset:48
	global_load_dwordx4 v[58:61], v[52:53], off offset:32
	global_load_dwordx4 v[70:73], v[52:53], off offset:16
	s_nop 0
	global_load_dwordx4 v[52:55], v[52:53], off
	ds_bpermute_b32 v56, v63, v40
	ds_bpermute_b32 v57, v63, v41
	s_mov_b64 s[8:9], 0
	s_waitcnt vmcnt(0)
	v_mov_b32_e32 v75, v54
	v_mov_b32_e32 v54, v53
	v_mov_b32_e32 v74, v52
	s_waitcnt lgkmcnt(0)
	v_pk_mul_f32 v[52:53], v[54:55], v[56:57]
	v_mov_b32_e32 v57, v72
	v_cndmask_b32_e64 v53, v53, -v53, s[6:7]
	v_cndmask_b32_e64 v52, v52, -v52, s[6:7]
	v_pk_fma_f32 v[54:55], v[40:41], v[74:75], v[52:53]
	ds_bpermute_b32 v52, v63, v42
	ds_bpermute_b32 v53, v63, v43
	v_mov_b32_e32 v72, v71
	v_mov_b32_e32 v56, v70
	v_mov_b32_e32 v71, v60
	v_mov_b32_e32 v60, v59
	s_waitcnt lgkmcnt(0)
	v_pk_mul_f32 v[52:53], v[72:73], v[52:53]
	v_mov_b32_e32 v70, v58
	v_cndmask_b32_e64 v53, v53, -v53, s[6:7]
	v_cndmask_b32_e64 v52, v52, -v52, s[6:7]
	v_pk_fma_f32 v[56:57], v[42:43], v[56:57], v[52:53]
	ds_bpermute_b32 v52, v63, v36
	ds_bpermute_b32 v53, v63, v37
	s_waitcnt lgkmcnt(0)
	v_pk_mul_f32 v[52:53], v[60:61], v[52:53]
	s_nop 0
	v_cndmask_b32_e64 v53, v53, -v53, s[6:7]
	v_cndmask_b32_e64 v52, v52, -v52, s[6:7]
	v_pk_fma_f32 v[58:59], v[36:37], v[70:71], v[52:53]
	ds_bpermute_b32 v52, v63, v38
	ds_bpermute_b32 v53, v63, v39
	v_mov_b32_e32 v61, v68
	v_mov_b32_e32 v68, v67
	v_mov_b32_e32 v60, v66
	s_waitcnt lgkmcnt(0)
	v_pk_mul_f32 v[52:53], v[68:69], v[52:53]
	s_nop 0
	v_cndmask_b32_e64 v53, v53, -v53, s[6:7]
	v_cndmask_b32_e64 v52, v52, -v52, s[6:7]
	v_pk_fma_f32 v[60:61], v[38:39], v[60:61], v[52:53]

.LBB0_708:
	s_mov_b64 s[2:3], s[0:1]
	s_mov_b32 s4, s12
	s_mov_b32 s5, s13
	s_load_dwordx2 s[4:5], s[2:3], 0x70
	s_load_dwordx2 s[34:35], s[2:3], 0xe8
	s_lshl_b64 s[2:3], s[50:51], 2
	v_mov_b32_e32 v145, v220
	s_waitcnt lgkmcnt(0)
	s_add_u32 s4, s4, s2
	s_addc_u32 s5, s5, s3
	s_add_u32 s2, s34, 0x200000
	s_addc_u32 s3, s35, 0
	s_bfe_u32 s6, s9, 0x10002
	s_lshl_b32 s10, s6, 12
	s_or_b32 s11, s10, 0x2000
	s_lshl_b32 s10, s9, 5
	s_lshl_b32 s6, s6, 20
	s_and_b32 s7, s9, 3
	s_and_b32 s22, s10, 0xf00
	s_add_i32 s6, s6, s8
	s_and_b32 s16, s9, 0xffffff80
	s_or_b32 s10, s11, s22
	s_lshl_b32 s6, s6, 1
	s_lshl_b32 s15, s7, 8
	s_add_u32 s6, s34, s6
	s_addc_u32 s18, s35, 0
	s_add_u32 s20, s6, s15
	s_addc_u32 s21, s18, 0
	s_add_u32 s48, s20, 0x600000
	s_addc_u32 s49, s21, 0
	s_add_u32 s56, s20, 0xa00000
	s_addc_u32 s57, s21, 0
	s_lshl_b32 s6, s11, 10
	s_add_u32 s6, s34, s6
	s_addc_u32 s11, s35, 0
	s_add_u32 s6, s6, s15
	s_addc_u32 s11, s11, 0
	s_add_u32 s36, s6, 0x68600000
	s_addc_u32 s43, s11, 0
	s_add_u32 s44, s6, 0x69600000
	s_addc_u32 s52, s11, 0
	s_mul_i32 s6, s10, 0x4800
	s_add_u32 s6, s34, s6
	s_addc_u32 s15, s35, 0
	s_add_u32 s11, s6, 0x2e600000
	s_addc_u32 s15, s15, 0
	s_lshl_b32 s6, s7, 9
	s_add_i32 s6, s6, s16
	v_ashrrev_i32_e32 v136, 4, v145
	s_ashr_i32 s7, s6, 31
	v_add_u32_e32 v138, 32, v136
	s_lshl_b64 s[6:7], s[6:7], 1
	v_lshlrev_b32_e32 v18, 3, v145
	v_ashrrev_i32_e32 v137, 31, v136
	v_ashrrev_i32_e32 v139, 31, v138
	s_add_u32 s18, s11, s6
	v_ashrrev_i32_e32 v228, 6, v145
	v_and_b32_e32 v144, 0x78, v18
	v_lshlrev_b64 v[132:133], 10, v[136:137]
	v_lshlrev_b64 v[134:135], 10, v[138:139]
	s_addc_u32 s19, s15, s7
	v_and_b32_e32 v227, 31, v145
	v_lshlrev_b32_e32 v188, 1, v144
	v_lshl_add_u64 v[0:1], s[56:57], 0, v[132:133]
	v_mov_b32_e32 v189, v177
	v_lshl_add_u64 v[2:3], s[56:57], 0, v[134:135]
	v_lshlrev_b32_e32 v229, 5, v228
	v_bfe_u32 v226, v145, 5, 1
	v_lshl_add_u64 v[0:1], v[0:1], 0, v[188:189]
	v_lshl_add_u64 v[2:3], v[2:3], 0, v[188:189]
	v_or_b32_e32 v19, v229, v227
	v_mov_b64_e32 v[16:17], s[18:19]
	global_load_dwordx4 v[8:11], v[0:1], off
	global_load_dwordx4 v[4:7], v[2:3], off
	v_lshl_add_u64 v[0:1], s[48:49], 0, v[132:133]
	v_lshl_add_u64 v[2:3], s[48:49], 0, v[134:135]
	v_mad_i64_i32 v[16:17], s[18:19], v19, s45, v[16:17]
	v_lshlrev_b32_e32 v190, 4, v226
	v_mov_b32_e32 v191, v177
	v_lshl_add_u64 v[0:1], v[0:1], 0, v[188:189]
	v_lshl_add_u64 v[2:3], v[2:3], 0, v[188:189]
	v_lshl_add_u64 v[16:17], v[16:17], 0, v[190:191]
	global_load_dwordx4 v[12:15], v[0:1], off
	s_nop 0
	global_load_dwordx4 v[0:3], v[2:3], off
	s_barrier
	global_load_dwordx4 v[162:165], v[16:17], off offset:160 nt
	global_load_dwordx4 v[166:169], v[16:17], off offset:224 nt
	v_and_b32_e32 v20, 32, v145
	global_load_dwordx4 v[154:157], v20, s[4:5] offset:464
	global_load_dwordx4 v[32:35], v20, s[4:5] offset:336
	global_load_dwordx4 v[178:181], v[16:17], off offset:128 nt
	global_load_dwordx4 v[182:185], v[16:17], off offset:192 nt
	global_load_dwordx4 v[44:47], v20, s[4:5] offset:320
	global_load_dwordx4 v[192:195], v20, s[4:5] offset:448
	global_load_dwordx4 v[120:123], v[16:17], off nt
	global_load_dwordx4 v[128:131], v[16:17], off offset:32 nt
	global_load_dwordx4 v[200:203], v20, s[4:5] offset:400
	global_load_dwordx4 v[80:83], v20, s[4:5] offset:272
	global_load_dwordx4 v[210:213], v20, s[4:5] offset:384
	global_load_dwordx4 v[88:91], v20, s[4:5] offset:256
	global_load_dwordx4 v[116:119], v[16:17], off offset:64 nt
	global_load_dwordx4 v[232:235], v[16:17], off offset:96 nt
	global_load_dwordx4 v[108:111], v20, s[4:5]
	global_load_dwordx4 v[104:107], v20, s[4:5] offset:16
	global_load_dwordx4 v[100:103], v20, s[4:5] offset:64
	global_load_dwordx4 v[96:99], v20, s[4:5] offset:80
	global_load_dwordx4 v[112:115], v20, s[4:5] offset:128
	global_load_dwordx4 v[124:127], v20, s[4:5] offset:144
	global_load_dwordx4 v[236:239], v20, s[4:5] offset:192
	global_load_dwordx4 v[240:243], v20, s[4:5] offset:208
	v_and_b32_e32 v21, 0xfffff0, v136
	v_lshlrev_b32_e32 v22, 1, v136
	v_and_or_b32 v21, v22, 8, v21
	v_lshrrev_b32_e32 v22, 1, v136
	v_and_b32_e32 v23, 3, v136
	v_and_or_b32 v22, v22, 4, v23
	v_and_b32_e32 v23, 0xfffff0, v138
	v_lshlrev_b32_e32 v24, 1, v138
	v_and_or_b32 v23, v24, 8, v23
	v_lshrrev_b32_e32 v21, 1, v21
	v_bfe_u32 v18, v18, 5, 2
	v_lshrrev_b32_e32 v23, 1, v23
	v_or_b32_e32 v21, v21, v18
	v_or_b32_e32 v18, v23, v18
	v_lshlrev_b32_e32 v21, 9, v21
	v_lshlrev_b32_e32 v22, 6, v22
	v_lshlrev_b32_e32 v18, 9, v18
	v_and_b32_e32 v16, 48, v188
	v_or3_b32 v191, v18, v22, v16
	v_or3_b32 v231, v21, v22, v16
	v_or_b32_e32 v16, s22, v227
	v_add_u32_e32 v16, v16, v229
	v_ashrrev_i32_e32 v16, 1, v16
	v_and_b32_e32 v16, 0xffffffe0, v16
	v_ashrrev_i32_e32 v17, 31, v16
	v_lshl_add_u64 v[16:17], v[16:17], 3, s[2:3]
	v_lshlrev_b32_e32 v176, 6, v226
	v_lshl_add_u64 v[16:17], v[16:17], 0, v[176:177]
	global_load_dwordx4 v[68:71], v[16:17], off offset:48
	global_load_dwordx4 v[76:79], v[16:17], off offset:32
	global_load_dwordx4 v[84:87], v[16:17], off offset:16
	global_load_dwordx4 v[92:95], v[16:17], off
	global_load_dwordx4 v[48:51], v[16:17], off offset:176
	global_load_dwordx4 v[56:59], v[16:17], off offset:160
	global_load_dwordx4 v[64:67], v[16:17], off offset:144
	global_load_dwordx4 v[72:75], v[16:17], off offset:128
	v_lshlrev_b32_e32 v16, 8, v19
	v_and_b32_e32 v16, 0x3f00, v16
	v_mov_b32_e32 v17, v177
	v_lshl_add_u64 v[16:17], s[2:3], 0, v[16:17]
	v_lshl_add_u64 v[36:37], v[16:17], 0, v[176:177]
	global_load_dwordx4 v[28:31], v[36:37], off offset:48
	global_load_dwordx4 v[40:43], v[36:37], off offset:32
	global_load_dwordx4 v[52:55], v[36:37], off offset:16
	global_load_dwordx4 v[60:63], v[36:37], off
	global_load_dwordx4 v[16:19], v[36:37], off offset:176
	global_load_dwordx4 v[20:23], v[36:37], off offset:160
	global_load_dwordx4 v[24:27], v[36:37], off offset:144
	s_nop 0
	global_load_dwordx4 v[36:39], v[36:37], off offset:128
	v_lshlrev_b32_e32 v230, 4, v145
	s_add_i32 s2, 0, 0x10000
	s_cmp_lg_u32 0, -1
	s_cselect_b32 s4, 0, 0
	s_mov_b32 s16, s17
	s_mov_b32 s18, s17
	s_mov_b32 s19, s17
	s_mov_b32 s24, s17
	s_mov_b32 s25, s17
	s_mov_b32 s26, s17
	s_mov_b32 s27, s17
	s_mov_b32 s28, s17
	s_mov_b32 s29, s17
	s_mov_b32 s30, s17
	s_mov_b32 s31, s17
	s_mov_b32 s85, 4
	v_lshlrev_b32_e32 v176, 1, v144
	s_waitcnt vmcnt(31)
	v_lshlrev_b32_e32 v225, 16, v123
	v_mov_b32_e32 v146, v156
	v_mov_b32_e32 v152, v154
	v_lshlrev_b32_e32 v141, 16, v165
	v_lshlrev_b32_e32 v140, 16, v169
	v_and_b32_e32 v142, 0xffff0000, v169
	v_lshlrev_b32_e32 v154, 16, v167
	v_and_b32_e32 v156, 0xffff0000, v167
	v_lshlrev_b32_e32 v167, 16, v181
	v_and_b32_e32 v169, 0xffff0000, v181
	s_waitcnt vmcnt(21)
	v_mov_b32_e32 v181, v102
	s_waitcnt vmcnt(17)
	v_mov_b32_e32 v102, v239
	v_lshlrev_b32_e32 v239, 16, v120
	v_and_b32_e32 v143, 0xffff0000, v165
	v_mov_b32_e32 v165, v44
	v_mov_b32_e32 v44, v193
	v_lshlrev_b32_e32 v175, 16, v180
	v_and_b32_e32 v193, 0xffff0000, v180
	s_waitcnt vmcnt(16)
	v_mov_b32_e32 v218, v240
	v_mov_b32_e32 v219, v96
	v_mov_b32_e32 v96, v241
	v_mov_b32_e32 v180, v238
	v_and_b32_e32 v241, 0xffff0000, v120
	v_lshlrev_b32_e32 v238, 16, v116
	v_and_b32_e32 v240, 0xffff0000, v116
	v_mul_f32_e32 v116, v239, v239
	v_mov_b32_e32 v170, v202
	v_mov_b32_e32 v202, v212
	v_mov_b32_e32 v208, v210
	v_lshlrev_b32_e32 v210, 16, v235
	v_and_b32_e32 v212, 0xffff0000, v235
	v_mov_b32_e32 v235, v104
	v_mov_b32_e32 v104, v125
	v_lshlrev_b32_e32 v125, 16, v121
	v_fmac_f32_e32 v116, v241, v241
	v_and_b32_e32 v121, 0xffff0000, v121
	v_fmac_f32_e32 v116, v125, v125
	v_lshlrev_b32_e32 v205, 16, v178
	v_lshlrev_b32_e32 v204, 16, v182
	v_and_b32_e32 v207, 0xffff0000, v178
	v_and_b32_e32 v206, 0xffff0000, v182
	v_lshlrev_b32_e32 v178, 16, v233
	v_and_b32_e32 v182, 0xffff0000, v233
	v_mov_b32_e32 v233, v106
	v_mov_b32_e32 v106, v127
	v_lshlrev_b32_e32 v127, 16, v122
	v_fmac_f32_e32 v116, v121, v121
	v_mov_b32_e32 v187, v100
	v_mov_b32_e32 v100, v237
	v_and_b32_e32 v237, 0xffff0000, v122
	v_fmac_f32_e32 v116, v127, v127
	v_fmac_f32_e32 v116, v237, v237
	v_and_b32_e32 v123, 0xffff0000, v123
	v_fmac_f32_e32 v116, v225, v225
	v_mov_b32_e32 v147, v34
	v_mov_b32_e32 v34, v157
	v_lshlrev_b32_e32 v148, 16, v168
	v_mov_b32_e32 v153, v32
	v_and_b32_e32 v150, 0xffff0000, v168
	v_mov_b32_e32 v32, v155
	v_lshlrev_b32_e32 v155, 16, v163
	v_and_b32_e32 v157, 0xffff0000, v163
	v_lshlrev_b32_e32 v161, 16, v162
	v_lshlrev_b32_e32 v160, 16, v166
	v_and_b32_e32 v163, 0xffff0000, v162
	v_and_b32_e32 v162, 0xffff0000, v166
	v_lshlrev_b32_e32 v166, 16, v185
	v_and_b32_e32 v168, 0xffff0000, v185
	v_lshlrev_b32_e32 v185, 16, v128
	v_fmac_f32_e32 v116, v123, v123
	v_mov_b32_e32 v158, v194
	v_mov_b32_e32 v159, v46
	v_mov_b32_e32 v46, v195
	v_mov_b32_e32 v194, v200
	v_mov_b32_e32 v195, v80
	v_mov_b32_e32 v80, v201
	v_lshlrev_b32_e32 v197, 16, v179
	v_lshlrev_b32_e32 v196, 16, v183
	v_and_b32_e32 v201, 0xffff0000, v179
	v_and_b32_e32 v200, 0xffff0000, v183
	v_lshlrev_b32_e32 v179, 16, v129
	v_and_b32_e32 v183, 0xffff0000, v129
	v_and_b32_e32 v129, 0xffff0000, v128
	v_fmac_f32_e32 v116, v185, v185
	v_fmac_f32_e32 v116, v129, v129
	v_fmac_f32_e32 v116, v179, v179
	v_lshlrev_b32_e32 v217, 16, v130
	v_fmac_f32_e32 v116, v183, v183
	v_mov_b32_e32 v171, v82
	v_mov_b32_e32 v82, v203
	v_mov_b32_e32 v203, v90
	v_mov_b32_e32 v90, v213
	v_mov_b32_e32 v209, v88
	v_mov_b32_e32 v88, v211
	v_lshlrev_b32_e32 v211, 16, v131
	v_and_b32_e32 v213, 0xffff0000, v131
	v_and_b32_e32 v131, 0xffff0000, v130
	v_fmac_f32_e32 v116, v217, v217
	v_fmac_f32_e32 v116, v131, v131
	v_fmac_f32_e32 v116, v211, v211
	v_fmac_f32_e32 v116, v213, v213
	v_lshlrev_b32_e32 v216, 16, v234
	v_and_b32_e32 v130, 0xffff0000, v234
	v_mov_b32_e32 v234, v124
	v_lshlrev_b32_e32 v124, 16, v117
	v_and_b32_e32 v120, 0xffff0000, v117
	v_pk_fma_f32 v[116:117], v[238:239], v[238:239], v[116:117] op_sel_hi:[1,1,0]
	v_lshlrev_b32_e32 v149, 16, v164
	v_pk_fma_f32 v[116:117], v[240:241], v[240:241], v[116:117]
	v_and_b32_e32 v151, 0xffff0000, v164
	v_pk_fma_f32 v[116:117], v[124:125], v[124:125], v[116:117]
	v_mov_b32_e32 v164, v192
	v_lshlrev_b32_e32 v174, 16, v184
	v_and_b32_e32 v192, 0xffff0000, v184
	v_lshlrev_b32_e32 v184, 16, v232
	v_and_b32_e32 v128, 0xffff0000, v232
	v_mov_b32_e32 v232, v126
	v_lshlrev_b32_e32 v126, 16, v118
	v_pk_fma_f32 v[116:117], v[120:121], v[120:121], v[116:117]
	v_mov_b32_e32 v186, v236
	v_and_b32_e32 v236, 0xffff0000, v118
	v_pk_fma_f32 v[116:117], v[126:127], v[126:127], v[116:117]
	v_lshlrev_b32_e32 v224, 16, v119
	v_pk_fma_f32 v[116:117], v[236:237], v[236:237], v[116:117]
	v_and_b32_e32 v122, 0xffff0000, v119
	v_pk_fma_f32 v[116:117], v[224:225], v[224:225], v[116:117]
	v_mul_f32_e32 v118, v205, v205
	v_pk_fma_f32 v[116:117], v[122:123], v[122:123], v[116:117]
	v_mov_b32_e32 v214, v242
	v_pk_fma_f32 v[116:117], v[184:185], v[184:185], v[116:117]
	v_mov_b32_e32 v215, v98
	v_pk_fma_f32 v[116:117], v[128:129], v[128:129], v[116:117]
	v_mov_b32_e32 v98, v243
	v_pk_fma_f32 v[116:117], v[178:179], v[178:179], v[116:117]
	v_mov_b32_e32 v242, v156
	v_pk_fma_f32 v[116:117], v[182:183], v[182:183], v[116:117]
	v_mov_b32_e32 v243, v154
	v_pk_fma_f32 v[116:117], v[216:217], v[216:217], v[116:117]
	v_mov_b32_e32 v198, v150
	v_pk_fma_f32 v[116:117], v[130:131], v[130:131], v[116:117]
	v_mov_b32_e32 v199, v148
	v_pk_fma_f32 v[116:117], v[210:211], v[210:211], v[116:117]
	v_mov_b32_e32 v172, v142
	v_pk_fma_f32 v[116:117], v[212:213], v[212:213], v[116:117]
	v_mov_b32_e32 v173, v140
	v_pk_add_f32 v[116:117], v[118:119], v[116:117] op_sel_hi:[0,1]
	v_mul_f32_e32 v118, v207, v207
	v_pk_add_f32 v[116:117], v[118:119], v[116:117] op_sel_hi:[0,1]
	v_mul_f32_e32 v118, v197, v197
	v_pk_add_f32 v[116:117], v[118:119], v[116:117] op_sel_hi:[0,1]
	v_mul_f32_e32 v118, v201, v201
	v_pk_add_f32 v[116:117], v[118:119], v[116:117] op_sel_hi:[0,1]
	v_mul_f32_e32 v118, v175, v175
	v_pk_add_f32 v[116:117], v[118:119], v[116:117] op_sel_hi:[0,1]
	v_mul_f32_e32 v118, v193, v193
	v_pk_add_f32 v[116:117], v[118:119], v[116:117] op_sel_hi:[0,1]
	v_mul_f32_e32 v118, v167, v167
	v_pk_add_f32 v[116:117], v[118:119], v[116:117] op_sel_hi:[0,1]
	v_mul_f32_e32 v118, v169, v169
	v_pk_add_f32 v[116:117], v[118:119], v[116:117] op_sel_hi:[0,1]
	v_mul_f32_e32 v118, v161, v161
	v_pk_add_f32 v[116:117], v[118:119], v[116:117] op_sel_hi:[0,1]
	v_mul_f32_e32 v118, v163, v163
	v_pk_add_f32 v[116:117], v[118:119], v[116:117] op_sel_hi:[0,1]
	v_mul_f32_e32 v118, v155, v155
	v_pk_add_f32 v[116:117], v[118:119], v[116:117] op_sel_hi:[0,1]
	v_mul_f32_e32 v118, v157, v157
	v_pk_add_f32 v[116:117], v[118:119], v[116:117] op_sel_hi:[0,1]
	v_mul_f32_e32 v118, v149, v149
	v_pk_add_f32 v[116:117], v[118:119], v[116:117] op_sel_hi:[0,1]
	v_mul_f32_e32 v118, v151, v151
	v_pk_add_f32 v[116:117], v[118:119], v[116:117] op_sel_hi:[0,1]
	v_mul_f32_e32 v118, v141, v141
	v_pk_add_f32 v[116:117], v[118:119], v[116:117] op_sel_hi:[0,1]
	v_mul_f32_e32 v118, v143, v143
	v_pk_add_f32 v[116:117], v[118:119], v[116:117] op_sel_hi:[0,1]
	v_pk_fma_f32 v[116:117], v[204:205], v[204:205], v[116:117]
	v_mul_f32_e32 v118, v154, v154
	v_pk_fma_f32 v[116:117], v[206:207], v[206:207], v[116:117]
	s_nop 0
	v_pk_fma_f32 v[116:117], v[196:197], v[196:197], v[116:117]
	s_nop 0
	v_pk_fma_f32 v[116:117], v[200:201], v[200:201], v[116:117]
	s_nop 0
	v_pk_fma_f32 v[116:117], v[174:175], v[174:175], v[116:117]
	s_nop 0
	v_pk_fma_f32 v[116:117], v[192:193], v[192:193], v[116:117]
	s_nop 0
	v_pk_fma_f32 v[116:117], v[166:167], v[166:167], v[116:117]
	s_nop 0
	v_pk_fma_f32 v[116:117], v[168:169], v[168:169], v[116:117]
	s_nop 0
	v_pk_fma_f32 v[116:117], v[160:161], v[160:161], v[116:117]
	s_nop 0
	v_pk_fma_f32 v[116:117], v[162:163], v[162:163], v[116:117]
	s_nop 0
	v_pk_add_f32 v[116:117], v[118:119], v[116:117] op_sel_hi:[0,1]
	v_mov_b32_e32 v119, v110
	v_pk_fma_f32 v[116:117], v[242:243], v[242:243], v[116:117]
	v_mul_f32_e32 v110, v148, v148
	v_pk_add_f32 v[116:117], v[110:111], v[116:117] op_sel_hi:[0,1]
	v_pk_fma_f32 v[116:117], v[198:199], v[198:199], v[116:117]
	v_mul_f32_e32 v110, v140, v140
	v_pk_add_f32 v[116:117], v[110:111], v[116:117] op_sel_hi:[0,1]
	v_pk_fma_f32 v[116:117], v[172:173], v[172:173], v[116:117]
	v_mov_b32_e32 v118, v114
	v_mov_b32_e32 v110, v116
	s_nop 1
	v_permlane32_swap_b32_e32 v116, v110
	v_add_f32_e32 v110, v116, v110
	v_fmamk_f32 v110, v110, 0x3c000000, v221
	v_mul_f32_e32 v114, 0x4b800000, v110
	v_cmp_gt_f32_e32 vcc, s42, v110
	s_nop 1
	v_cndmask_b32_e32 v110, v110, v114, vcc
	v_rsq_f32_e32 v116, v110
	v_mov_b32_e32 v110, v115
	v_mov_b32_e32 v115, v108
	v_mov_b32_e32 v114, v112
	v_mul_f32_e32 v108, 0x45800000, v116
	v_cndmask_b32_e32 v112, v116, v108, vcc
	v_pk_mul_f32 v[114:115], v[114:115], v[112:113] op_sel_hi:[1,0]
	v_mov_b32_e32 v108, v113
	v_pk_mul_f32 v[114:115], v[114:115], v[238:239]
	v_pk_mul_f32 v[116:117], v[234:235], v[112:113] op_sel_hi:[1,0]
	v_pk_mul_f32 v[108:109], v[108:109], v[112:113] op_sel_hi:[1,0]
	v_pk_mul_f32 v[118:119], v[118:119], v[112:113] op_sel_hi:[1,0]
	v_pk_mul_f32 v[110:111], v[110:111], v[112:113] op_sel_hi:[1,0]
	v_pk_mul_f32 v[106:107], v[106:107], v[112:113] op_sel_hi:[1,0]
	v_pk_mul_f32 v[100:101], v[100:101], v[112:113] op_sel_hi:[1,0]
	v_pk_mul_f32 v[96:97], v[96:97], v[112:113] op_sel_hi:[1,0]
	v_pk_mul_f32 v[172:173], v[112:113], v[194:195] op_sel_hi:[0,1]
	v_pk_mul_f32 v[32:33], v[112:113], v[32:33] op_sel_hi:[0,1]
	v_pk_mul_f32 v[116:117], v[116:117], v[126:127]
	v_pk_mul_f32 v[108:109], v[108:109], v[240:241]
	v_pk_mul_f32 v[104:105], v[104:105], v[112:113] op_sel_hi:[1,0]
	v_pk_mul_f32 v[118:119], v[118:119], v[124:125]
	v_pk_mul_f32 v[124:125], v[232:233], v[112:113] op_sel_hi:[1,0]
	v_pk_mul_f32 v[110:111], v[110:111], v[120:121]
	v_pk_mul_f32 v[106:107], v[106:107], v[122:123]
	v_pk_mul_f32 v[120:121], v[186:187], v[112:113] op_sel_hi:[1,0]
	v_pk_mul_f32 v[122:123], v[218:219], v[112:113] op_sel_hi:[1,0]
	v_pk_mul_f32 v[100:101], v[100:101], v[128:129]
	v_pk_mul_f32 v[96:97], v[96:97], v[130:131]
	v_pk_mul_f32 v[126:127], v[180:181], v[112:113] op_sel_hi:[1,0]
	v_pk_mul_f32 v[128:129], v[214:215], v[112:113] op_sel_hi:[1,0]
	v_pk_mul_f32 v[102:103], v[102:103], v[112:113] op_sel_hi:[1,0]
	v_pk_mul_f32 v[98:99], v[98:99], v[112:113] op_sel_hi:[1,0]
	v_pk_mul_f32 v[130:131], v[112:113], v[208:209] op_sel_hi:[0,1]
	v_pk_mul_f32 v[172:173], v[172:173], v[174:175]
	v_pk_mul_f32 v[88:89], v[112:113], v[88:89] op_sel_hi:[0,1]
	v_pk_mul_f32 v[80:81], v[112:113], v[80:81] op_sel_hi:[0,1]
	v_pk_mul_f32 v[174:175], v[112:113], v[202:203] op_sel_hi:[0,1]
	v_pk_mul_f32 v[170:171], v[112:113], v[170:171] op_sel_hi:[0,1]
	v_pk_mul_f32 v[90:91], v[112:113], v[90:91] op_sel_hi:[0,1]
	v_pk_mul_f32 v[82:83], v[112:113], v[82:83] op_sel_hi:[0,1]
	v_pk_mul_f32 v[164:165], v[112:113], v[164:165] op_sel_hi:[0,1]
	v_pk_mul_f32 v[152:153], v[112:113], v[152:153] op_sel_hi:[0,1]
	v_pk_mul_f32 v[44:45], v[112:113], v[44:45] op_sel_hi:[0,1]
	v_pk_mul_f32 v[32:33], v[32:33], v[150:151]
	v_pk_mul_f32 v[150:151], v[112:113], v[158:159] op_sel_hi:[0,1]
	v_pk_mul_f32 v[146:147], v[112:113], v[146:147] op_sel_hi:[0,1]
	v_pk_mul_f32 v[46:47], v[112:113], v[46:47] op_sel_hi:[0,1]
	v_pk_mul_f32 v[34:35], v[112:113], v[34:35] op_sel_hi:[0,1]
	s_waitcnt vmcnt(12)
	v_pk_mul_f32 v[112:113], v[114:115], v[92:93] op_sel:[1,0] op_sel_hi:[0,1]
	v_pk_mul_f32 v[92:93], v[114:115], v[92:93]
	v_sub_f32_e32 v112, v112, v113
	v_add_f32_e32 v113, v93, v92
	v_pk_mul_f32 v[92:93], v[108:109], v[94:95] op_sel:[1,0] op_sel_hi:[0,1]
	v_sub_f32_e32 v114, v92, v93
	v_pk_mul_f32 v[92:93], v[108:109], v[94:95]
	v_pk_mul_f32 v[104:105], v[104:105], v[236:237]
	v_add_f32_e32 v94, v93, v92
	v_pk_mul_f32 v[92:93], v[118:119], v[84:85] op_sel:[1,0] op_sel_hi:[0,1]
	v_pk_mul_f32 v[84:85], v[118:119], v[84:85]
	v_sub_f32_e32 v92, v92, v93
	v_add_f32_e32 v93, v85, v84
	v_pk_mul_f32 v[84:85], v[110:111], v[86:87] op_sel:[1,0] op_sel_hi:[0,1]
	v_sub_f32_e32 v95, v84, v85
	v_pk_mul_f32 v[84:85], v[110:111], v[86:87]
	v_pk_mul_f32 v[124:125], v[124:125], v[224:225]
	v_add_f32_e32 v86, v85, v84
	v_pk_mul_f32 v[84:85], v[116:117], v[76:77] op_sel:[1,0] op_sel_hi:[0,1]
	v_pk_mul_f32 v[76:77], v[116:117], v[76:77]
	v_sub_f32_e32 v84, v84, v85
	v_add_f32_e32 v85, v77, v76
	v_pk_mul_f32 v[76:77], v[104:105], v[78:79] op_sel:[1,0] op_sel_hi:[0,1]
	v_sub_f32_e32 v87, v76, v77
	v_pk_mul_f32 v[76:77], v[104:105], v[78:79]
	v_pk_mul_f32 v[120:121], v[120:121], v[184:185]
	v_add_f32_e32 v78, v77, v76
	v_pk_mul_f32 v[76:77], v[124:125], v[68:69] op_sel:[1,0] op_sel_hi:[0,1]
	v_pk_mul_f32 v[68:69], v[124:125], v[68:69]
	v_sub_f32_e32 v76, v76, v77
	v_add_f32_e32 v77, v69, v68
	v_pk_mul_f32 v[68:69], v[106:107], v[70:71] op_sel:[1,0] op_sel_hi:[0,1]
	v_sub_f32_e32 v79, v68, v69
	v_pk_mul_f32 v[68:69], v[106:107], v[70:71]
	v_pk_mul_f32 v[126:127], v[126:127], v[178:179]
	v_add_f32_e32 v70, v69, v68
	s_waitcnt vmcnt(8)
	v_pk_mul_f32 v[68:69], v[120:121], v[72:73] op_sel:[1,0] op_sel_hi:[0,1]
	v_sub_f32_e32 v71, v68, v69
	v_pk_mul_f32 v[68:69], v[120:121], v[72:73]
	v_pk_mul_f32 v[102:103], v[102:103], v[182:183]
	v_add_f32_e32 v72, v69, v68
	v_pk_mul_f32 v[68:69], v[100:101], v[74:75] op_sel:[1,0] op_sel_hi:[0,1]
	v_sub_f32_e32 v73, v68, v69
	v_pk_mul_f32 v[68:69], v[100:101], v[74:75]
	v_pk_mul_f32 v[122:123], v[122:123], v[216:217]
	v_add_f32_e32 v74, v69, v68
	v_pk_mul_f32 v[68:69], v[126:127], v[64:65] op_sel:[1,0] op_sel_hi:[0,1]
	v_pk_mul_f32 v[64:65], v[126:127], v[64:65]
	v_sub_f32_e32 v68, v68, v69
	v_add_f32_e32 v69, v65, v64
	v_pk_mul_f32 v[64:65], v[102:103], v[66:67] op_sel:[1,0] op_sel_hi:[0,1]
	v_sub_f32_e32 v75, v64, v65
	v_pk_mul_f32 v[64:65], v[102:103], v[66:67]
	v_pk_mul_f32 v[128:129], v[128:129], v[210:211]
	v_add_f32_e32 v66, v65, v64
	v_pk_mul_f32 v[64:65], v[122:123], v[56:57] op_sel:[1,0] op_sel_hi:[0,1]
	v_pk_mul_f32 v[56:57], v[122:123], v[56:57]
	v_sub_f32_e32 v64, v64, v65
	v_add_f32_e32 v65, v57, v56
	v_pk_mul_f32 v[56:57], v[96:97], v[58:59] op_sel:[1,0] op_sel_hi:[0,1]
	v_sub_f32_e32 v67, v56, v57
	v_pk_mul_f32 v[56:57], v[96:97], v[58:59]
	v_pk_mul_f32 v[98:99], v[98:99], v[212:213]
	v_add_f32_e32 v58, v57, v56
	v_pk_mul_f32 v[56:57], v[128:129], v[48:49] op_sel:[1,0] op_sel_hi:[0,1]
	v_pk_mul_f32 v[48:49], v[128:129], v[48:49]
	v_sub_f32_e32 v56, v56, v57
	v_add_f32_e32 v57, v49, v48
	v_pk_mul_f32 v[48:49], v[98:99], v[50:51] op_sel:[1,0] op_sel_hi:[0,1]
	v_pk_mul_f32 v[130:131], v[130:131], v[204:205]
	v_sub_f32_e32 v59, v48, v49
	v_pk_mul_f32 v[48:49], v[98:99], v[50:51]
	v_pk_mul_f32 v[88:89], v[88:89], v[206:207]
	v_add_f32_e32 v50, v49, v48
	s_waitcnt vmcnt(4)
	v_pk_mul_f32 v[48:49], v[130:131], v[60:61] op_sel:[1,0] op_sel_hi:[0,1]
	v_sub_f32_e32 v51, v48, v49
	v_pk_mul_f32 v[48:49], v[130:131], v[60:61]
	v_pk_mul_f32 v[174:175], v[174:175], v[196:197]
	v_add_f32_e32 v60, v49, v48
	v_pk_mul_f32 v[48:49], v[88:89], v[62:63] op_sel:[1,0] op_sel_hi:[0,1]
	v_sub_f32_e32 v61, v48, v49
	v_pk_mul_f32 v[48:49], v[88:89], v[62:63]
	v_pk_mul_f32 v[90:91], v[90:91], v[200:201]
	v_add_f32_e32 v62, v49, v48
	v_pk_mul_f32 v[48:49], v[174:175], v[52:53] op_sel:[1,0] op_sel_hi:[0,1]
	v_sub_f32_e32 v63, v48, v49
	v_pk_mul_f32 v[48:49], v[174:175], v[52:53]
	v_pk_mul_f32 v[80:81], v[80:81], v[192:193]
	v_add_f32_e32 v52, v49, v48
	v_pk_mul_f32 v[48:49], v[90:91], v[54:55] op_sel:[1,0] op_sel_hi:[0,1]
	v_sub_f32_e32 v53, v48, v49
	v_pk_mul_f32 v[48:49], v[90:91], v[54:55]
	v_pk_mul_f32 v[166:167], v[170:171], v[166:167]
	v_add_f32_e32 v54, v49, v48
	v_pk_mul_f32 v[48:49], v[172:173], v[40:41] op_sel:[1,0] op_sel_hi:[0,1]
	v_pk_mul_f32 v[40:41], v[172:173], v[40:41]
	v_sub_f32_e32 v48, v48, v49
	v_add_f32_e32 v49, v41, v40
	v_pk_mul_f32 v[40:41], v[80:81], v[42:43] op_sel:[1,0] op_sel_hi:[0,1]
	v_sub_f32_e32 v55, v40, v41
	v_pk_mul_f32 v[40:41], v[80:81], v[42:43]
	v_pk_mul_f32 v[82:83], v[82:83], v[168:169]
	v_add_f32_e32 v42, v41, v40
	v_pk_mul_f32 v[40:41], v[166:167], v[28:29] op_sel:[1,0] op_sel_hi:[0,1]
	v_pk_mul_f32 v[28:29], v[166:167], v[28:29]
	v_sub_f32_e32 v40, v40, v41
	v_add_f32_e32 v41, v29, v28
	v_pk_mul_f32 v[28:29], v[82:83], v[30:31] op_sel:[1,0] op_sel_hi:[0,1]
	v_pk_mul_f32 v[160:161], v[164:165], v[160:161]
	v_sub_f32_e32 v43, v28, v29
	v_pk_mul_f32 v[28:29], v[82:83], v[30:31]
	v_pk_mul_f32 v[44:45], v[44:45], v[162:163]
	v_add_f32_e32 v30, v29, v28
	s_waitcnt vmcnt(0)
	v_pk_mul_f32 v[28:29], v[160:161], v[36:37] op_sel:[1,0] op_sel_hi:[0,1]
	v_sub_f32_e32 v31, v28, v29
	v_pk_mul_f32 v[28:29], v[160:161], v[36:37]
	v_pk_mul_f32 v[150:151], v[150:151], v[154:155]
	v_add_f32_e32 v36, v29, v28
	v_pk_mul_f32 v[28:29], v[44:45], v[38:39] op_sel:[1,0] op_sel_hi:[0,1]
	v_sub_f32_e32 v37, v28, v29
	v_pk_mul_f32 v[28:29], v[44:45], v[38:39]
	v_pk_mul_f32 v[46:47], v[46:47], v[156:157]
	v_add_f32_e32 v38, v29, v28
	v_pk_mul_f32 v[28:29], v[150:151], v[24:25] op_sel:[1,0] op_sel_hi:[0,1]
	v_pk_mul_f32 v[24:25], v[150:151], v[24:25]
	v_sub_f32_e32 v28, v28, v29
	v_add_f32_e32 v29, v25, v24
	v_pk_mul_f32 v[24:25], v[46:47], v[26:27] op_sel:[1,0] op_sel_hi:[0,1]
	v_pk_mul_f32 v[148:149], v[152:153], v[148:149]
	v_sub_f32_e32 v39, v24, v25
	v_pk_mul_f32 v[24:25], v[46:47], v[26:27]
	v_pk_mul_f32 v[140:141], v[146:147], v[140:141]
	v_add_f32_e32 v26, v25, v24
	v_pk_mul_f32 v[24:25], v[148:149], v[20:21] op_sel:[1,0] op_sel_hi:[0,1]
	v_pk_mul_f32 v[20:21], v[148:149], v[20:21]
	v_sub_f32_e32 v24, v24, v25
	v_add_f32_e32 v25, v21, v20
	v_pk_mul_f32 v[20:21], v[32:33], v[22:23] op_sel:[1,0] op_sel_hi:[0,1]
	v_sub_f32_e32 v27, v20, v21
	v_pk_mul_f32 v[20:21], v[32:33], v[22:23]
	v_pk_mul_f32 v[34:35], v[34:35], v[142:143]
	v_add_f32_e32 v22, v21, v20
	v_pk_mul_f32 v[20:21], v[140:141], v[16:17] op_sel:[1,0] op_sel_hi:[0,1]
	v_pk_mul_f32 v[16:17], v[140:141], v[16:17]
	v_sub_f32_e32 v20, v20, v21
	v_add_f32_e32 v21, v17, v16
	v_pk_mul_f32 v[16:17], v[34:35], v[18:19] op_sel:[1,0] op_sel_hi:[0,1]
	v_sub_f32_e32 v23, v16, v17
	v_pk_mul_f32 v[16:17], v[34:35], v[18:19]
	v_add_u32_e32 v200, 0, v231
	v_add_u32_e32 v201, 0, v191
	v_add_f32_e32 v16, v17, v16
	v_cvt_pk_bf16_f32 v124, v112, v114
	v_cvt_pk_bf16_f32 v125, v92, v95
	v_cvt_pk_bf16_f32 v126, v84, v87
	v_cvt_pk_bf16_f32 v127, v76, v79
	v_cvt_pk_bf16_f32 v120, v71, v73
	v_cvt_pk_bf16_f32 v121, v68, v75
	v_cvt_pk_bf16_f32 v122, v64, v67
	v_cvt_pk_bf16_f32 v123, v56, v59
	v_cvt_pk_bf16_f32 v116, v113, v94
	v_cvt_pk_bf16_f32 v117, v93, v86
	v_cvt_pk_bf16_f32 v118, v85, v78
	v_cvt_pk_bf16_f32 v119, v77, v70
	v_cvt_pk_bf16_f32 v112, v72, v74
	v_cvt_pk_bf16_f32 v113, v69, v66
	v_cvt_pk_bf16_f32 v114, v65, v58
	v_cvt_pk_bf16_f32 v115, v57, v50
	v_cvt_pk_bf16_f32 v108, v51, v61
	v_cvt_pk_bf16_f32 v109, v63, v53
	v_cvt_pk_bf16_f32 v110, v48, v55
	v_cvt_pk_bf16_f32 v111, v40, v43
	v_cvt_pk_bf16_f32 v104, v31, v37
	v_cvt_pk_bf16_f32 v105, v28, v39
	v_cvt_pk_bf16_f32 v106, v24, v27
	v_cvt_pk_bf16_f32 v107, v20, v23
	v_cvt_pk_bf16_f32 v100, v60, v62
	v_cvt_pk_bf16_f32 v101, v52, v54
	v_cvt_pk_bf16_f32 v102, v49, v42
	v_cvt_pk_bf16_f32 v103, v41, v30
	v_cvt_pk_bf16_f32 v96, v36, v38
	v_cvt_pk_bf16_f32 v97, v29, v26
	v_cvt_pk_bf16_f32 v98, v25, v22
	v_cvt_pk_bf16_f32 v99, v21, v16
	s_waitcnt vmcnt(0)
	ds_write_b128 v200, v[8:11]
	ds_write_b128 v201, v[4:7]
	v_lshlrev_b32_e32 v4, 8, v136
	v_and_b32_e32 v5, 0x70, v145
	v_bitop3_b32 v4, v188, v4, v5 bitop3:0xde
	v_add_u32_e32 v202, 0, v4
	v_lshlrev_b32_e32 v4, 8, v138
	v_bitop3_b32 v4, v188, v4, v5 bitop3:0xde
	v_add_u32_e32 v203, 0, v4
	v_lshlrev_b32_e32 v8, 8, v227
	v_and_b32_e32 v9, 0x70, v230
	ds_write_b128 v202, v[12:15] offset:32768
	ds_write_b128 v203, v[0:3] offset:32768
	v_bitop3_b32 v0, v190, v8, v9 bitop3:0xde
	v_add_u32_e32 v204, 0, v0
	s_waitcnt lgkmcnt(0)
	s_barrier
	ds_read_b128 v[0:3], v204 offset:32768
	ds_read_b128 v[4:7], v204 offset:40960
	s_waitcnt lgkmcnt(1)
	v_mfma_f32_32x32x16_bf16 v[32:47], v[0:3], v[124:127], 0
	v_or_b32_e32 v0, 32, v190
	v_bitop3_b32 v0, v0, v8, v9 bitop3:0xde
	v_add_u32_e32 v207, 0, v0
	v_and_b32_e32 v196, 63, v145
	v_lshlrev_b32_e32 v10, 3, v196
	v_and_b32_e32 v11, 0xc0, v230
	v_lshlrev_b64 v[64:65], 9, v[136:137]
	s_waitcnt lgkmcnt(0)
	v_mfma_f32_32x32x16_bf16 v[16:31], v[4:7], v[124:127], 0
	ds_read_b128 v[0:3], v207 offset:32768
	ds_read_b128 v[4:7], v207 offset:40960
	v_lshlrev_b64 v[66:67], 9, v[138:139]
	v_mov_b32_e32 v197, 0
	v_lshlrev_b64 v[192:193], 1, v[64:65]
	v_lshlrev_b64 v[194:195], 1, v[66:67]
	s_waitcnt lgkmcnt(1)
	v_mfma_f32_32x32x16_bf16 v[32:47], v[0:3], v[120:123], v[32:47]
	v_or_b32_e32 v0, 64, v190
	v_bitop3_b32 v0, v0, v8, v9 bitop3:0xde
	v_add_u32_e32 v209, 0, v0
	s_waitcnt lgkmcnt(0)
	v_mfma_f32_32x32x16_bf16 v[16:31], v[4:7], v[120:123], v[16:31]
	ds_read_b128 v[0:3], v209 offset:32768
	ds_read_b128 v[4:7], v209 offset:40960
	s_waitcnt lgkmcnt(1)
	v_mfma_f32_32x32x16_bf16 v[32:47], v[0:3], v[116:119], v[32:47]
	v_or_b32_e32 v0, 0x60, v190
	v_bitop3_b32 v0, v0, v8, v9 bitop3:0xde
	v_add_u32_e32 v205, 0, v0
	s_waitcnt lgkmcnt(0)
	v_mfma_f32_32x32x16_bf16 v[16:31], v[4:7], v[116:119], v[16:31]
	ds_read_b128 v[0:3], v205 offset:32768
	ds_read_b128 v[4:7], v205 offset:40960
	s_waitcnt lgkmcnt(1)
	v_mfma_f32_32x32x16_bf16 v[32:47], v[0:3], v[112:115], v[32:47]
	v_or_b32_e32 v0, 0x80, v190
	v_bitop3_b32 v0, v0, v8, v9 bitop3:0xde
	v_add_u32_e32 v206, 0, v0
	s_waitcnt lgkmcnt(0)
	v_mfma_f32_32x32x16_bf16 v[16:31], v[4:7], v[112:115], v[16:31]
	ds_read_b128 v[0:3], v206 offset:32768
	ds_read_b128 v[4:7], v206 offset:40960
	s_waitcnt lgkmcnt(1)
	v_mfma_f32_32x32x16_bf16 v[32:47], v[0:3], v[108:111], v[32:47]
	v_or_b32_e32 v0, 0xa0, v190
	v_bitop3_b32 v0, v0, v8, v9 bitop3:0xde
	v_add_u32_e32 v208, 0, v0
	s_waitcnt lgkmcnt(0)
	v_mfma_f32_32x32x16_bf16 v[16:31], v[4:7], v[108:111], v[16:31]
	ds_read_b128 v[0:3], v208 offset:32768
	ds_read_b128 v[4:7], v208 offset:40960
	s_waitcnt lgkmcnt(1)
	v_mfma_f32_32x32x16_bf16 v[32:47], v[0:3], v[104:107], v[32:47]
	v_or_b32_e32 v0, 0xc0, v190
	v_bitop3_b32 v0, v0, v8, v9 bitop3:0xde
	v_add_u32_e32 v210, 0, v0
	ds_read_b128 v[0:3], v210 offset:32768
	s_waitcnt lgkmcnt(1)
	v_mfma_f32_32x32x16_bf16 v[16:31], v[4:7], v[104:107], v[16:31]
	v_and_b32_e32 v4, 0x3fffffc0, v145
	v_lshl_add_u32 v191, v4, 2, s2
	ds_read_b128 v[4:7], v210 offset:40960
	s_waitcnt lgkmcnt(1)
	v_mfma_f32_32x32x16_bf16 v[32:47], v[0:3], v[100:103], v[32:47]
	v_or_b32_e32 v0, 0xe0, v190
	v_bitop3_b32 v0, v0, v8, v9 bitop3:0xde
	v_add_u32_e32 v211, 0, v0
	ds_read_b128 v[0:3], v211 offset:32768
	s_waitcnt lgkmcnt(1)
	v_mfma_f32_32x32x16_bf16 v[16:31], v[4:7], v[100:103], v[16:31]
	v_lshlrev_b32_e32 v5, 1, v145
	v_and_or_b32 v4, v10, 24, v11
	v_and_b32_e32 v5, 32, v5
	v_and_b32_e32 v6, 0x100, v10
	v_or3_b32 v69, v4, v5, v6
	ds_read_b128 v[4:7], v211 offset:40960
	v_add_u32_e32 v199, s4, v69
	s_waitcnt lgkmcnt(1)
	v_mfma_f32_32x32x16_bf16 v[32:47], v[0:3], v[96:99], v[32:47]
	s_waitcnt lgkmcnt(0)
	v_mfma_f32_32x32x16_bf16 v[16:31], v[4:7], v[96:99], v[16:31]
	s_nop 9
	v_max_f32_e32 v0, v33, v33
	v_max_f32_e32 v1, v32, v32
	v_max_f32_e32 v0, v1, v0
	v_max3_f32 v0, v0, v34, v35
	v_max3_f32 v0, v0, v36, v37
	v_max3_f32 v0, v0, v38, v39
	v_max3_f32 v0, v0, v40, v41
	v_max3_f32 v0, v0, v42, v43
	v_max3_f32 v0, v0, v44, v45
	v_max3_f32 v0, v0, v46, v47
	v_max3_f32 v0, v0, v16, v17
	v_max3_f32 v0, v0, v18, v19
	v_max3_f32 v0, v0, v20, v21
	v_max3_f32 v0, v0, v22, v23
	v_max3_f32 v0, v0, v24, v25
	v_max3_f32 v0, v0, v26, v27
	v_max3_f32 v0, v0, v28, v29
	v_max3_f32 v0, v0, v30, v31
	v_mov_b32_e32 v1, v0
	s_nop 1
	v_permlane32_swap_b32_e32 v0, v1
	v_max_f32_e32 v1, v1, v1
	v_max_f32_e32 v0, v0, v0
	v_max_f32_e32 v0, v0, v1
	v_add_f32_e32 v1, 0x7149f2ca, v0
	v_cmp_ge_f32_e32 vcc, s14, v1
	s_cmp_eq_u64 vcc, exec
	s_cselect_b64 vcc, -1, 0
	s_add_u32 s2, s20, 0x610000
	s_addc_u32 s3, s21, 0
	s_add_u32 s22, s20, 0xa10000
	s_addc_u32 s23, s21, 0
	v_max_f32_e32 v68, 0xf149f2ca, v0
	v_lshl_add_u64 v[0:1], s[22:23], 0, v[132:133]
	v_lshl_add_u64 v[2:3], s[22:23], 0, v[134:135]
	v_lshl_add_u64 v[0:1], v[0:1], 0, v[188:189]
	v_lshl_add_u64 v[2:3], v[2:3], 0, v[188:189]
	global_load_dwordx4 v[48:51], v[0:1], off
	global_load_dwordx4 v[52:55], v[2:3], off
	v_lshl_add_u64 v[0:1], s[2:3], 0, v[132:133]
	v_lshl_add_u64 v[2:3], s[2:3], 0, v[134:135]
	s_add_u32 s2, s20, 0x620000
	v_lshl_add_u64 v[0:1], v[0:1], 0, v[188:189]
	s_addc_u32 s3, s21, 0
	v_lshl_add_u64 v[2:3], v[2:3], 0, v[188:189]
	global_load_dwordx4 v[56:59], v[0:1], off
	global_load_dwordx4 v[60:63], v[2:3], off
	s_add_u32 s20, s20, 0xa20000
	v_lshl_add_u64 v[0:1], s[2:3], 0, v[134:135]
	s_addc_u32 s21, s21, 0
	v_lshl_add_u64 v[0:1], v[0:1], 0, v[188:189]
	v_lshl_add_u64 v[2:3], s[2:3], 0, v[132:133]
	v_lshl_add_u64 v[2:3], v[2:3], 0, v[188:189]
	global_load_dwordx4 v[140:143], v[0:1], off
	global_load_dwordx4 v[136:139], v[2:3], off
	v_lshl_add_u64 v[0:1], s[20:21], 0, v[134:135]
	v_lshl_add_u64 v[0:1], v[0:1], 0, v[188:189]
	v_lshl_add_u64 v[2:3], s[20:21], 0, v[132:133]
	v_lshl_add_u64 v[2:3], v[2:3], 0, v[188:189]
	global_load_dwordx4 v[132:135], v[0:1], off
	global_load_dwordx4 v[128:131], v[2:3], off
	v_sub_f32_e32 v0, 0xf149f2ca, v68
	v_mul_f32_e32 v0, 0x3e0293ee, v0
	v_exp_f32_e32 v70, v0
	v_cndmask_b32_e32 v168, v68, v246, vcc
	v_mul_f32_e32 v68, 0xbe0293ee, v168
	v_fmamk_f32 v32, v32, 0x3e0293ee, v68
	v_cndmask_b32_e64 v212, v70, 1.0, vcc
	v_mov_b32_e32 v70, v68
	v_fmamk_f32 v33, v33, 0x3e0293ee, v68
	v_fmamk_f32 v34, v34, 0x3e0293ee, v68
	v_fmamk_f32 v35, v35, 0x3e0293ee, v68
	v_fmamk_f32 v36, v36, 0x3e0293ee, v68
	v_fmamk_f32 v37, v37, 0x3e0293ee, v68
	v_fmamk_f32 v38, v38, 0x3e0293ee, v68
	v_fmamk_f32 v39, v39, 0x3e0293ee, v68
	v_fmamk_f32 v40, v40, 0x3e0293ee, v68
	v_fmamk_f32 v41, v41, 0x3e0293ee, v68
	v_fmamk_f32 v42, v42, 0x3e0293ee, v68
	v_fmamk_f32 v43, v43, 0x3e0293ee, v68
	v_fmamk_f32 v44, v44, 0x3e0293ee, v68
	v_fmamk_f32 v45, v45, 0x3e0293ee, v68
	v_fmamk_f32 v46, v46, 0x3e0293ee, v68
	v_fmac_f32_e32 v70, 0x3e0293ee, v47
	s_mov_b32 s20, s17
	s_mov_b32 s21, s17
	s_mov_b32 s22, s17
	s_mov_b32 s23, s17
	v_mov_b64_e32 v[0:1], s[16:17]
	v_exp_f32_e32 v216, v32
	v_exp_f32_e32 v230, v33
	v_exp_f32_e32 v174, v34
	v_exp_f32_e32 v219, v35
	v_exp_f32_e32 v173, v36
	v_exp_f32_e32 v175, v37
	v_exp_f32_e32 v163, v38
	v_exp_f32_e32 v172, v39
	v_exp_f32_e32 v164, v40
	v_exp_f32_e32 v171, v41
	v_exp_f32_e32 v165, v42
	v_exp_f32_e32 v170, v43
	v_exp_f32_e32 v166, v44
	v_exp_f32_e32 v169, v45
	v_exp_f32_e32 v145, v46
	v_exp_f32_e32 v167, v70
	v_mov_b64_e32 v[14:15], s[30:31]
	s_waitcnt vmcnt(4)
	v_mov_b64_e32 v[2:3], s[18:19]
	v_mov_b64_e32 v[4:5], s[20:21]
	v_mov_b64_e32 v[6:7], s[22:23]
	v_mov_b64_e32 v[8:9], s[24:25]
	v_mov_b64_e32 v[10:11], s[26:27]
	v_mov_b64_e32 v[12:13], s[28:29]
	v_pk_fma_f32 v[152:153], v[30:31], s[88:89], v[68:69] op_sel_hi:[1,0,0]
	v_pk_fma_f32 v[154:155], v[28:29], s[88:89], v[68:69] op_sel_hi:[1,0,0]
	v_pk_fma_f32 v[160:161], v[26:27], s[88:89], v[68:69] op_sel_hi:[1,0,0]
	v_pk_fma_f32 v[146:147], v[24:25], s[88:89], v[68:69] op_sel_hi:[1,0,0]
	v_pk_fma_f32 v[148:149], v[22:23], s[88:89], v[68:69] op_sel_hi:[1,0,0]
	v_pk_fma_f32 v[150:151], v[20:21], s[88:89], v[68:69] op_sel_hi:[1,0,0]
	v_pk_fma_f32 v[156:157], v[18:19], s[88:89], v[68:69] op_sel_hi:[1,0,0]
	v_pk_fma_f32 v[158:159], v[16:17], s[88:89], v[68:69] op_sel_hi:[1,0,0]
	s_waitcnt vmcnt(7)
	ds_write_b128 v200, v[48:51] offset:16384
	s_waitcnt vmcnt(6)
	ds_write_b128 v201, v[52:55] offset:16384
	s_waitcnt vmcnt(5)
	ds_write_b128 v202, v[56:59] offset:49152
	s_waitcnt vmcnt(4)
	ds_write_b128 v203, v[60:63] offset:49152
	s_addk_i32 s4, 0x4000
	v_mov_b64_e32 v[62:63], v[14:15]
	v_mov_b64_e32 v[46:47], v[14:15]
	v_mov_b64_e32 v[30:31], v[14:15]
	v_cmp_gt_u32_e64 s[2:3], 32, v196
	v_lshl_add_u32 v189, v227, 2, v191
	v_add_u32_e32 v198, s4, v69
	v_mov_b64_e32 v[60:61], v[12:13]
	v_mov_b64_e32 v[58:59], v[10:11]
	v_mov_b64_e32 v[56:57], v[8:9]
	v_mov_b64_e32 v[54:55], v[6:7]
	v_mov_b64_e32 v[52:53], v[4:5]
	v_mov_b64_e32 v[50:51], v[2:3]
	v_mov_b64_e32 v[48:49], v[0:1]
	v_mov_b64_e32 v[44:45], v[12:13]
	v_mov_b64_e32 v[42:43], v[10:11]
	v_mov_b64_e32 v[40:41], v[8:9]
	v_mov_b64_e32 v[38:39], v[6:7]
	v_mov_b64_e32 v[36:37], v[4:5]
	v_mov_b64_e32 v[34:35], v[2:3]
	v_mov_b64_e32 v[32:33], v[0:1]
	v_mov_b64_e32 v[28:29], v[12:13]
	v_mov_b64_e32 v[26:27], v[10:11]
	v_mov_b64_e32 v[24:25], v[8:9]
	v_mov_b64_e32 v[22:23], v[6:7]
	v_mov_b64_e32 v[20:21], v[4:5]
	v_mov_b64_e32 v[18:19], v[2:3]
	v_mov_b64_e32 v[16:17], v[0:1]
	s_waitcnt lgkmcnt(0)
	s_barrier
	v_add_u32_e32 v222, v192, v176
	v_add_u32_e32 v243, v194, v176

.LBB0_737:
	s_or_b64 exec, exec, s[6:7]
	s_lshl_b32 s2, s8, 1
	s_add_u32 s4, s25, s2
	s_addc_u32 s5, s26, 0
	v_lshrrev_b32_e32 v112, 4, v166
	v_lshl_add_u64 v[64:65], s[4:5], 0, v[176:177]
	v_or_b32_e32 v110, v112, v165
	v_lshl_add_u64 v[64:65], v[64:65], 0, s[66:67]
	s_waitcnt lgkmcnt(0)
	v_mad_i64_i32 v[66:67], s[4:5], v110, s45, v[64:65]
	v_or_b32_e32 v108, 4, v110
	v_or_b32_e32 v106, 8, v110
	v_mad_i64_i32 v[68:69], s[4:5], v108, s45, v[64:65]
	global_load_dwordx4 v[92:95], v[66:67], off nt
	global_load_dwordx4 v[88:91], v[68:69], off nt
	v_mad_i64_i32 v[66:67], s[4:5], v106, s45, v[64:65]
	v_or_b32_e32 v104, 12, v110
	v_or_b32_e32 v102, 16, v110
	v_mad_i64_i32 v[68:69], s[4:5], v104, s45, v[64:65]
	global_load_dwordx4 v[84:87], v[66:67], off nt
	global_load_dwordx4 v[80:83], v[68:69], off nt
	v_mad_i64_i32 v[66:67], s[4:5], v102, s45, v[64:65]
	v_or_b32_e32 v100, 20, v110
	v_lshl_add_u32 v99, v162, 4, v161
	v_mad_i64_i32 v[68:69], s[4:5], v100, s45, v[64:65]
	global_load_dwordx4 v[76:79], v[66:67], off nt
	global_load_dwordx4 v[72:75], v[68:69], off nt
	ds_read_b32 v101, v99
	s_movk_i32 s3, 0x2200
	v_mul_lo_u32 v97, v164, s3
	v_or_b32_e32 v98, 24, v110
	v_or_b32_e32 v96, 28, v110
	s_waitcnt lgkmcnt(0)
	v_rcp_f32_e32 v101, v101
	v_add_u32_e32 v97, s33, v97
	v_mad_i64_i32 v[66:67], s[4:5], v98, s45, v[64:65]
	v_mad_i64_i32 v[64:65], s[4:5], v96, s45, v[64:65]
	v_lshl_add_u32 v103, v163, 1, v97
	s_movk_i32 s3, 0x440
	v_mul_f32_e32 v0, v0, v101
	global_load_dwordx4 v[68:71], v[66:67], off nt
	s_nop 0
	global_load_dwordx4 v[64:67], v[64:65], off nt
	v_mad_u32_u24 v105, v162, s3, v103
	v_cvt_pk_bf16_f32 v0, v0, v177
	ds_write_b16 v105, v0
	v_mul_f32_e32 v0, v16, v101
	v_cvt_pk_bf16_f32 v0, v0, v177
	ds_write_b16 v105, v0 offset:64
	v_mul_f32_e32 v0, v32, v101
	v_cvt_pk_bf16_f32 v0, v0, v177
	ds_write_b16 v105, v0 offset:128
	v_mul_f32_e32 v0, v48, v101
	v_cvt_pk_bf16_f32 v0, v0, v177
	ds_read_b32 v16, v99 offset:4
	ds_write_b16 v105, v0 offset:192
	v_lshl_or_b32 v0, v162, 2, 1
	s_movk_i32 s3, 0x110
	v_mad_u32_u24 v0, v0, s3, v103
	s_waitcnt lgkmcnt(1)
	v_rcp_f32_e32 v16, v16
	s_lshl_b64 s[4:5], s[20:21], 21
	s_add_u32 s3, s18, s4
	s_addc_u32 s4, s19, s5
	v_mul_f32_e32 v1, v1, v16
	v_cvt_pk_bf16_f32 v1, v1, v177
	ds_write_b16 v0, v1
	v_mul_f32_e32 v1, v17, v16
	v_cvt_pk_bf16_f32 v1, v1, v177
	ds_write_b16 v0, v1 offset:64
	v_mul_f32_e32 v1, v33, v16
	v_cvt_pk_bf16_f32 v1, v1, v177
	ds_write_b16 v0, v1 offset:128
	v_mul_f32_e32 v1, v49, v16
	v_cvt_pk_bf16_f32 v1, v1, v177
	ds_read_b32 v16, v99 offset:8
	ds_write_b16 v0, v1 offset:192
	s_add_u32 s2, s3, s2
	s_addc_u32 s3, s4, 0
	v_ashrrev_i32_e32 v111, 31, v110
	s_waitcnt lgkmcnt(1)
	v_rcp_f32_e32 v16, v16
	v_ashrrev_i32_e32 v109, 31, v108
	v_ashrrev_i32_e32 v107, 31, v106
	v_ashrrev_i32_e32 v105, 31, v104
	v_mul_f32_e32 v1, v2, v16
	v_cvt_pk_bf16_f32 v1, v1, v177
	ds_write_b16 v0, v1 offset:272
	v_mul_f32_e32 v1, v18, v16
	v_cvt_pk_bf16_f32 v1, v1, v177
	ds_write_b16 v0, v1 offset:336
	v_mul_f32_e32 v1, v34, v16
	v_cvt_pk_bf16_f32 v1, v1, v177
	ds_write_b16 v0, v1 offset:400
	v_mul_f32_e32 v1, v50, v16
	v_cvt_pk_bf16_f32 v1, v1, v177
	ds_read_b32 v2, v99 offset:12
	ds_write_b16 v0, v1 offset:464
	v_ashrrev_i32_e32 v103, 31, v102
	v_ashrrev_i32_e32 v101, 31, v100
	s_add_i32 s24, s24, s83
	s_waitcnt lgkmcnt(1)
	v_rcp_f32_e32 v2, v2
	s_nop 0
	v_mul_f32_e32 v1, v3, v2
	v_cvt_pk_bf16_f32 v1, v1, v177
	ds_write_b16 v0, v1 offset:544
	v_mul_f32_e32 v1, v19, v2
	v_cvt_pk_bf16_f32 v1, v1, v177
	ds_write_b16 v0, v1 offset:608
	v_mul_f32_e32 v1, v35, v2
	v_cvt_pk_bf16_f32 v1, v1, v177
	ds_write_b16 v0, v1 offset:672
	v_mul_f32_e32 v1, v51, v2
	v_cvt_pk_bf16_f32 v1, v1, v177
	ds_write_b16 v0, v1 offset:736
	ds_read_b32 v1, v99 offset:32
	s_waitcnt lgkmcnt(0)
	v_rcp_f32_e32 v1, v1
	s_nop 0
	v_mul_f32_e32 v2, v4, v1
	v_cvt_pk_bf16_f32 v2, v2, v177
	ds_write_b16 v0, v2 offset:1904
	v_mul_f32_e32 v2, v20, v1
	v_cvt_pk_bf16_f32 v2, v2, v177
	ds_write_b16 v0, v2 offset:1968
	v_mul_f32_e32 v2, v36, v1
	v_cvt_pk_bf16_f32 v2, v2, v177
	v_mul_f32_e32 v1, v52, v1
	ds_write_b16 v0, v2 offset:2032
	v_cvt_pk_bf16_f32 v1, v1, v177
	ds_read_b32 v2, v99 offset:36
	ds_write_b16 v0, v1 offset:2096
	s_waitcnt lgkmcnt(1)
	v_rcp_f32_e32 v2, v2
	s_nop 0
	v_mul_f32_e32 v1, v5, v2
	v_cvt_pk_bf16_f32 v1, v1, v177
	ds_write_b16 v0, v1 offset:2176
	v_mul_f32_e32 v1, v21, v2
	v_cvt_pk_bf16_f32 v1, v1, v177
	ds_write_b16 v0, v1 offset:2240
	v_mul_f32_e32 v1, v37, v2
	v_cvt_pk_bf16_f32 v1, v1, v177
	ds_write_b16 v0, v1 offset:2304
	v_mul_f32_e32 v1, v53, v2
	v_cvt_pk_bf16_f32 v1, v1, v177
	ds_read_b32 v2, v99 offset:40
	ds_write_b16 v0, v1 offset:2368
	s_waitcnt lgkmcnt(1)
	v_rcp_f32_e32 v2, v2
	s_nop 0
	v_mul_f32_e32 v1, v6, v2
	v_cvt_pk_bf16_f32 v1, v1, v177
	ds_write_b16 v0, v1 offset:2448
	v_mul_f32_e32 v1, v22, v2
	v_cvt_pk_bf16_f32 v1, v1, v177
	ds_write_b16 v0, v1 offset:2512
	v_mul_f32_e32 v1, v38, v2
	v_cvt_pk_bf16_f32 v1, v1, v177
	ds_write_b16 v0, v1 offset:2576
	v_mul_f32_e32 v1, v54, v2
	v_cvt_pk_bf16_f32 v1, v1, v177
	ds_read_b32 v2, v99 offset:44
	ds_write_b16 v0, v1 offset:2640
	s_waitcnt vmcnt(7)
	v_lshlrev_b32_e32 v6, 16, v92
	s_waitcnt lgkmcnt(1)
	v_rcp_f32_e32 v2, v2
	s_nop 0
	v_mul_f32_e32 v1, v7, v2
	v_cvt_pk_bf16_f32 v1, v1, v177
	ds_write_b16 v0, v1 offset:2720
	v_mul_f32_e32 v1, v23, v2
	v_cvt_pk_bf16_f32 v1, v1, v177
	ds_write_b16 v0, v1 offset:2784
	v_mul_f32_e32 v1, v39, v2
	v_cvt_pk_bf16_f32 v1, v1, v177
	ds_write_b16 v0, v1 offset:2848
	v_mul_f32_e32 v1, v55, v2
	v_cvt_pk_bf16_f32 v1, v1, v177
	ds_write_b16 v0, v1 offset:2912
	ds_read_b32 v1, v99 offset:64
	s_waitcnt lgkmcnt(0)
	v_rcp_f32_e32 v1, v1
	s_nop 0
	v_mul_f32_e32 v2, v8, v1
	v_cvt_pk_bf16_f32 v2, v2, v177
	ds_write_b16 v0, v2 offset:4080
	v_mul_f32_e32 v2, v24, v1
	v_cvt_pk_bf16_f32 v2, v2, v177
	ds_write_b16 v0, v2 offset:4144
	v_mul_f32_e32 v2, v40, v1
	v_cvt_pk_bf16_f32 v2, v2, v177
	v_mul_f32_e32 v1, v56, v1
	ds_write_b16 v0, v2 offset:4208
	v_cvt_pk_bf16_f32 v1, v1, v177
	ds_read_b32 v2, v99 offset:68
	ds_write_b16 v0, v1 offset:4272
	s_waitcnt lgkmcnt(1)
	v_rcp_f32_e32 v2, v2
	s_nop 0
	v_mul_f32_e32 v1, v9, v2
	v_cvt_pk_bf16_f32 v1, v1, v177
	ds_write_b16 v0, v1 offset:4352
	v_mul_f32_e32 v1, v25, v2
	v_cvt_pk_bf16_f32 v1, v1, v177
	ds_write_b16 v0, v1 offset:4416
	v_mul_f32_e32 v1, v41, v2
	v_cvt_pk_bf16_f32 v1, v1, v177
	ds_write_b16 v0, v1 offset:4480
	v_mul_f32_e32 v1, v57, v2
	v_cvt_pk_bf16_f32 v1, v1, v177
	ds_read_b32 v2, v99 offset:72
	ds_write_b16 v0, v1 offset:4544
	s_waitcnt lgkmcnt(1)
	v_rcp_f32_e32 v2, v2
	s_nop 0
	v_mul_f32_e32 v1, v10, v2
	v_cvt_pk_bf16_f32 v1, v1, v177
	ds_write_b16 v0, v1 offset:4624
	v_mul_f32_e32 v1, v26, v2
	v_cvt_pk_bf16_f32 v1, v1, v177
	ds_write_b16 v0, v1 offset:4688
	v_mul_f32_e32 v1, v42, v2
	v_cvt_pk_bf16_f32 v1, v1, v177
	ds_write_b16 v0, v1 offset:4752
	v_mul_f32_e32 v1, v58, v2
	v_cvt_pk_bf16_f32 v1, v1, v177
	ds_read_b32 v2, v99 offset:76
	ds_write_b16 v0, v1 offset:4816
	s_waitcnt lgkmcnt(1)
	v_rcp_f32_e32 v2, v2
	s_nop 0
	v_mul_f32_e32 v1, v11, v2
	v_cvt_pk_bf16_f32 v1, v1, v177
	ds_write_b16 v0, v1 offset:4896
	v_mul_f32_e32 v1, v27, v2
	v_cvt_pk_bf16_f32 v1, v1, v177
	ds_write_b16 v0, v1 offset:4960
	v_mul_f32_e32 v1, v43, v2
	v_cvt_pk_bf16_f32 v1, v1, v177
	ds_write_b16 v0, v1 offset:5024
	v_mul_f32_e32 v1, v59, v2
	v_cvt_pk_bf16_f32 v1, v1, v177
	ds_write_b16 v0, v1 offset:5088
	ds_read_b32 v1, v99 offset:96
	v_lshlrev_b64 v[10:11], 13, v[110:111]
	s_waitcnt lgkmcnt(0)
	v_rcp_f32_e32 v1, v1
	s_nop 0
	v_mul_f32_e32 v2, v12, v1
	v_cvt_pk_bf16_f32 v2, v2, v177
	ds_write_b16 v0, v2 offset:6256
	v_mul_f32_e32 v2, v28, v1
	v_cvt_pk_bf16_f32 v2, v2, v177
	ds_write_b16 v0, v2 offset:6320
	v_mul_f32_e32 v2, v44, v1
	v_cvt_pk_bf16_f32 v2, v2, v177
	v_mul_f32_e32 v1, v60, v1
	ds_write_b16 v0, v2 offset:6384
	v_cvt_pk_bf16_f32 v1, v1, v177
	ds_read_b32 v2, v99 offset:100
	ds_write_b16 v0, v1 offset:6448
	s_waitcnt lgkmcnt(1)
	v_rcp_f32_e32 v2, v2
	s_nop 0
	v_mul_f32_e32 v1, v13, v2
	v_cvt_pk_bf16_f32 v1, v1, v177
	ds_write_b16 v0, v1 offset:6528
	v_mul_f32_e32 v1, v29, v2
	v_cvt_pk_bf16_f32 v1, v1, v177
	ds_write_b16 v0, v1 offset:6592
	v_mul_f32_e32 v1, v45, v2
	v_cvt_pk_bf16_f32 v1, v1, v177
	ds_write_b16 v0, v1 offset:6656
	v_mul_f32_e32 v1, v61, v2
	v_cvt_pk_bf16_f32 v1, v1, v177
	ds_read_b32 v2, v99 offset:104
	ds_write_b16 v0, v1 offset:6720
	s_waitcnt lgkmcnt(1)
	v_rcp_f32_e32 v2, v2
	s_nop 0
	v_mul_f32_e32 v1, v14, v2
	v_cvt_pk_bf16_f32 v1, v1, v177
	ds_write_b16 v0, v1 offset:6800
	v_mul_f32_e32 v1, v30, v2
	v_cvt_pk_bf16_f32 v1, v1, v177
	ds_write_b16 v0, v1 offset:6864
	v_mul_f32_e32 v1, v46, v2
	v_cvt_pk_bf16_f32 v1, v1, v177
	ds_write_b16 v0, v1 offset:6928
	v_mul_f32_e32 v1, v62, v2
	v_cvt_pk_bf16_f32 v1, v1, v177
	ds_read_b32 v2, v99 offset:108
	ds_write_b16 v0, v1 offset:6992
	v_ashrrev_i32_e32 v99, 31, v98
	s_waitcnt lgkmcnt(1)
	v_rcp_f32_e32 v2, v2
	s_nop 0
	v_mul_f32_e32 v1, v15, v2
	v_cvt_pk_bf16_f32 v1, v1, v177
	ds_write_b16 v0, v1 offset:7072
	v_mul_f32_e32 v1, v31, v2
	v_cvt_pk_bf16_f32 v1, v1, v177
	ds_write_b16 v0, v1 offset:7136
	v_mul_f32_e32 v1, v47, v2
	v_cvt_pk_bf16_f32 v1, v1, v177
	ds_write_b16 v0, v1 offset:7200
	v_mul_f32_e32 v1, v63, v2
	v_cvt_pk_bf16_f32 v1, v1, v177
	ds_write_b16 v0, v1 offset:7264
	v_mul_u32_u24_e32 v0, 0x110, v112
	s_waitcnt lgkmcnt(0)
	v_add3_u32 v12, v97, v176, v0
	ds_read_b128 v[2:5], v12
	v_lshl_add_u64 v[0:1], s[2:3], 0, v[176:177]
	v_lshl_add_u64 v[0:1], v[0:1], 0, s[60:61]
	v_lshl_add_u64 v[10:11], v[0:1], 0, v[10:11]
	v_ashrrev_i32_e32 v97, 31, v96
	s_waitcnt lgkmcnt(0)
	v_lshlrev_b32_e32 v7, 16, v2
	v_mul_f32_e32 v6, v7, v6
	v_and_b32_e32 v2, 0xffff0000, v2
	v_and_b32_e32 v7, 0xffff0000, v92
	v_mul_f32_e32 v2, v2, v7
	v_cvt_pk_bf16_f32 v2, v6, v2
	v_lshlrev_b32_e32 v6, 16, v93
	v_lshlrev_b32_e32 v7, 16, v3
	v_mul_f32_e32 v6, v7, v6
	v_and_b32_e32 v3, 0xffff0000, v3
	v_and_b32_e32 v7, 0xffff0000, v93
	v_mul_f32_e32 v3, v3, v7
	v_cvt_pk_bf16_f32 v3, v6, v3
	v_lshlrev_b32_e32 v6, 16, v94
	v_lshlrev_b32_e32 v7, 16, v4
	v_mul_f32_e32 v6, v7, v6
	v_and_b32_e32 v4, 0xffff0000, v4
	v_and_b32_e32 v7, 0xffff0000, v94
	v_mul_f32_e32 v4, v4, v7
	v_cvt_pk_bf16_f32 v4, v6, v4
	v_lshlrev_b32_e32 v6, 16, v95
	v_lshlrev_b32_e32 v7, 16, v5
	v_mul_f32_e32 v6, v7, v6
	v_and_b32_e32 v5, 0xffff0000, v5
	v_and_b32_e32 v7, 0xffff0000, v95
	v_mul_f32_e32 v5, v5, v7
	v_cvt_pk_bf16_f32 v5, v6, v5
	ds_read_b128 v[6:9], v12 offset:1088
	global_store_dwordx4 v[10:11], v[2:5], off
	v_lshlrev_b64 v[10:11], 13, v[108:109]
	v_lshl_add_u64 v[10:11], v[0:1], 0, v[10:11]
	s_waitcnt vmcnt(7)
	v_lshlrev_b32_e32 v2, 16, v88
	s_waitcnt lgkmcnt(0)
	v_lshlrev_b32_e32 v3, 16, v6
	v_mul_f32_e32 v2, v3, v2
	v_and_b32_e32 v3, 0xffff0000, v6
	v_and_b32_e32 v4, 0xffff0000, v88
	v_mul_f32_e32 v3, v3, v4
	v_cvt_pk_bf16_f32 v2, v2, v3
	v_lshlrev_b32_e32 v3, 16, v89
	v_lshlrev_b32_e32 v4, 16, v7
	v_mul_f32_e32 v3, v4, v3
	v_and_b32_e32 v4, 0xffff0000, v7
	v_and_b32_e32 v5, 0xffff0000, v89
	v_mul_f32_e32 v4, v4, v5
	v_cvt_pk_bf16_f32 v3, v3, v4
	v_lshlrev_b32_e32 v4, 16, v90
	v_lshlrev_b32_e32 v5, 16, v8
	v_mul_f32_e32 v4, v5, v4
	v_and_b32_e32 v5, 0xffff0000, v8
	v_and_b32_e32 v6, 0xffff0000, v90
	v_mul_f32_e32 v5, v5, v6
	v_cvt_pk_bf16_f32 v4, v4, v5
	v_lshlrev_b32_e32 v5, 16, v91
	v_lshlrev_b32_e32 v6, 16, v9
	v_mul_f32_e32 v5, v6, v5
	v_and_b32_e32 v6, 0xffff0000, v9
	v_and_b32_e32 v7, 0xffff0000, v91
	v_mul_f32_e32 v6, v6, v7
	v_cvt_pk_bf16_f32 v5, v5, v6
	ds_read_b128 v[6:9], v12 offset:2176
	global_store_dwordx4 v[10:11], v[2:5], off
	v_lshlrev_b64 v[10:11], 13, v[106:107]
	v_lshl_add_u64 v[10:11], v[0:1], 0, v[10:11]
	s_waitcnt vmcnt(7)
	v_lshlrev_b32_e32 v2, 16, v84
	s_waitcnt lgkmcnt(0)
	v_lshlrev_b32_e32 v3, 16, v6
	v_mul_f32_e32 v2, v3, v2
	v_and_b32_e32 v3, 0xffff0000, v6
	v_and_b32_e32 v4, 0xffff0000, v84
	v_mul_f32_e32 v3, v3, v4
	v_cvt_pk_bf16_f32 v2, v2, v3
	v_lshlrev_b32_e32 v3, 16, v85
	v_lshlrev_b32_e32 v4, 16, v7
	v_mul_f32_e32 v3, v4, v3
	v_and_b32_e32 v4, 0xffff0000, v7
	v_and_b32_e32 v5, 0xffff0000, v85
	v_mul_f32_e32 v4, v4, v5
	v_cvt_pk_bf16_f32 v3, v3, v4
	v_lshlrev_b32_e32 v4, 16, v86
	v_lshlrev_b32_e32 v5, 16, v8
	v_mul_f32_e32 v4, v5, v4
	v_and_b32_e32 v5, 0xffff0000, v8
	v_and_b32_e32 v6, 0xffff0000, v86
	v_mul_f32_e32 v5, v5, v6
	v_cvt_pk_bf16_f32 v4, v4, v5
	v_lshlrev_b32_e32 v5, 16, v87
	v_lshlrev_b32_e32 v6, 16, v9
	v_mul_f32_e32 v5, v6, v5
	v_and_b32_e32 v6, 0xffff0000, v9
	v_and_b32_e32 v7, 0xffff0000, v87
	v_mul_f32_e32 v6, v6, v7
	v_cvt_pk_bf16_f32 v5, v5, v6
	ds_read_b128 v[6:9], v12 offset:3264
	global_store_dwordx4 v[10:11], v[2:5], off
	v_lshlrev_b64 v[10:11], 13, v[104:105]
	v_lshl_add_u64 v[10:11], v[0:1], 0, v[10:11]
	s_waitcnt vmcnt(7)
	v_lshlrev_b32_e32 v2, 16, v80
	s_waitcnt lgkmcnt(0)
	v_lshlrev_b32_e32 v3, 16, v6
	v_mul_f32_e32 v2, v3, v2
	v_and_b32_e32 v3, 0xffff0000, v6
	v_and_b32_e32 v4, 0xffff0000, v80
	v_mul_f32_e32 v3, v3, v4
	v_cvt_pk_bf16_f32 v2, v2, v3
	v_lshlrev_b32_e32 v3, 16, v81
	v_lshlrev_b32_e32 v4, 16, v7
	v_mul_f32_e32 v3, v4, v3
	v_and_b32_e32 v4, 0xffff0000, v7
	v_and_b32_e32 v5, 0xffff0000, v81
	v_mul_f32_e32 v4, v4, v5
	v_cvt_pk_bf16_f32 v3, v3, v4
	v_lshlrev_b32_e32 v4, 16, v82
	v_lshlrev_b32_e32 v5, 16, v8
	v_mul_f32_e32 v4, v5, v4
	v_and_b32_e32 v5, 0xffff0000, v8
	v_and_b32_e32 v6, 0xffff0000, v82
	v_mul_f32_e32 v5, v5, v6
	v_cvt_pk_bf16_f32 v4, v4, v5
	v_lshlrev_b32_e32 v5, 16, v83
	v_lshlrev_b32_e32 v6, 16, v9
	v_mul_f32_e32 v5, v6, v5
	v_and_b32_e32 v6, 0xffff0000, v9
	v_and_b32_e32 v7, 0xffff0000, v83
	v_mul_f32_e32 v6, v6, v7
	v_cvt_pk_bf16_f32 v5, v5, v6
	ds_read_b128 v[6:9], v12 offset:4352
	global_store_dwordx4 v[10:11], v[2:5], off
	v_lshlrev_b64 v[10:11], 13, v[102:103]
	v_lshl_add_u64 v[10:11], v[0:1], 0, v[10:11]
	s_waitcnt vmcnt(7)
	v_lshlrev_b32_e32 v2, 16, v76
	s_waitcnt lgkmcnt(0)
	v_lshlrev_b32_e32 v3, 16, v6
	v_mul_f32_e32 v2, v3, v2
	v_and_b32_e32 v3, 0xffff0000, v6
	v_and_b32_e32 v4, 0xffff0000, v76
	v_mul_f32_e32 v3, v3, v4
	v_cvt_pk_bf16_f32 v2, v2, v3
	v_lshlrev_b32_e32 v3, 16, v77
	v_lshlrev_b32_e32 v4, 16, v7
	v_mul_f32_e32 v3, v4, v3
	v_and_b32_e32 v4, 0xffff0000, v7
	v_and_b32_e32 v5, 0xffff0000, v77
	v_mul_f32_e32 v4, v4, v5
	v_cvt_pk_bf16_f32 v3, v3, v4
	v_lshlrev_b32_e32 v4, 16, v78
	v_lshlrev_b32_e32 v5, 16, v8
	v_mul_f32_e32 v4, v5, v4
	v_and_b32_e32 v5, 0xffff0000, v8
	v_and_b32_e32 v6, 0xffff0000, v78
	v_mul_f32_e32 v5, v5, v6
	v_cvt_pk_bf16_f32 v4, v4, v5
	v_lshlrev_b32_e32 v5, 16, v79
	v_lshlrev_b32_e32 v6, 16, v9
	v_mul_f32_e32 v5, v6, v5
	v_and_b32_e32 v6, 0xffff0000, v9
	v_and_b32_e32 v7, 0xffff0000, v79
	v_mul_f32_e32 v6, v6, v7
	v_cvt_pk_bf16_f32 v5, v5, v6
	ds_read_b128 v[6:9], v12 offset:5440
	global_store_dwordx4 v[10:11], v[2:5], off
	v_lshlrev_b64 v[10:11], 13, v[100:101]
	v_lshl_add_u64 v[10:11], v[0:1], 0, v[10:11]
	s_waitcnt vmcnt(7)
	v_lshlrev_b32_e32 v2, 16, v72
	s_waitcnt lgkmcnt(0)
	v_lshlrev_b32_e32 v3, 16, v6
	v_mul_f32_e32 v2, v3, v2
	v_and_b32_e32 v3, 0xffff0000, v6
	v_and_b32_e32 v4, 0xffff0000, v72
	v_mul_f32_e32 v3, v3, v4
	v_cvt_pk_bf16_f32 v2, v2, v3
	v_lshlrev_b32_e32 v3, 16, v73
	v_lshlrev_b32_e32 v4, 16, v7
	v_mul_f32_e32 v3, v4, v3
	v_and_b32_e32 v4, 0xffff0000, v7
	v_and_b32_e32 v5, 0xffff0000, v73
	v_mul_f32_e32 v4, v4, v5
	v_cvt_pk_bf16_f32 v3, v3, v4
	v_lshlrev_b32_e32 v4, 16, v74
	v_lshlrev_b32_e32 v5, 16, v8
	v_mul_f32_e32 v4, v5, v4
	v_and_b32_e32 v5, 0xffff0000, v8
	v_and_b32_e32 v6, 0xffff0000, v74
	v_mul_f32_e32 v5, v5, v6
	v_cvt_pk_bf16_f32 v4, v4, v5
	v_lshlrev_b32_e32 v5, 16, v75
	v_lshlrev_b32_e32 v6, 16, v9
	v_mul_f32_e32 v5, v6, v5
	v_and_b32_e32 v6, 0xffff0000, v9
	v_and_b32_e32 v7, 0xffff0000, v75
	v_mul_f32_e32 v6, v6, v7
	v_cvt_pk_bf16_f32 v5, v5, v6
	ds_read_b128 v[6:9], v12 offset:6528
	global_store_dwordx4 v[10:11], v[2:5], off
	v_lshlrev_b64 v[10:11], 13, v[98:99]
	v_lshl_add_u64 v[10:11], v[0:1], 0, v[10:11]
	s_waitcnt vmcnt(7)
	v_lshlrev_b32_e32 v2, 16, v68
	s_waitcnt lgkmcnt(0)
	v_lshlrev_b32_e32 v3, 16, v6
	v_mul_f32_e32 v2, v3, v2
	v_and_b32_e32 v3, 0xffff0000, v6
	v_and_b32_e32 v4, 0xffff0000, v68
	v_mul_f32_e32 v3, v3, v4
	v_cvt_pk_bf16_f32 v2, v2, v3
	v_lshlrev_b32_e32 v3, 16, v69
	v_lshlrev_b32_e32 v4, 16, v7
	v_mul_f32_e32 v3, v4, v3
	v_and_b32_e32 v4, 0xffff0000, v7
	v_and_b32_e32 v5, 0xffff0000, v69
	v_mul_f32_e32 v4, v4, v5
	v_cvt_pk_bf16_f32 v3, v3, v4
	v_lshlrev_b32_e32 v4, 16, v70
	v_lshlrev_b32_e32 v5, 16, v8
	v_mul_f32_e32 v4, v5, v4
	v_and_b32_e32 v5, 0xffff0000, v8
	v_and_b32_e32 v6, 0xffff0000, v70
	v_mul_f32_e32 v5, v5, v6
	v_cvt_pk_bf16_f32 v4, v4, v5
	v_lshlrev_b32_e32 v5, 16, v71
	v_lshlrev_b32_e32 v6, 16, v9
	v_mul_f32_e32 v5, v6, v5
	v_and_b32_e32 v6, 0xffff0000, v9
	v_and_b32_e32 v7, 0xffff0000, v71
	v_mul_f32_e32 v6, v6, v7
	v_cvt_pk_bf16_f32 v5, v5, v6
	ds_read_b128 v[6:9], v12 offset:7616
	global_store_dwordx4 v[10:11], v[2:5], off
	v_readlane_b32 s2, v255, 50
	s_add_i32 s16, s16, s2
	s_waitcnt vmcnt(7)
	v_lshlrev_b32_e32 v2, 16, v64
	s_waitcnt lgkmcnt(0)
	v_lshlrev_b32_e32 v3, 16, v6
	v_mul_f32_e32 v2, v3, v2
	v_and_b32_e32 v3, 0xffff0000, v6
	v_and_b32_e32 v4, 0xffff0000, v64
	v_mul_f32_e32 v3, v3, v4
	v_cvt_pk_bf16_f32 v2, v2, v3
	v_lshlrev_b32_e32 v3, 16, v65
	v_lshlrev_b32_e32 v4, 16, v7
	v_mul_f32_e32 v3, v4, v3
	v_and_b32_e32 v4, 0xffff0000, v7
	v_and_b32_e32 v5, 0xffff0000, v65
	v_mul_f32_e32 v4, v4, v5
	v_cvt_pk_bf16_f32 v3, v3, v4
	v_lshlrev_b32_e32 v4, 16, v66
	v_lshlrev_b32_e32 v5, 16, v8
	v_mul_f32_e32 v4, v5, v4
	v_and_b32_e32 v5, 0xffff0000, v8
	v_and_b32_e32 v6, 0xffff0000, v66
	v_mul_f32_e32 v5, v5, v6
	v_cvt_pk_bf16_f32 v4, v4, v5
	v_lshlrev_b32_e32 v5, 16, v67
	v_lshlrev_b32_e32 v6, 16, v9
	v_mul_f32_e32 v5, v6, v5
	v_and_b32_e32 v6, 0xffff0000, v9
	v_and_b32_e32 v7, 0xffff0000, v67
	v_mul_f32_e32 v6, v6, v7
	v_cvt_pk_bf16_f32 v5, v5, v6
	v_lshlrev_b64 v[6:7], 13, v[96:97]
	v_lshl_add_u64 v[0:1], v[0:1], 0, v[6:7]
	s_cmp_ge_i32 s24, s89
	global_store_dwordx4 v[0:1], v[2:5], off
	s_cbranch_scc1 .LBB0_728

.LBB0_850:
	v_mov_b32_e32 v138, v220
	s_lshl_b32 s27, s55, 8
	v_readfirstlane_b32 s26, v138
	s_ashr_i32 s28, s26, 2
	s_andn2_b32 s28, s28, 63
	s_lshr_b32 s26, s26, 1
	s_add_i32 s28, s28, s27
	s_lshl_b32 s27, s37, 8
	s_and_b32 s26, s26, 0x60
	v_and_or_b32 v142, v138, 15, s28
	s_or_b32 s26, s26, s27
	v_lshrrev_b32_e32 v138, 1, v138
	v_and_or_b32 v140, v138, 24, s26
	v_mov_b64_e32 v[144:145], s[8:9]
	v_mad_i64_i32 v[138:139], s[26:27], v142, s45, v[144:145]
	v_ashrrev_i32_e32 v141, 31, v140
	v_lshl_add_u64 v[152:153], v[138:139], 0, s[94:95]
	v_lshlrev_b64 v[138:139], 1, v[140:141]
	v_lshl_add_u64 v[148:149], v[152:153], 0, v[138:139]
	global_load_dwordx4 v[148:151], v[148:149], off nt
	v_or_b32_e32 v140, 0x80, v140
	v_ashrrev_i32_e32 v141, 31, v140
	v_lshlrev_b64 v[140:141], 1, v[140:141]
	v_lshl_add_u64 v[152:153], v[152:153], 0, v[140:141]
	s_andn2_b64 vcc, exec, s[2:3]
	s_mov_b64 s[2:3], -1
	s_waitcnt vmcnt(0)
	v_lshlrev_b32_e32 v143, 16, v148
	v_and_b32_e32 v148, 0xffff0000, v148
	v_lshlrev_b32_e32 v154, 16, v149
	v_and_b32_e32 v149, 0xffff0000, v149
	v_lshlrev_b32_e32 v156, 16, v151
	v_and_b32_e32 v151, 0xffff0000, v151
	v_lshlrev_b32_e32 v155, 16, v150
	v_and_b32_e32 v150, 0xffff0000, v150
	v_mul_f32_e32 v124, v124, v143
	v_mul_f32_e32 v125, v125, v148
	v_mul_f32_e32 v126, v126, v154
	v_mul_f32_e32 v127, v127, v149
	v_mul_f32_e32 v123, v123, v151
	v_mul_f32_e32 v143, v120, v155
	v_mul_f32_e32 v148, v121, v150
	v_mul_f32_e32 v149, v122, v156
	v_cvt_pk_bf16_f32 v120, v124, v125
	v_cvt_pk_bf16_f32 v121, v126, v127
	v_cvt_pk_bf16_f32 v122, v143, v148
	v_cvt_pk_bf16_f32 v123, v149, v123
	global_load_dwordx4 v[124:127], v[152:153], off nt
	v_ashrrev_i32_e32 v143, 31, v142
	v_lshlrev_b64 v[150:151], 13, v[142:143]
	v_lshl_add_u64 v[150:151], s[18:19], 0, v[150:151]
	v_or_b32_e32 v148, 16, v142
	v_lshl_add_u64 v[150:151], v[150:151], 0, s[66:67]
	v_mad_i64_i32 v[152:153], s[26:27], v148, s45, v[144:145]
	v_lshl_add_u64 v[156:157], v[150:151], 0, v[138:139]
	v_lshl_add_u64 v[152:153], v[152:153], 0, s[94:95]
	global_store_dwordx4 v[156:157], v[120:123], off
	v_lshl_add_u64 v[154:155], v[152:153], 0, v[138:139]
	v_ashrrev_i32_e32 v149, 31, v148
	s_waitcnt vmcnt(1)
	v_lshlrev_b32_e32 v120, 16, v124
	v_and_b32_e32 v121, 0xffff0000, v124
	v_lshlrev_b32_e32 v122, 16, v125
	v_and_b32_e32 v123, 0xffff0000, v125
	v_lshlrev_b32_e32 v124, 16, v126
	v_and_b32_e32 v125, 0xffff0000, v126
	v_lshlrev_b32_e32 v126, 16, v127
	v_and_b32_e32 v127, 0xffff0000, v127
	v_mul_f32_e32 v116, v116, v120
	v_mul_f32_e32 v117, v117, v121
	v_mul_f32_e32 v118, v118, v122
	v_mul_f32_e32 v119, v119, v123
	v_mul_f32_e32 v115, v115, v127
	v_mul_f32_e32 v120, v112, v124
	v_mul_f32_e32 v121, v113, v125
	v_mul_f32_e32 v122, v114, v126
	v_cvt_pk_bf16_f32 v112, v116, v117
	v_cvt_pk_bf16_f32 v113, v118, v119
	v_cvt_pk_bf16_f32 v114, v120, v121
	v_cvt_pk_bf16_f32 v115, v122, v115
	global_load_dwordx4 v[116:119], v[154:155], off nt
	v_lshl_add_u64 v[122:123], v[150:151], 0, v[140:141]
	global_store_dwordx4 v[122:123], v[112:115], off
	v_lshl_add_u64 v[120:121], v[152:153], 0, v[140:141]
	s_waitcnt vmcnt(1)
	v_lshlrev_b32_e32 v112, 16, v116
	v_and_b32_e32 v113, 0xffff0000, v116
	v_lshlrev_b32_e32 v114, 16, v117
	v_and_b32_e32 v115, 0xffff0000, v117
	v_lshlrev_b32_e32 v116, 16, v118
	v_and_b32_e32 v117, 0xffff0000, v118
	v_lshlrev_b32_e32 v118, 16, v119
	v_and_b32_e32 v119, 0xffff0000, v119
	v_mul_f32_e32 v108, v108, v112
	v_mul_f32_e32 v109, v109, v113
	v_mul_f32_e32 v110, v110, v114
	v_mul_f32_e32 v111, v111, v115
	v_mul_f32_e32 v107, v107, v119
	v_mul_f32_e32 v112, v104, v116
	v_mul_f32_e32 v113, v105, v117
	v_mul_f32_e32 v114, v106, v118
	v_cvt_pk_bf16_f32 v104, v108, v109
	v_cvt_pk_bf16_f32 v105, v110, v111
	v_cvt_pk_bf16_f32 v106, v112, v113
	v_cvt_pk_bf16_f32 v107, v114, v107
	global_load_dwordx4 v[108:111], v[120:121], off nt
	v_lshlrev_b64 v[116:117], 13, v[148:149]
	v_lshl_add_u64 v[116:117], s[18:19], 0, v[116:117]
	v_or_b32_e32 v112, 32, v142
	v_lshl_add_u64 v[116:117], v[116:117], 0, s[66:67]
	v_mad_i64_i32 v[114:115], s[26:27], v112, s45, v[144:145]
	v_lshl_add_u64 v[120:121], v[116:117], 0, v[138:139]
	v_lshl_add_u64 v[114:115], v[114:115], 0, s[94:95]
	global_store_dwordx4 v[120:121], v[104:107], off
	v_lshl_add_u64 v[118:119], v[114:115], 0, v[138:139]
	v_ashrrev_i32_e32 v113, 31, v112
	s_waitcnt vmcnt(1)
	v_lshlrev_b32_e32 v104, 16, v108
	v_and_b32_e32 v105, 0xffff0000, v108
	v_lshlrev_b32_e32 v106, 16, v109
	v_and_b32_e32 v107, 0xffff0000, v109
	v_lshlrev_b32_e32 v108, 16, v110
	v_and_b32_e32 v109, 0xffff0000, v110
	v_lshlrev_b32_e32 v110, 16, v111
	v_and_b32_e32 v111, 0xffff0000, v111
	v_mul_f32_e32 v100, v100, v104
	v_mul_f32_e32 v101, v101, v105
	v_mul_f32_e32 v102, v102, v106
	v_mul_f32_e32 v103, v103, v107
	v_mul_f32_e32 v99, v99, v111
	v_mul_f32_e32 v104, v96, v108
	v_mul_f32_e32 v105, v97, v109
	v_mul_f32_e32 v106, v98, v110
	v_cvt_pk_bf16_f32 v96, v100, v101
	v_cvt_pk_bf16_f32 v97, v102, v103
	v_cvt_pk_bf16_f32 v98, v104, v105
	v_cvt_pk_bf16_f32 v99, v106, v99
	global_load_dwordx4 v[100:103], v[118:119], off nt
	v_lshl_add_u64 v[106:107], v[116:117], 0, v[140:141]
	global_store_dwordx4 v[106:107], v[96:99], off
	v_lshl_add_u64 v[104:105], v[114:115], 0, v[140:141]
	s_waitcnt vmcnt(1)
	v_lshlrev_b32_e32 v96, 16, v100
	v_and_b32_e32 v97, 0xffff0000, v100
	v_lshlrev_b32_e32 v98, 16, v101
	v_and_b32_e32 v99, 0xffff0000, v101
	v_lshlrev_b32_e32 v100, 16, v102
	v_and_b32_e32 v101, 0xffff0000, v102
	v_lshlrev_b32_e32 v102, 16, v103
	v_and_b32_e32 v103, 0xffff0000, v103
	v_mul_f32_e32 v92, v92, v96
	v_mul_f32_e32 v93, v93, v97
	v_mul_f32_e32 v94, v94, v98
	v_mul_f32_e32 v95, v95, v99
	v_mul_f32_e32 v91, v91, v103
	v_mul_f32_e32 v96, v88, v100
	v_mul_f32_e32 v97, v89, v101
	v_mul_f32_e32 v98, v90, v102
	v_cvt_pk_bf16_f32 v88, v92, v93
	v_cvt_pk_bf16_f32 v89, v94, v95
	v_cvt_pk_bf16_f32 v90, v96, v97
	v_cvt_pk_bf16_f32 v91, v98, v91
	global_load_dwordx4 v[92:95], v[104:105], off nt
	v_lshlrev_b64 v[100:101], 13, v[112:113]
	v_lshl_add_u64 v[100:101], s[18:19], 0, v[100:101]
	v_or_b32_e32 v96, 48, v142
	v_lshl_add_u64 v[100:101], v[100:101], 0, s[66:67]
	v_mad_i64_i32 v[98:99], s[26:27], v96, s45, v[144:145]
	v_lshl_add_u64 v[104:105], v[100:101], 0, v[138:139]
	v_lshl_add_u64 v[98:99], v[98:99], 0, s[94:95]
	global_store_dwordx4 v[104:105], v[88:91], off
	v_lshl_add_u64 v[102:103], v[98:99], 0, v[138:139]
	v_ashrrev_i32_e32 v97, 31, v96
	s_waitcnt vmcnt(1)
	v_lshlrev_b32_e32 v88, 16, v92
	v_and_b32_e32 v89, 0xffff0000, v92
	v_lshlrev_b32_e32 v90, 16, v93
	v_and_b32_e32 v91, 0xffff0000, v93
	v_lshlrev_b32_e32 v92, 16, v94
	v_and_b32_e32 v93, 0xffff0000, v94
	v_lshlrev_b32_e32 v94, 16, v95
	v_and_b32_e32 v95, 0xffff0000, v95
	v_mul_f32_e32 v84, v84, v88
	v_mul_f32_e32 v85, v85, v89
	v_mul_f32_e32 v86, v86, v90
	v_mul_f32_e32 v87, v87, v91
	v_mul_f32_e32 v83, v83, v95
	v_mul_f32_e32 v88, v80, v92
	v_mul_f32_e32 v89, v81, v93
	v_mul_f32_e32 v90, v82, v94
	v_cvt_pk_bf16_f32 v80, v84, v85
	v_cvt_pk_bf16_f32 v81, v86, v87
	v_cvt_pk_bf16_f32 v82, v88, v89
	v_cvt_pk_bf16_f32 v83, v90, v83
	global_load_dwordx4 v[84:87], v[102:103], off nt
	v_lshl_add_u64 v[90:91], v[100:101], 0, v[140:141]
	global_store_dwordx4 v[90:91], v[80:83], off
	v_lshl_add_u64 v[88:89], v[98:99], 0, v[140:141]
	s_waitcnt vmcnt(1)
	v_lshlrev_b32_e32 v80, 16, v84
	v_and_b32_e32 v81, 0xffff0000, v84
	v_lshlrev_b32_e32 v82, 16, v85
	v_and_b32_e32 v83, 0xffff0000, v85
	v_lshlrev_b32_e32 v84, 16, v86
	v_and_b32_e32 v85, 0xffff0000, v86
	v_lshlrev_b32_e32 v86, 16, v87
	v_and_b32_e32 v87, 0xffff0000, v87
	v_mul_f32_e32 v76, v76, v80
	v_mul_f32_e32 v77, v77, v81
	v_mul_f32_e32 v78, v78, v82
	v_mul_f32_e32 v79, v79, v83
	v_mul_f32_e32 v75, v75, v87
	v_mul_f32_e32 v80, v72, v84
	v_mul_f32_e32 v81, v73, v85
	v_mul_f32_e32 v82, v74, v86
	v_cvt_pk_bf16_f32 v72, v76, v77
	v_cvt_pk_bf16_f32 v73, v78, v79
	v_cvt_pk_bf16_f32 v74, v80, v81
	v_cvt_pk_bf16_f32 v75, v82, v75
	global_load_dwordx4 v[76:79], v[88:89], off nt
	v_lshlrev_b64 v[84:85], 13, v[96:97]
	v_lshl_add_u64 v[84:85], s[18:19], 0, v[84:85]
	v_add_u32_e32 v80, 0x80, v142
	v_lshl_add_u64 v[84:85], v[84:85], 0, s[66:67]
	v_mad_i64_i32 v[82:83], s[26:27], v80, s45, v[144:145]
	v_lshl_add_u64 v[88:89], v[84:85], 0, v[138:139]
	v_lshl_add_u64 v[82:83], v[82:83], 0, s[94:95]
	global_store_dwordx4 v[88:89], v[72:75], off
	v_lshl_add_u64 v[86:87], v[82:83], 0, v[138:139]
	v_ashrrev_i32_e32 v81, 31, v80
	s_waitcnt vmcnt(1)
	v_lshlrev_b32_e32 v72, 16, v76
	v_and_b32_e32 v73, 0xffff0000, v76
	v_lshlrev_b32_e32 v74, 16, v77
	v_and_b32_e32 v75, 0xffff0000, v77
	v_lshlrev_b32_e32 v76, 16, v78
	v_and_b32_e32 v77, 0xffff0000, v78
	v_lshlrev_b32_e32 v78, 16, v79
	v_and_b32_e32 v79, 0xffff0000, v79
	v_mul_f32_e32 v68, v68, v72
	v_mul_f32_e32 v69, v69, v73
	v_mul_f32_e32 v70, v70, v74
	v_mul_f32_e32 v71, v71, v75
	v_mul_f32_e32 v67, v67, v79
	v_mul_f32_e32 v72, v64, v76
	v_mul_f32_e32 v73, v65, v77
	v_mul_f32_e32 v74, v66, v78
	v_cvt_pk_bf16_f32 v64, v68, v69
	v_cvt_pk_bf16_f32 v65, v70, v71
	v_cvt_pk_bf16_f32 v66, v72, v73
	v_cvt_pk_bf16_f32 v67, v74, v67
	global_load_dwordx4 v[68:71], v[86:87], off nt
	v_lshl_add_u64 v[74:75], v[84:85], 0, v[140:141]
	global_store_dwordx4 v[74:75], v[64:67], off
	v_lshl_add_u64 v[72:73], v[82:83], 0, v[140:141]
	s_waitcnt vmcnt(1)
	v_lshlrev_b32_e32 v64, 16, v68
	v_and_b32_e32 v65, 0xffff0000, v68
	v_lshlrev_b32_e32 v66, 16, v69
	v_and_b32_e32 v67, 0xffff0000, v69
	v_lshlrev_b32_e32 v68, 16, v70
	v_and_b32_e32 v69, 0xffff0000, v70
	v_lshlrev_b32_e32 v70, 16, v71
	v_and_b32_e32 v71, 0xffff0000, v71
	v_mul_f32_e32 v60, v60, v64
	v_mul_f32_e32 v61, v61, v65
	v_mul_f32_e32 v62, v62, v66
	v_mul_f32_e32 v63, v63, v67
	v_mul_f32_e32 v59, v59, v71
	v_mul_f32_e32 v64, v56, v68
	v_mul_f32_e32 v65, v57, v69
	v_mul_f32_e32 v66, v58, v70
	v_cvt_pk_bf16_f32 v56, v60, v61
	v_cvt_pk_bf16_f32 v57, v62, v63
	v_cvt_pk_bf16_f32 v58, v64, v65
	v_cvt_pk_bf16_f32 v59, v66, v59
	global_load_dwordx4 v[60:63], v[72:73], off nt
	v_lshlrev_b64 v[68:69], 13, v[80:81]
	v_lshl_add_u64 v[68:69], s[18:19], 0, v[68:69]
	v_add_u32_e32 v64, 0x90, v142
	v_lshl_add_u64 v[68:69], v[68:69], 0, s[66:67]
	v_mad_i64_i32 v[66:67], s[26:27], v64, s45, v[144:145]
	v_lshl_add_u64 v[72:73], v[68:69], 0, v[138:139]
	v_lshl_add_u64 v[66:67], v[66:67], 0, s[94:95]
	global_store_dwordx4 v[72:73], v[56:59], off
	v_lshl_add_u64 v[70:71], v[66:67], 0, v[138:139]
	v_ashrrev_i32_e32 v65, 31, v64
	s_waitcnt vmcnt(1)
	v_lshlrev_b32_e32 v56, 16, v60
	v_and_b32_e32 v57, 0xffff0000, v60
	v_lshlrev_b32_e32 v58, 16, v61
	v_and_b32_e32 v59, 0xffff0000, v61
	v_lshlrev_b32_e32 v60, 16, v62
	v_and_b32_e32 v61, 0xffff0000, v62
	v_lshlrev_b32_e32 v62, 16, v63
	v_and_b32_e32 v63, 0xffff0000, v63
	v_mul_f32_e32 v52, v52, v56
	v_mul_f32_e32 v53, v53, v57
	v_mul_f32_e32 v54, v54, v58
	v_mul_f32_e32 v55, v55, v59
	v_mul_f32_e32 v51, v51, v63
	v_mul_f32_e32 v56, v48, v60
	v_mul_f32_e32 v57, v49, v61
	v_mul_f32_e32 v58, v50, v62
	v_cvt_pk_bf16_f32 v48, v52, v53
	v_cvt_pk_bf16_f32 v49, v54, v55
	v_cvt_pk_bf16_f32 v50, v56, v57
	v_cvt_pk_bf16_f32 v51, v58, v51
	global_load_dwordx4 v[52:55], v[70:71], off nt
	v_lshl_add_u64 v[58:59], v[68:69], 0, v[140:141]
	global_store_dwordx4 v[58:59], v[48:51], off
	v_lshl_add_u64 v[56:57], v[66:67], 0, v[140:141]
	s_waitcnt vmcnt(1)
	v_lshlrev_b32_e32 v48, 16, v52
	v_and_b32_e32 v49, 0xffff0000, v52
	v_lshlrev_b32_e32 v50, 16, v53
	v_and_b32_e32 v51, 0xffff0000, v53
	v_lshlrev_b32_e32 v52, 16, v54
	v_and_b32_e32 v53, 0xffff0000, v54
	v_lshlrev_b32_e32 v54, 16, v55
	v_and_b32_e32 v55, 0xffff0000, v55
	v_mul_f32_e32 v44, v44, v48
	v_mul_f32_e32 v45, v45, v49
	v_mul_f32_e32 v46, v46, v50
	v_mul_f32_e32 v47, v47, v51
	v_mul_f32_e32 v43, v43, v55
	v_mul_f32_e32 v48, v40, v52
	v_mul_f32_e32 v49, v41, v53
	v_mul_f32_e32 v50, v42, v54
	v_cvt_pk_bf16_f32 v40, v44, v45
	v_cvt_pk_bf16_f32 v41, v46, v47
	v_cvt_pk_bf16_f32 v42, v48, v49
	v_cvt_pk_bf16_f32 v43, v50, v43
	global_load_dwordx4 v[44:47], v[56:57], off nt
	v_lshlrev_b64 v[52:53], 13, v[64:65]
	v_lshl_add_u64 v[52:53], s[18:19], 0, v[52:53]
	v_add_u32_e32 v48, 0xa0, v142
	v_lshl_add_u64 v[52:53], v[52:53], 0, s[66:67]
	v_mad_i64_i32 v[50:51], s[26:27], v48, s45, v[144:145]
	v_lshl_add_u64 v[56:57], v[52:53], 0, v[138:139]
	v_lshl_add_u64 v[50:51], v[50:51], 0, s[94:95]
	global_store_dwordx4 v[56:57], v[40:43], off
	v_lshl_add_u64 v[54:55], v[50:51], 0, v[138:139]
	v_ashrrev_i32_e32 v49, 31, v48
	s_waitcnt vmcnt(1)
	v_lshlrev_b32_e32 v40, 16, v44
	v_and_b32_e32 v41, 0xffff0000, v44
	v_lshlrev_b32_e32 v42, 16, v45
	v_and_b32_e32 v43, 0xffff0000, v45
	v_lshlrev_b32_e32 v44, 16, v46
	v_and_b32_e32 v45, 0xffff0000, v46
	v_lshlrev_b32_e32 v46, 16, v47
	v_and_b32_e32 v47, 0xffff0000, v47
	v_mul_f32_e32 v36, v36, v40
	v_mul_f32_e32 v37, v37, v41
	v_mul_f32_e32 v38, v38, v42
	v_mul_f32_e32 v39, v39, v43
	v_mul_f32_e32 v35, v35, v47
	v_mul_f32_e32 v40, v32, v44
	v_mul_f32_e32 v41, v33, v45
	v_mul_f32_e32 v42, v34, v46
	v_cvt_pk_bf16_f32 v32, v36, v37
	v_cvt_pk_bf16_f32 v33, v38, v39
	v_cvt_pk_bf16_f32 v34, v40, v41
	v_cvt_pk_bf16_f32 v35, v42, v35
	global_load_dwordx4 v[36:39], v[54:55], off nt
	v_lshl_add_u64 v[42:43], v[52:53], 0, v[140:141]
	global_store_dwordx4 v[42:43], v[32:35], off
	v_lshl_add_u64 v[40:41], v[50:51], 0, v[140:141]
	s_waitcnt vmcnt(1)
	v_lshlrev_b32_e32 v32, 16, v36
	v_and_b32_e32 v33, 0xffff0000, v36
	v_lshlrev_b32_e32 v34, 16, v37
	v_and_b32_e32 v35, 0xffff0000, v37
	v_lshlrev_b32_e32 v36, 16, v38
	v_and_b32_e32 v37, 0xffff0000, v38
	v_lshlrev_b32_e32 v38, 16, v39
	v_and_b32_e32 v39, 0xffff0000, v39
	v_mul_f32_e32 v28, v28, v32
	v_mul_f32_e32 v29, v29, v33
	v_mul_f32_e32 v30, v30, v34
	v_mul_f32_e32 v31, v31, v35
	v_mul_f32_e32 v27, v27, v39
	v_mul_f32_e32 v32, v24, v36
	v_mul_f32_e32 v33, v25, v37
	v_mul_f32_e32 v34, v26, v38
	v_cvt_pk_bf16_f32 v24, v28, v29
	v_cvt_pk_bf16_f32 v25, v30, v31
	v_cvt_pk_bf16_f32 v26, v32, v33
	v_cvt_pk_bf16_f32 v27, v34, v27
	global_load_dwordx4 v[28:31], v[40:41], off nt
	v_lshlrev_b64 v[36:37], 13, v[48:49]
	v_lshl_add_u64 v[36:37], s[18:19], 0, v[36:37]
	v_add_u32_e32 v32, 0xb0, v142
	v_lshl_add_u64 v[36:37], v[36:37], 0, s[66:67]
	v_mad_i64_i32 v[34:35], s[26:27], v32, s45, v[144:145]
	v_lshl_add_u64 v[40:41], v[36:37], 0, v[138:139]
	v_lshl_add_u64 v[34:35], v[34:35], 0, s[94:95]
	global_store_dwordx4 v[40:41], v[24:27], off
	v_lshl_add_u64 v[38:39], v[34:35], 0, v[138:139]
	v_ashrrev_i32_e32 v33, 31, v32
	s_waitcnt vmcnt(1)
	v_lshlrev_b32_e32 v24, 16, v28
	v_and_b32_e32 v25, 0xffff0000, v28
	v_lshlrev_b32_e32 v26, 16, v29
	v_and_b32_e32 v27, 0xffff0000, v29
	v_lshlrev_b32_e32 v28, 16, v30
	v_and_b32_e32 v29, 0xffff0000, v30
	v_lshlrev_b32_e32 v30, 16, v31
	v_and_b32_e32 v31, 0xffff0000, v31
	v_mul_f32_e32 v20, v20, v24
	v_mul_f32_e32 v21, v21, v25
	v_mul_f32_e32 v22, v22, v26
	v_mul_f32_e32 v23, v23, v27
	v_mul_f32_e32 v19, v19, v31
	v_mul_f32_e32 v24, v16, v28
	v_mul_f32_e32 v25, v17, v29
	v_mul_f32_e32 v26, v18, v30
	v_cvt_pk_bf16_f32 v16, v20, v21
	v_cvt_pk_bf16_f32 v17, v22, v23
	v_cvt_pk_bf16_f32 v18, v24, v25
	v_cvt_pk_bf16_f32 v19, v26, v19
	global_load_dwordx4 v[20:23], v[38:39], off nt
	v_lshl_add_u64 v[26:27], v[36:37], 0, v[140:141]
	global_store_dwordx4 v[26:27], v[16:19], off
	v_lshl_add_u64 v[24:25], v[34:35], 0, v[140:141]
	s_waitcnt vmcnt(1)
	v_lshlrev_b32_e32 v16, 16, v20
	v_and_b32_e32 v17, 0xffff0000, v20
	v_lshlrev_b32_e32 v18, 16, v21
	v_and_b32_e32 v19, 0xffff0000, v21
	v_lshlrev_b32_e32 v20, 16, v22
	v_and_b32_e32 v21, 0xffff0000, v22
	v_lshlrev_b32_e32 v22, 16, v23
	v_and_b32_e32 v23, 0xffff0000, v23
	v_mul_f32_e32 v12, v12, v16
	v_mul_f32_e32 v13, v13, v17
	v_mul_f32_e32 v14, v14, v18
	v_mul_f32_e32 v15, v15, v19
	v_mul_f32_e32 v11, v11, v23
	v_mul_f32_e32 v16, v8, v20
	v_mul_f32_e32 v17, v9, v21
	v_mul_f32_e32 v18, v10, v22
	v_cvt_pk_bf16_f32 v8, v12, v13
	v_cvt_pk_bf16_f32 v9, v14, v15
	v_cvt_pk_bf16_f32 v10, v16, v17
	v_cvt_pk_bf16_f32 v11, v18, v11
	global_load_dwordx4 v[12:15], v[24:25], off nt
	v_lshlrev_b64 v[16:17], 13, v[32:33]
	v_lshl_add_u64 v[16:17], s[18:19], 0, v[16:17]
	v_lshl_add_u64 v[16:17], v[16:17], 0, s[66:67]
	v_lshl_add_u64 v[18:19], v[16:17], 0, v[138:139]
	global_store_dwordx4 v[18:19], v[8:11], off
	v_lshl_add_u64 v[16:17], v[16:17], 0, v[140:141]
	s_waitcnt vmcnt(1)
	v_lshlrev_b32_e32 v8, 16, v12
	v_and_b32_e32 v9, 0xffff0000, v12
	v_lshlrev_b32_e32 v10, 16, v13
	v_and_b32_e32 v11, 0xffff0000, v13
	v_lshlrev_b32_e32 v12, 16, v14
	v_and_b32_e32 v13, 0xffff0000, v14
	v_lshlrev_b32_e32 v14, 16, v15
	v_and_b32_e32 v15, 0xffff0000, v15
	v_mul_f32_e32 v3, v3, v15
	v_mul_f32_e32 v4, v4, v8
	v_mul_f32_e32 v5, v5, v9
	v_mul_f32_e32 v6, v6, v10
	v_mul_f32_e32 v7, v7, v11
	v_mul_f32_e32 v8, v0, v12
	v_mul_f32_e32 v9, v1, v13
	v_mul_f32_e32 v10, v2, v14
	v_cvt_pk_bf16_f32 v0, v4, v5
	v_cvt_pk_bf16_f32 v1, v6, v7
	v_cvt_pk_bf16_f32 v2, v8, v9
	v_cvt_pk_bf16_f32 v3, v10, v3
	global_store_dwordx4 v[16:17], v[0:3], off
	s_cbranch_vccnz .LBB0_833
	s_andn2_b64 vcc, exec, s[6:7]
	s_cbranch_vccnz .LBB0_832
	s_barrier
	s_branch .LBB0_832

.LBB0_985:
	v_add_co_u32_e32 v148, vcc, s25, v144
	v_lshl_add_u64 v[64:65], v[146:147], 0, s[8:9]
	s_nop 0
	v_addc_co_u32_e32 v149, vcc, -1, v145, vcc
	v_add_co_u32_e32 v150, vcc, s26, v144
	v_add_co_u32_e64 v68, s[0:1], s22, v64
	s_nop 0
	v_addc_co_u32_e32 v151, vcc, -1, v145, vcc
	v_add_co_u32_e32 v152, vcc, s27, v144
	v_addc_co_u32_e64 v69, s[0:1], 0, v65, s[0:1]
	s_nop 0
	v_addc_co_u32_e32 v153, vcc, -1, v145, vcc
	v_add_co_u32_e32 v66, vcc, 0x6a600000, v64
	v_add_co_u32_e64 v70, s[0:1], s23, v64
	s_nop 0
	v_addc_co_u32_e32 v67, vcc, 0, v65, vcc
	v_addc_co_u32_e64 v71, s[0:1], 0, v65, s[0:1]
	global_load_dwordx4 v[124:127], v[68:69], off nt
	global_load_dwordx4 v[120:123], v[70:71], off nt
	global_load_dwordx4 v[116:119], v[68:69], off offset:1024 nt
	global_load_dwordx4 v[112:115], v[70:71], off offset:1024 nt
	global_load_dwordx4 v[108:111], v[68:69], off offset:2048 nt
	global_load_dwordx4 v[104:107], v[70:71], off offset:2048 nt
	global_load_dwordx4 v[100:103], v[68:69], off offset:3072 nt
	global_load_dwordx4 v[96:99], v[70:71], off offset:3072 nt
	v_add_co_u32_e32 v64, vcc, 0x72600000, v64
	global_load_dwordx4 v[92:95], v[66:67], off nt
	global_load_dwordx4 v[88:91], v[66:67], off offset:1024 nt
	global_load_dwordx4 v[84:87], v[66:67], off offset:2048 nt
	global_load_dwordx4 v[80:83], v[66:67], off offset:3072 nt
	v_addc_co_u32_e32 v65, vcc, 0, v65, vcc
	global_load_dwordx4 v[76:79], v[64:65], off nt
	global_load_dwordx4 v[72:75], v[64:65], off offset:1024 nt
	global_load_dwordx4 v[68:71], v[64:65], off offset:2048 nt
	s_nop 0
	global_load_dwordx4 v[64:67], v[64:65], off offset:3072 nt
	s_ashr_i32 s11, s10, 31
	s_lshl_b64 s[0:1], s[10:11], 13
	s_add_u32 s12, s16, s0
	s_addc_u32 s13, s17, s1
	s_add_u32 s0, s18, s0
	v_lshl_add_u64 v[154:155], s[12:13], 0, v[136:137]
	s_addc_u32 s1, s19, s1
	v_lshl_add_u64 v[156:157], s[12:13], 0, v[138:139]
	v_lshl_add_u64 v[168:169], s[0:1], 0, v[136:137]
	v_lshl_add_u64 v[166:167], s[0:1], 0, v[138:139]
	s_lshl_b64 s[12:13], s[10:11], 14
	s_add_u32 s0, s4, s12
	s_addc_u32 s1, s5, s13
	v_lshl_add_u64 v[164:165], s[0:1], 0, v[128:129]
	v_lshl_add_u64 v[162:163], s[0:1], 0, v[130:131]
	v_lshl_add_u64 v[160:161], s[0:1], 0, v[132:133]
	v_lshl_add_u64 v[158:159], s[0:1], 0, v[134:135]
	s_add_i32 s10, s10, 2
	s_add_u32 s8, s8, 0x4000
	s_addc_u32 s9, s9, 0
	s_cmp_eq_u32 s8, 0x10000
	s_waitcnt vmcnt(0)
	v_lshlrev_b32_e32 v178, 16, v124
	v_and_b32_e32 v179, 0xffff0000, v124
	v_lshlrev_b32_e32 v180, 16, v120
	v_and_b32_e32 v181, 0xffff0000, v120
	v_lshlrev_b32_e32 v124, 16, v125
	v_and_b32_e32 v125, 0xffff0000, v125
	v_lshlrev_b32_e32 v120, 16, v121
	v_and_b32_e32 v121, 0xffff0000, v121
	v_lshlrev_b32_e32 v182, 16, v126
	v_and_b32_e32 v183, 0xffff0000, v126
	v_lshlrev_b32_e32 v184, 16, v122
	v_and_b32_e32 v185, 0xffff0000, v122
	v_lshlrev_b32_e32 v126, 16, v127
	v_and_b32_e32 v127, 0xffff0000, v127
	v_lshlrev_b32_e32 v122, 16, v123
	v_and_b32_e32 v123, 0xffff0000, v123
	v_lshlrev_b32_e32 v186, 16, v116
	v_and_b32_e32 v187, 0xffff0000, v116
	v_lshlrev_b32_e32 v188, 16, v112
	v_and_b32_e32 v189, 0xffff0000, v112
	v_lshlrev_b32_e32 v116, 16, v117
	v_and_b32_e32 v117, 0xffff0000, v117
	v_lshlrev_b32_e32 v112, 16, v113
	v_and_b32_e32 v113, 0xffff0000, v113
	v_lshlrev_b32_e32 v190, 16, v118
	v_and_b32_e32 v191, 0xffff0000, v118
	v_lshlrev_b32_e32 v192, 16, v114
	v_and_b32_e32 v193, 0xffff0000, v114
	v_lshlrev_b32_e32 v118, 16, v119
	v_and_b32_e32 v119, 0xffff0000, v119
	v_lshlrev_b32_e32 v114, 16, v115
	v_and_b32_e32 v115, 0xffff0000, v115
	v_lshlrev_b32_e32 v194, 16, v108
	v_and_b32_e32 v195, 0xffff0000, v108
	v_lshlrev_b32_e32 v196, 16, v104
	v_and_b32_e32 v197, 0xffff0000, v104
	v_lshlrev_b32_e32 v108, 16, v109
	v_and_b32_e32 v109, 0xffff0000, v109
	v_lshlrev_b32_e32 v104, 16, v105
	v_and_b32_e32 v105, 0xffff0000, v105
	v_lshlrev_b32_e32 v198, 16, v110
	v_and_b32_e32 v199, 0xffff0000, v110
	v_lshlrev_b32_e32 v200, 16, v106
	v_and_b32_e32 v201, 0xffff0000, v106
	v_lshlrev_b32_e32 v110, 16, v111
	v_and_b32_e32 v111, 0xffff0000, v111
	v_lshlrev_b32_e32 v106, 16, v107
	v_and_b32_e32 v107, 0xffff0000, v107
	v_lshlrev_b32_e32 v202, 16, v100
	v_and_b32_e32 v203, 0xffff0000, v100
	v_lshlrev_b32_e32 v204, 16, v96
	v_and_b32_e32 v205, 0xffff0000, v96
	v_lshlrev_b32_e32 v100, 16, v101
	v_and_b32_e32 v101, 0xffff0000, v101
	v_lshlrev_b32_e32 v96, 16, v97
	v_and_b32_e32 v97, 0xffff0000, v97
	v_lshlrev_b32_e32 v206, 16, v102
	v_and_b32_e32 v207, 0xffff0000, v102
	v_lshlrev_b32_e32 v208, 16, v98
	v_and_b32_e32 v209, 0xffff0000, v98
	v_lshlrev_b32_e32 v102, 16, v103
	v_and_b32_e32 v103, 0xffff0000, v103
	v_lshlrev_b32_e32 v98, 16, v99
	v_and_b32_e32 v99, 0xffff0000, v99
	v_lshlrev_b32_e32 v210, 16, v92
	v_and_b32_e32 v211, 0xffff0000, v92
	v_lshlrev_b32_e32 v92, 16, v93
	v_and_b32_e32 v93, 0xffff0000, v93
	v_lshlrev_b32_e32 v212, 16, v94
	v_and_b32_e32 v213, 0xffff0000, v94
	v_lshlrev_b32_e32 v94, 16, v95
	v_and_b32_e32 v95, 0xffff0000, v95
	v_pk_add_f32 v[178:179], v[178:179], v[180:181]
	v_pk_add_f32 v[120:121], v[124:125], v[120:121]
	v_pk_add_f32 v[122:123], v[126:127], v[122:123]
	v_pk_add_f32 v[126:127], v[186:187], v[188:189]
	v_pk_add_f32 v[112:113], v[116:117], v[112:113]
	v_pk_add_f32 v[116:117], v[190:191], v[192:193]
	v_pk_add_f32 v[114:115], v[118:119], v[114:115]
	v_pk_add_f32 v[104:105], v[108:109], v[104:105]
	v_pk_add_f32 v[108:109], v[198:199], v[200:201]
	v_pk_add_f32 v[106:107], v[110:111], v[106:107]
	v_pk_add_f32 v[110:111], v[202:203], v[204:205]
	v_pk_add_f32 v[96:97], v[100:101], v[96:97]
	v_pk_add_f32 v[98:99], v[102:103], v[98:99]
	v_lshlrev_b32_e32 v102, 16, v76
	v_and_b32_e32 v103, 0xffff0000, v76
	v_lshlrev_b32_e32 v76, 16, v77
	v_and_b32_e32 v77, 0xffff0000, v77
	v_lshlrev_b32_e32 v180, 16, v78
	v_and_b32_e32 v181, 0xffff0000, v78
	v_lshlrev_b32_e32 v78, 16, v79
	v_and_b32_e32 v79, 0xffff0000, v79
	v_lshlrev_b32_e32 v214, 16, v88
	v_and_b32_e32 v215, 0xffff0000, v88
	v_lshlrev_b32_e32 v88, 16, v89
	v_and_b32_e32 v89, 0xffff0000, v89
	v_lshlrev_b32_e32 v216, 16, v90
	v_and_b32_e32 v217, 0xffff0000, v90
	v_lshlrev_b32_e32 v90, 16, v91
	v_and_b32_e32 v91, 0xffff0000, v91
	v_lshlrev_b32_e32 v218, 16, v84
	v_and_b32_e32 v219, 0xffff0000, v84
	v_lshlrev_b32_e32 v84, 16, v85
	v_and_b32_e32 v85, 0xffff0000, v85
	v_lshlrev_b32_e32 v220, 16, v86
	v_and_b32_e32 v221, 0xffff0000, v86
	v_lshlrev_b32_e32 v86, 16, v87
	v_and_b32_e32 v87, 0xffff0000, v87
	v_lshlrev_b32_e32 v222, 16, v80
	v_and_b32_e32 v223, 0xffff0000, v80
	v_lshlrev_b32_e32 v80, 16, v81
	v_and_b32_e32 v81, 0xffff0000, v81
	v_lshlrev_b32_e32 v224, 16, v82
	v_and_b32_e32 v225, 0xffff0000, v82
	v_lshlrev_b32_e32 v82, 16, v83
	v_and_b32_e32 v83, 0xffff0000, v83
	v_pk_add_f32 v[124:125], v[182:183], v[184:185]
	v_pk_add_f32 v[118:119], v[194:195], v[196:197]
	v_pk_add_f32 v[100:101], v[206:207], v[208:209]
	v_lshlrev_b32_e32 v182, 16, v72
	v_and_b32_e32 v183, 0xffff0000, v72
	v_lshlrev_b32_e32 v72, 16, v73
	v_and_b32_e32 v73, 0xffff0000, v73
	v_lshlrev_b32_e32 v184, 16, v74
	v_and_b32_e32 v185, 0xffff0000, v74
	v_lshlrev_b32_e32 v74, 16, v75
	v_and_b32_e32 v75, 0xffff0000, v75
	v_lshlrev_b32_e32 v186, 16, v68
	v_and_b32_e32 v187, 0xffff0000, v68
	v_lshlrev_b32_e32 v68, 16, v69
	v_and_b32_e32 v69, 0xffff0000, v69
	v_lshlrev_b32_e32 v188, 16, v70
	v_and_b32_e32 v189, 0xffff0000, v70
	v_lshlrev_b32_e32 v70, 16, v71
	v_and_b32_e32 v71, 0xffff0000, v71
	v_lshlrev_b32_e32 v190, 16, v64
	v_and_b32_e32 v191, 0xffff0000, v64
	v_lshlrev_b32_e32 v64, 16, v65
	v_and_b32_e32 v65, 0xffff0000, v65
	v_lshlrev_b32_e32 v192, 16, v66
	v_and_b32_e32 v193, 0xffff0000, v66
	v_lshlrev_b32_e32 v66, 16, v67
	v_and_b32_e32 v67, 0xffff0000, v67
	v_mul_f32_e32 v194, v178, v178
	v_mul_f32_e32 v196, v120, v120
	v_mov_b32_e32 v204, v127
	v_mov_b32_e32 v205, v113
	v_mul_f32_e32 v206, v117, v117
	v_mul_f32_e32 v208, v115, v115
	v_mov_b32_e32 v232, v109
	v_mov_b32_e32 v233, v107
	v_mul_f32_e32 v234, v110, v110
	v_mul_f32_e32 v236, v96, v96
	v_pk_add_f32 v[102:103], v[210:211], v[102:103]
	v_pk_add_f32 v[76:77], v[92:93], v[76:77]
	v_pk_add_f32 v[92:93], v[212:213], v[180:181]
	v_pk_add_f32 v[78:79], v[94:95], v[78:79]
	v_pk_mul_f32 v[200:201], v[122:123], v[122:123]
	v_mov_b32_e32 v202, v126
	v_mov_b32_e32 v203, v112
	v_pk_mul_f32 v[226:227], v[118:119], v[118:119]
	v_mov_b32_e32 v230, v108
	v_mov_b32_e32 v231, v106
	v_pk_mul_f32 v[240:241], v[98:99], v[98:99]
	v_pk_add_f32 v[94:95], v[214:215], v[182:183]
	v_pk_add_f32 v[72:73], v[88:89], v[72:73]
	v_pk_add_f32 v[88:89], v[216:217], v[184:185]
	v_pk_add_f32 v[74:75], v[90:91], v[74:75]
	v_pk_add_f32 v[90:91], v[218:219], v[186:187]
	v_pk_add_f32 v[68:69], v[84:85], v[68:69]
	v_pk_add_f32 v[84:85], v[220:221], v[188:189]
	v_pk_add_f32 v[70:71], v[86:87], v[70:71]
	v_pk_add_f32 v[86:87], v[222:223], v[190:191]
	v_pk_add_f32 v[64:65], v[80:81], v[64:65]
	v_pk_add_f32 v[80:81], v[224:225], v[192:193]
	v_pk_add_f32 v[66:67], v[82:83], v[66:67]
	v_pk_fma_f32 v[82:83], v[178:179], v[178:179], v[194:195] op_sel_hi:[1,1,0]
	v_pk_fma_f32 v[180:181], v[120:121], v[120:121], v[196:197] op_sel_hi:[1,1,0]
	v_pk_mul_f32 v[182:183], v[204:205], v[204:205]
	v_pk_fma_f32 v[184:185], v[116:117], v[116:117], v[206:207] op_sel_hi:[1,1,0]
	v_pk_fma_f32 v[186:187], v[114:115], v[114:115], v[208:209] op_sel_hi:[1,1,0]
	v_pk_mul_f32 v[188:189], v[232:233], v[232:233]
	v_pk_fma_f32 v[190:191], v[110:111], v[110:111], v[234:235] op_sel_hi:[1,1,0]
	v_pk_fma_f32 v[192:193], v[96:97], v[96:97], v[236:237] op_sel_hi:[1,1,0]
	v_mov_b32_e32 v196, v103
	v_mov_b32_e32 v197, v77
	v_mov_b32_e32 v206, v93
	v_mov_b32_e32 v207, v79
	v_mov_b32_e32 v194, v102
	v_mov_b32_e32 v195, v76
	v_mov_b32_e32 v204, v92
	v_mov_b32_e32 v205, v78
	v_mov_b32_e32 v82, v200
	v_mov_b32_e32 v180, v201
	v_pk_fma_f32 v[182:183], v[202:203], v[202:203], v[182:183]
	v_mov_b32_e32 v185, v226
	v_mov_b32_e32 v187, v227
	v_pk_fma_f32 v[188:189], v[230:231], v[230:231], v[188:189]
	v_mov_b32_e32 v190, v240
	v_mov_b32_e32 v192, v241
	v_pk_mul_f32 v[196:197], v[196:197], v[196:197]
	v_pk_mul_f32 v[200:201], v[206:207], v[206:207]
	v_mul_f32_e32 v208, v94, v94
	v_mul_f32_e32 v210, v72, v72
	v_pk_add_f32 v[82:83], v[82:83], v[180:181]
	v_pk_add_f32 v[180:181], v[182:183], v[182:183] op_sel:[0,1] op_sel_hi:[1,0]
	v_pk_add_f32 v[182:183], v[184:185], v[186:187]
	v_pk_add_f32 v[184:185], v[188:189], v[188:189] op_sel_hi:[0,1]
	v_pk_add_f32 v[186:187], v[190:191], v[192:193]
	v_pk_fma_f32 v[188:189], v[194:195], v[194:195], v[196:197]
	v_pk_fma_f32 v[190:191], v[204:205], v[204:205], v[200:201]
	v_pk_mul_f32 v[212:213], v[88:89], v[88:89]
	v_pk_mul_f32 v[214:215], v[74:75], v[74:75]
	v_pk_fma_f32 v[202:203], v[94:95], v[94:95], v[208:209] op_sel_hi:[1,1,0]
	v_pk_fma_f32 v[206:207], v[72:73], v[72:73], v[210:211] op_sel_hi:[1,1,0]
	v_pk_add_f32 v[188:189], v[188:189], v[188:189] op_sel_hi:[0,1]
	v_pk_add_f32 v[190:191], v[190:191], v[190:191] op_sel_hi:[0,1]
	v_mov_b32_e32 v218, v91
	v_mov_b32_e32 v219, v69
	v_mov_b32_e32 v202, v214
	v_mov_b32_e32 v206, v215
	v_mov_b32_e32 v188, v212
	v_mov_b32_e32 v190, v213
	v_mov_b32_e32 v216, v90
	v_mov_b32_e32 v217, v68
	v_pk_mul_f32 v[208:209], v[218:219], v[218:219]
	v_pk_add_f32 v[196:197], v[202:203], v[206:207]
	v_pk_add_f32 v[188:189], v[188:189], v[190:191]
	v_mul_f32_e32 v220, v85, v85
	v_mul_f32_e32 v222, v71, v71
	v_pk_fma_f32 v[192:193], v[216:217], v[216:217], v[208:209]
	v_pk_add_f32 v[188:189], v[188:189], v[196:197]
	v_pk_mul_f32 v[224:225], v[86:87], v[86:87]
	v_pk_mul_f32 v[232:233], v[64:65], v[64:65]
	v_pk_fma_f32 v[210:211], v[84:85], v[84:85], v[220:221] op_sel_hi:[1,1,0]
	v_pk_fma_f32 v[218:219], v[70:71], v[70:71], v[222:223] op_sel_hi:[1,1,0]
	v_pk_add_f32 v[192:193], v[192:193], v[192:193] op_sel:[0,1] op_sel_hi:[1,0]
	v_pk_add_f32 v[188:189], v[188:189], v[188:189] op_sel:[0,1] op_sel_hi:[1,0]
	v_mov_b32_e32 v236, v81
	v_mov_b32_e32 v237, v67
	v_mov_b32_e32 v211, v224
	v_mov_b32_e32 v219, v225
	v_mov_b32_e32 v193, v233
	v_mov_b32_e32 v189, v232
	v_mov_b32_e32 v234, v80
	v_mov_b32_e32 v235, v66
	v_pk_mul_f32 v[220:221], v[236:237], v[236:237]
	v_pk_add_f32 v[200:201], v[210:211], v[218:219]
	v_pk_add_f32 v[188:189], v[188:189], v[192:193]
	v_pk_fma_f32 v[194:195], v[234:235], v[234:235], v[220:221]
	v_pk_add_f32 v[188:189], v[200:201], v[188:189]
	v_pk_mul_f32 v[198:199], v[124:125], v[124:125]
	v_pk_add_f32 v[194:195], v[194:195], v[194:195] op_sel_hi:[0,1]
	v_pk_add_f32 v[188:189], v[188:189], v[188:189] op_sel_hi:[0,1]
	v_mov_b32_e32 v194, v198
	v_mov_b32_e32 v188, v199
	v_pk_add_f32 v[188:189], v[194:195], v[188:189]
	v_pk_mul_f32 v[228:229], v[104:105], v[104:105]
	v_pk_add_f32 v[82:83], v[188:189], v[82:83]
	v_mov_b32_e32 v181, v229
	v_pk_add_f32 v[82:83], v[82:83], v[82:83] op_sel:[0,1] op_sel_hi:[1,0]
	v_pk_mul_f32 v[238:239], v[100:101], v[100:101]
	v_mov_b32_e32 v83, v228
	v_pk_add_f32 v[82:83], v[82:83], v[180:181]
	v_mov_b32_e32 v184, v238
	v_pk_add_f32 v[82:83], v[182:183], v[82:83]
	s_nop 0
	v_pk_add_f32 v[82:83], v[82:83], v[82:83] op_sel_hi:[0,1]
	v_mov_b32_e32 v82, v239
	v_pk_add_f32 v[82:83], v[184:185], v[82:83]
	s_nop 0
	v_pk_add_f32 v[82:83], v[82:83], v[186:187]
	s_nop 0
	v_add_f32_e32 v82, v82, v83
	ds_bpermute_b32 v83, v170, v82
	s_waitcnt lgkmcnt(0)
	v_add_f32_e32 v82, v82, v83
	ds_bpermute_b32 v83, v171, v82
	s_waitcnt lgkmcnt(0)
	v_add_f32_e32 v82, v82, v83
	ds_bpermute_b32 v83, v172, v82
	s_waitcnt lgkmcnt(0)
	v_add_f32_e32 v82, v82, v83
	ds_bpermute_b32 v83, v173, v82
	s_waitcnt lgkmcnt(0)
	v_add_f32_e32 v82, v82, v83
	ds_bpermute_b32 v83, v174, v82
	s_waitcnt lgkmcnt(0)
	v_add_f32_e32 v82, v82, v83
	ds_bpermute_b32 v83, v175, v82
	s_waitcnt lgkmcnt(0)
	v_add_f32_e32 v82, v82, v83
	v_fmamk_f32 v82, v82, 0x39800000, v176
	v_mul_f32_e32 v83, 0x4b800000, v82
	v_cmp_gt_f32_e32 vcc, s24, v82
	s_nop 1
	v_cndmask_b32_e32 v82, v82, v83, vcc
	v_rsq_f32_e32 v82, v82
	s_nop 0
	v_mul_f32_e32 v83, 0x45800000, v82
	v_cndmask_b32_e32 v82, v82, v83, vcc
	v_pk_mul_f32 v[102:103], v[102:103], v[82:83] op_sel_hi:[1,0]
	v_pk_mul_f32 v[76:77], v[76:77], v[82:83] op_sel_hi:[1,0]
	v_pk_mul_f32 v[92:93], v[92:93], v[82:83] op_sel_hi:[1,0]
	v_pk_mul_f32 v[78:79], v[78:79], v[82:83] op_sel_hi:[1,0]
	v_pk_mul_f32 v[94:95], v[94:95], v[82:83] op_sel_hi:[1,0]
	v_pk_mul_f32 v[72:73], v[72:73], v[82:83] op_sel_hi:[1,0]
	v_pk_mul_f32 v[88:89], v[88:89], v[82:83] op_sel_hi:[1,0]
	v_pk_mul_f32 v[180:181], v[74:75], v[82:83] op_sel_hi:[1,0]
	v_pk_mul_f32 v[90:91], v[90:91], v[82:83] op_sel_hi:[1,0]
	v_pk_mul_f32 v[182:183], v[68:69], v[82:83] op_sel_hi:[1,0]
	v_pk_mul_f32 v[188:189], v[64:65], v[82:83] op_sel_hi:[1,0]
	v_pk_mul_f32 v[192:193], v[66:67], v[82:83] op_sel_hi:[1,0]
	v_pk_mul_f32 v[66:67], v[6:7], v[76:77]
	v_pk_mul_f32 v[64:65], v[4:5], v[102:103]
	v_pk_mul_f32 v[84:85], v[84:85], v[82:83] op_sel_hi:[1,0]
	v_pk_mul_f32 v[184:185], v[70:71], v[82:83] op_sel_hi:[1,0]
	v_pk_mul_f32 v[186:187], v[86:87], v[82:83] op_sel_hi:[1,0]
	v_pk_mul_f32 v[190:191], v[80:81], v[82:83] op_sel_hi:[1,0]
	v_pk_mul_f32 v[178:179], v[178:179], v[82:83] op_sel_hi:[1,0]
	v_pk_mul_f32 v[120:121], v[120:121], v[82:83] op_sel_hi:[1,0]
	v_pk_mul_f32 v[124:125], v[124:125], v[82:83] op_sel_hi:[1,0]
	v_pk_mul_f32 v[122:123], v[122:123], v[82:83] op_sel_hi:[1,0]
	v_pk_mul_f32 v[126:127], v[126:127], v[82:83] op_sel_hi:[1,0]
	v_pk_mul_f32 v[112:113], v[112:113], v[82:83] op_sel_hi:[1,0]
	v_pk_mul_f32 v[116:117], v[116:117], v[82:83] op_sel_hi:[1,0]
	v_pk_mul_f32 v[114:115], v[114:115], v[82:83] op_sel_hi:[1,0]
	v_pk_mul_f32 v[118:119], v[118:119], v[82:83] op_sel_hi:[1,0]
	v_pk_mul_f32 v[194:195], v[104:105], v[82:83] op_sel_hi:[1,0]
	v_pk_mul_f32 v[196:197], v[108:109], v[82:83] op_sel_hi:[1,0]
	v_pk_mul_f32 v[198:199], v[106:107], v[82:83] op_sel_hi:[1,0]
	v_pk_mul_f32 v[200:201], v[110:111], v[82:83] op_sel_hi:[1,0]
	v_pk_mul_f32 v[202:203], v[96:97], v[82:83] op_sel_hi:[1,0]
	v_pk_mul_f32 v[204:205], v[100:101], v[82:83] op_sel_hi:[1,0]
	v_pk_mul_f32 v[206:207], v[98:99], v[82:83] op_sel_hi:[1,0]
	v_pk_mul_f32 v[70:71], v[2:3], v[78:79]
	v_pk_mul_f32 v[68:69], v[0:1], v[92:93]
	v_pk_mul_f32 v[74:75], v[14:15], v[72:73]
	v_pk_mul_f32 v[72:73], v[12:13], v[94:95]
	v_pk_mul_f32 v[78:79], v[10:11], v[180:181]
	v_pk_mul_f32 v[76:77], v[8:9], v[88:89]
	v_pk_mul_f32 v[82:83], v[22:23], v[182:183]
	v_pk_mul_f32 v[80:81], v[20:21], v[90:91]
	global_store_dwordx4 v[148:149], v[64:67], off offset:-2064 nt
	global_store_dwordx4 v[148:149], v[68:71], off offset:-2048 nt
	global_store_dwordx4 v[148:149], v[72:75], off offset:-16 nt
	global_store_dwordx4 v[150:151], v[76:79], off offset:-4096 nt
	v_pk_mul_f32 v[86:87], v[18:19], v[184:185]
	v_pk_mul_f32 v[84:85], v[16:17], v[84:85]
	v_pk_mul_f32 v[90:91], v[30:31], v[188:189]
	v_pk_mul_f32 v[88:89], v[28:29], v[186:187]
	v_pk_mul_f32 v[94:95], v[26:27], v[192:193]
	v_pk_mul_f32 v[92:93], v[24:25], v[190:191]
	v_pk_mul_f32 v[98:99], v[38:39], v[120:121]
	v_pk_mul_f32 v[96:97], v[36:37], v[178:179]
	global_store_dwordx4 v[150:151], v[80:83], off offset:-2064 nt
	global_store_dwordx4 v[150:151], v[84:87], off offset:-2048 nt
	global_store_dwordx4 v[150:151], v[88:91], off offset:-16 nt
	global_store_dwordx4 v[150:151], v[92:95], off nt
	v_pk_mul_f32 v[102:103], v[34:35], v[122:123]
	v_pk_mul_f32 v[100:101], v[32:33], v[124:125]
	v_pk_mul_f32 v[106:107], v[46:47], v[112:113]
	v_pk_mul_f32 v[104:105], v[44:45], v[126:127]
	v_pk_mul_f32 v[110:111], v[42:43], v[114:115]
	v_pk_mul_f32 v[108:109], v[40:41], v[116:117]
	v_pk_mul_f32 v[114:115], v[54:55], v[194:195]
	v_pk_mul_f32 v[112:113], v[52:53], v[118:119]
	global_store_dwordx4 v[152:153], v[96:99], off offset:-2064 nt
	global_store_dwordx4 v[152:153], v[100:103], off offset:-2048 nt
	global_store_dwordx4 v[152:153], v[104:107], off offset:-16 nt
	global_store_dwordx4 v[144:145], v[108:111], off offset:-4096 nt
	v_pk_mul_f32 v[118:119], v[50:51], v[198:199]
	v_pk_mul_f32 v[116:117], v[48:49], v[196:197]
	v_pk_mul_f32 v[122:123], v[62:63], v[202:203]
	v_pk_mul_f32 v[120:121], v[60:61], v[200:201]
	v_pk_mul_f32 v[126:127], v[58:59], v[206:207]
	v_pk_mul_f32 v[124:125], v[56:57], v[204:205]
	global_store_dwordx4 v[144:145], v[112:115], off offset:-2064 nt
	global_store_dwordx4 v[144:145], v[116:119], off offset:-2048 nt
	global_store_dwordx4 v[144:145], v[120:123], off offset:-16 nt
	global_store_dwordx4 v[144:145], v[124:127], off nt
	global_load_dwordx4 v[64:67], v[154:155], off nt
	global_load_dwordx4 v[68:71], v[168:169], off nt
	global_load_dwordx4 v[72:75], v[154:155], off offset:1024 nt
	global_load_dwordx4 v[76:79], v[168:169], off offset:1024 nt
	global_load_dwordx4 v[80:83], v[154:155], off offset:2048 nt
	global_load_dwordx4 v[84:87], v[168:169], off offset:2048 nt
	global_load_dwordx4 v[88:91], v[154:155], off offset:3072 nt
	global_load_dwordx4 v[92:95], v[168:169], off offset:3072 nt
	global_load_dwordx4 v[96:99], v[156:157], off nt
	global_load_dwordx4 v[100:103], v[166:167], off nt
	global_load_dwordx4 v[104:107], v[156:157], off offset:1024 nt
	global_load_dwordx4 v[108:111], v[166:167], off offset:1024 nt
	global_load_dwordx4 v[112:115], v[156:157], off offset:2048 nt
	global_load_dwordx4 v[116:119], v[156:157], off offset:3072 nt
	global_load_dwordx4 v[120:123], v[166:167], off offset:2048 nt
	global_load_dwordx4 v[124:127], v[166:167], off offset:3072 nt
	v_lshl_add_u64 v[144:145], v[144:145], 0, s[6:7]
	s_waitcnt vmcnt(15)
	v_lshlrev_b32_e32 v148, 16, v64
	v_and_b32_e32 v149, 0xffff0000, v64
	s_waitcnt vmcnt(14)
	v_lshlrev_b32_e32 v150, 16, v68
	v_and_b32_e32 v151, 0xffff0000, v68
	v_lshlrev_b32_e32 v64, 16, v65
	v_and_b32_e32 v65, 0xffff0000, v65
	v_lshlrev_b32_e32 v68, 16, v69
	v_and_b32_e32 v69, 0xffff0000, v69
	v_lshlrev_b32_e32 v152, 16, v66
	v_and_b32_e32 v153, 0xffff0000, v66
	v_lshlrev_b32_e32 v154, 16, v70
	v_and_b32_e32 v155, 0xffff0000, v70
	v_lshlrev_b32_e32 v66, 16, v67
	v_and_b32_e32 v67, 0xffff0000, v67
	v_lshlrev_b32_e32 v70, 16, v71
	v_and_b32_e32 v71, 0xffff0000, v71
	v_pk_add_f32 v[148:149], v[148:149], v[150:151]
	v_pk_add_f32 v[64:65], v[64:65], v[68:69]
	v_pk_add_f32 v[68:69], v[152:153], v[154:155]
	v_pk_add_f32 v[66:67], v[66:67], v[70:71]
	s_waitcnt vmcnt(13)
	v_lshlrev_b32_e32 v156, 16, v72
	v_and_b32_e32 v157, 0xffff0000, v72
	s_waitcnt vmcnt(12)
	v_lshlrev_b32_e32 v166, 16, v76
	v_and_b32_e32 v167, 0xffff0000, v76
	v_lshlrev_b32_e32 v72, 16, v73
	v_and_b32_e32 v73, 0xffff0000, v73
	v_lshlrev_b32_e32 v76, 16, v77
	v_and_b32_e32 v77, 0xffff0000, v77
	s_waitcnt vmcnt(2)
	v_lshlrev_b32_e32 v224, 16, v118
	v_and_b32_e32 v225, 0xffff0000, v118
	s_waitcnt vmcnt(0)
	v_lshlrev_b32_e32 v226, 16, v126
	v_and_b32_e32 v227, 0xffff0000, v126
	v_lshlrev_b32_e32 v118, 16, v119
	v_and_b32_e32 v119, 0xffff0000, v119
	v_lshlrev_b32_e32 v126, 16, v127
	v_and_b32_e32 v127, 0xffff0000, v127
	v_mov_b32_e32 v150, v149
	v_mov_b32_e32 v151, v65
	v_mov_b32_e32 v154, v69
	v_mov_b32_e32 v155, v67
	v_lshlrev_b32_e32 v168, 16, v74
	v_and_b32_e32 v169, 0xffff0000, v74
	v_lshlrev_b32_e32 v178, 16, v78
	v_and_b32_e32 v179, 0xffff0000, v78
	v_lshlrev_b32_e32 v74, 16, v75
	v_and_b32_e32 v75, 0xffff0000, v75
	v_lshlrev_b32_e32 v78, 16, v79
	v_and_b32_e32 v79, 0xffff0000, v79
	v_pk_add_f32 v[70:71], v[156:157], v[166:167]
	v_pk_add_f32 v[72:73], v[72:73], v[76:77]
	v_pk_add_f32 v[118:119], v[118:119], v[126:127]
	v_mov_b32_e32 v126, v148
	v_mov_b32_e32 v127, v64
	v_mov_b32_e32 v152, v68
	v_mov_b32_e32 v153, v66
	v_pk_mul_f32 v[150:151], v[150:151], v[150:151]
	v_pk_mul_f32 v[154:155], v[154:155], v[154:155]
	v_lshlrev_b32_e32 v180, 16, v80
	v_and_b32_e32 v181, 0xffff0000, v80
	v_lshlrev_b32_e32 v182, 16, v84
	v_and_b32_e32 v183, 0xffff0000, v84
	v_lshlrev_b32_e32 v80, 16, v81
	v_and_b32_e32 v81, 0xffff0000, v81
	v_lshlrev_b32_e32 v84, 16, v85
	v_and_b32_e32 v85, 0xffff0000, v85
	v_pk_add_f32 v[76:77], v[168:169], v[178:179]
	v_pk_add_f32 v[74:75], v[74:75], v[78:79]
	v_mul_f32_e32 v156, v70, v70
	v_mul_f32_e32 v166, v72, v72
	v_pk_fma_f32 v[126:127], v[126:127], v[126:127], v[150:151]
	v_pk_fma_f32 v[150:151], v[152:153], v[152:153], v[154:155]
	v_pk_add_f32 v[78:79], v[180:181], v[182:183]
	v_pk_add_f32 v[80:81], v[80:81], v[84:85]
	v_pk_mul_f32 v[168:169], v[76:77], v[76:77]
	v_pk_mul_f32 v[178:179], v[74:75], v[74:75]
	v_pk_fma_f32 v[156:157], v[70:71], v[70:71], v[156:157] op_sel_hi:[1,1,0]
	v_pk_fma_f32 v[166:167], v[72:73], v[72:73], v[166:167] op_sel_hi:[1,1,0]
	v_pk_add_f32 v[126:127], v[126:127], v[126:127] op_sel_hi:[0,1]
	v_pk_add_f32 v[150:151], v[150:151], v[150:151] op_sel_hi:[0,1]
	v_lshlrev_b32_e32 v184, 16, v82
	v_and_b32_e32 v185, 0xffff0000, v82
	v_lshlrev_b32_e32 v186, 16, v86
	v_and_b32_e32 v187, 0xffff0000, v86
	v_lshlrev_b32_e32 v82, 16, v83
	v_and_b32_e32 v83, 0xffff0000, v83
	v_lshlrev_b32_e32 v86, 16, v87
	v_and_b32_e32 v87, 0xffff0000, v87
	v_mov_b32_e32 v182, v79
	v_mov_b32_e32 v183, v81
	v_mov_b32_e32 v156, v178
	v_mov_b32_e32 v166, v179
	v_mov_b32_e32 v126, v168
	v_mov_b32_e32 v150, v169
	v_lshlrev_b32_e32 v188, 16, v88
	v_and_b32_e32 v189, 0xffff0000, v88
	v_lshlrev_b32_e32 v190, 16, v92
	v_and_b32_e32 v191, 0xffff0000, v92
	v_lshlrev_b32_e32 v88, 16, v89
	v_and_b32_e32 v89, 0xffff0000, v89
	v_lshlrev_b32_e32 v92, 16, v93
	v_and_b32_e32 v93, 0xffff0000, v93
	v_pk_add_f32 v[84:85], v[184:185], v[186:187]
	v_pk_add_f32 v[82:83], v[82:83], v[86:87]
	v_mov_b32_e32 v180, v78
	v_mov_b32_e32 v181, v80
	v_pk_mul_f32 v[182:183], v[182:183], v[182:183]
	v_pk_add_f32 v[156:157], v[156:157], v[166:167]
	v_pk_add_f32 v[126:127], v[126:127], v[150:151]
	v_lshlrev_b32_e32 v192, 16, v90
	v_and_b32_e32 v193, 0xffff0000, v90
	v_lshlrev_b32_e32 v194, 16, v94
	v_and_b32_e32 v195, 0xffff0000, v94
	v_lshlrev_b32_e32 v90, 16, v91
	v_and_b32_e32 v91, 0xffff0000, v91
	v_lshlrev_b32_e32 v94, 16, v95
	v_and_b32_e32 v95, 0xffff0000, v95
	v_pk_add_f32 v[86:87], v[188:189], v[190:191]
	v_pk_add_f32 v[88:89], v[88:89], v[92:93]
	v_mul_f32_e32 v184, v85, v85
	v_mul_f32_e32 v186, v83, v83
	v_pk_fma_f32 v[152:153], v[180:181], v[180:181], v[182:183]
	v_pk_add_f32 v[126:127], v[126:127], v[156:157]
	v_pk_add_f32 v[92:93], v[192:193], v[194:195]
	v_pk_add_f32 v[90:91], v[90:91], v[94:95]
	v_pk_mul_f32 v[188:189], v[86:87], v[86:87]
	v_pk_mul_f32 v[190:191], v[88:89], v[88:89]
	v_pk_fma_f32 v[184:185], v[84:85], v[84:85], v[184:185] op_sel_hi:[1,1,0]
	v_pk_fma_f32 v[186:187], v[82:83], v[82:83], v[186:187] op_sel_hi:[1,1,0]
	v_pk_add_f32 v[152:153], v[152:153], v[152:153] op_sel:[0,1] op_sel_hi:[1,0]
	v_pk_add_f32 v[126:127], v[126:127], v[126:127] op_sel:[0,1] op_sel_hi:[1,0]
	v_lshlrev_b32_e32 v196, 16, v96
	v_and_b32_e32 v197, 0xffff0000, v96
	v_lshlrev_b32_e32 v198, 16, v100
	v_and_b32_e32 v199, 0xffff0000, v100
	v_lshlrev_b32_e32 v96, 16, v97
	v_and_b32_e32 v97, 0xffff0000, v97
	v_lshlrev_b32_e32 v100, 16, v101
	v_and_b32_e32 v101, 0xffff0000, v101
	v_mov_b32_e32 v194, v93
	v_mov_b32_e32 v195, v91
	v_mov_b32_e32 v185, v188
	v_mov_b32_e32 v187, v189
	v_mov_b32_e32 v153, v191
	v_mov_b32_e32 v127, v190
	v_lshlrev_b32_e32 v200, 16, v98
	v_and_b32_e32 v201, 0xffff0000, v98
	v_lshlrev_b32_e32 v202, 16, v102
	v_and_b32_e32 v203, 0xffff0000, v102
	v_lshlrev_b32_e32 v98, 16, v99
	v_and_b32_e32 v99, 0xffff0000, v99
	v_lshlrev_b32_e32 v102, 16, v103
	v_and_b32_e32 v103, 0xffff0000, v103
	v_pk_add_f32 v[94:95], v[196:197], v[198:199]
	v_pk_add_f32 v[96:97], v[96:97], v[100:101]
	v_mov_b32_e32 v192, v92
	v_mov_b32_e32 v193, v90
	v_pk_mul_f32 v[194:195], v[194:195], v[194:195]
	v_pk_add_f32 v[166:167], v[184:185], v[186:187]
	v_pk_add_f32 v[126:127], v[126:127], v[152:153]
	v_lshlrev_b32_e32 v204, 16, v104
	v_and_b32_e32 v205, 0xffff0000, v104
	v_lshlrev_b32_e32 v206, 16, v108
	v_and_b32_e32 v207, 0xffff0000, v108
	v_lshlrev_b32_e32 v104, 16, v105
	v_and_b32_e32 v105, 0xffff0000, v105
	v_lshlrev_b32_e32 v108, 16, v109
	v_and_b32_e32 v109, 0xffff0000, v109
	v_pk_add_f32 v[100:101], v[200:201], v[202:203]
	v_pk_add_f32 v[98:99], v[98:99], v[102:103]
	v_mul_f32_e32 v196, v94, v94
	v_mul_f32_e32 v198, v96, v96
	v_pk_fma_f32 v[154:155], v[192:193], v[192:193], v[194:195]
	v_pk_add_f32 v[126:127], v[166:167], v[126:127]
	v_pk_add_f32 v[102:103], v[204:205], v[206:207]
	v_pk_add_f32 v[104:105], v[104:105], v[108:109]
	v_pk_mul_f32 v[200:201], v[100:101], v[100:101]
	v_pk_mul_f32 v[202:203], v[98:99], v[98:99]
	v_pk_fma_f32 v[196:197], v[94:95], v[94:95], v[196:197] op_sel_hi:[1,1,0]
	v_pk_fma_f32 v[198:199], v[96:97], v[96:97], v[198:199] op_sel_hi:[1,1,0]
	v_pk_add_f32 v[154:155], v[154:155], v[154:155] op_sel_hi:[0,1]
	v_pk_add_f32 v[126:127], v[126:127], v[126:127] op_sel_hi:[0,1]
	v_lshlrev_b32_e32 v208, 16, v106
	v_and_b32_e32 v209, 0xffff0000, v106
	v_lshlrev_b32_e32 v210, 16, v110
	v_and_b32_e32 v211, 0xffff0000, v110
	v_lshlrev_b32_e32 v106, 16, v107
	v_and_b32_e32 v107, 0xffff0000, v107
	v_lshlrev_b32_e32 v110, 16, v111
	v_and_b32_e32 v111, 0xffff0000, v111
	v_mov_b32_e32 v206, v103
	v_mov_b32_e32 v207, v105
	v_mov_b32_e32 v196, v202
	v_mov_b32_e32 v198, v203
	v_mov_b32_e32 v154, v200
	v_mov_b32_e32 v126, v201
	v_lshlrev_b32_e32 v212, 16, v112
	v_and_b32_e32 v213, 0xffff0000, v112
	v_lshlrev_b32_e32 v214, 16, v120
	v_and_b32_e32 v215, 0xffff0000, v120
	v_lshlrev_b32_e32 v112, 16, v113
	v_and_b32_e32 v113, 0xffff0000, v113
	v_lshlrev_b32_e32 v120, 16, v121
	v_and_b32_e32 v121, 0xffff0000, v121
	v_pk_add_f32 v[108:109], v[208:209], v[210:211]
	v_pk_add_f32 v[106:107], v[106:107], v[110:111]
	v_mov_b32_e32 v204, v102
	v_mov_b32_e32 v205, v104
	v_pk_mul_f32 v[206:207], v[206:207], v[206:207]
	v_pk_add_f32 v[182:183], v[196:197], v[198:199]
	v_pk_add_f32 v[126:127], v[154:155], v[126:127]
	v_lshlrev_b32_e32 v216, 16, v114
	v_and_b32_e32 v217, 0xffff0000, v114
	v_lshlrev_b32_e32 v218, 16, v122
	v_and_b32_e32 v219, 0xffff0000, v122
	v_lshlrev_b32_e32 v114, 16, v115
	v_and_b32_e32 v115, 0xffff0000, v115
	v_lshlrev_b32_e32 v122, 16, v123
	v_and_b32_e32 v123, 0xffff0000, v123
	v_pk_add_f32 v[110:111], v[212:213], v[214:215]
	v_pk_add_f32 v[112:113], v[112:113], v[120:121]
	v_mul_f32_e32 v208, v109, v109
	v_mul_f32_e32 v210, v107, v107
	v_pk_fma_f32 v[178:179], v[204:205], v[204:205], v[206:207]
	v_pk_add_f32 v[126:127], v[126:127], v[182:183]
	v_pk_add_f32 v[120:121], v[216:217], v[218:219]
	v_pk_add_f32 v[114:115], v[114:115], v[122:123]
	v_pk_mul_f32 v[212:213], v[110:111], v[110:111]
	v_pk_mul_f32 v[214:215], v[112:113], v[112:113]
	v_pk_fma_f32 v[208:209], v[108:109], v[108:109], v[208:209] op_sel_hi:[1,1,0]
	v_pk_fma_f32 v[210:211], v[106:107], v[106:107], v[210:211] op_sel_hi:[1,1,0]
	v_pk_add_f32 v[178:179], v[178:179], v[178:179] op_sel:[0,1] op_sel_hi:[1,0]
	v_pk_add_f32 v[126:127], v[126:127], v[126:127] op_sel:[0,1] op_sel_hi:[1,0]
	v_lshlrev_b32_e32 v220, 16, v116
	v_and_b32_e32 v221, 0xffff0000, v116
	v_lshlrev_b32_e32 v222, 16, v124
	v_and_b32_e32 v223, 0xffff0000, v124
	v_lshlrev_b32_e32 v116, 16, v117
	v_and_b32_e32 v117, 0xffff0000, v117
	v_lshlrev_b32_e32 v124, 16, v125
	v_and_b32_e32 v125, 0xffff0000, v125
	v_mov_b32_e32 v218, v121
	v_mov_b32_e32 v219, v115
	v_mov_b32_e32 v209, v212
	v_mov_b32_e32 v211, v213
	v_mov_b32_e32 v179, v215
	v_mov_b32_e32 v127, v214
	v_pk_add_f32 v[122:123], v[220:221], v[222:223]
	v_pk_add_f32 v[116:117], v[116:117], v[124:125]
	v_mov_b32_e32 v216, v120
	v_mov_b32_e32 v217, v114
	v_pk_mul_f32 v[218:219], v[218:219], v[218:219]
	v_pk_add_f32 v[184:185], v[208:209], v[210:211]
	v_pk_add_f32 v[126:127], v[126:127], v[178:179]
	v_pk_add_f32 v[124:125], v[224:225], v[226:227]
	v_mul_f32_e32 v220, v122, v122
	v_mul_f32_e32 v222, v116, v116
	v_pk_fma_f32 v[180:181], v[216:217], v[216:217], v[218:219]
	v_pk_add_f32 v[126:127], v[184:185], v[126:127]
	v_pk_mul_f32 v[224:225], v[124:125], v[124:125]
	v_pk_mul_f32 v[226:227], v[118:119], v[118:119]
	v_pk_fma_f32 v[220:221], v[122:123], v[122:123], v[220:221] op_sel_hi:[1,1,0]
	v_pk_fma_f32 v[222:223], v[116:117], v[116:117], v[222:223] op_sel_hi:[1,1,0]
	v_pk_add_f32 v[180:181], v[180:181], v[180:181] op_sel_hi:[0,1]
	v_pk_add_f32 v[126:127], v[126:127], v[126:127] op_sel_hi:[0,1]
	v_mov_b32_e32 v220, v226
	v_mov_b32_e32 v222, v227
	v_mov_b32_e32 v180, v224
	v_mov_b32_e32 v126, v225
	v_pk_add_f32 v[186:187], v[220:221], v[222:223]
	v_pk_add_f32 v[126:127], v[180:181], v[126:127]
	s_nop 0
	v_pk_add_f32 v[126:127], v[126:127], v[186:187]
	s_nop 0
	v_add_f32_e32 v126, v126, v127
	ds_bpermute_b32 v127, v170, v126
	s_waitcnt lgkmcnt(0)
	v_add_f32_e32 v126, v126, v127
	ds_bpermute_b32 v127, v171, v126
	s_waitcnt lgkmcnt(0)
	v_add_f32_e32 v126, v126, v127
	ds_bpermute_b32 v127, v172, v126
	s_waitcnt lgkmcnt(0)
	v_add_f32_e32 v126, v126, v127
	ds_bpermute_b32 v127, v173, v126
	s_waitcnt lgkmcnt(0)
	v_add_f32_e32 v126, v126, v127
	ds_bpermute_b32 v127, v174, v126
	s_waitcnt lgkmcnt(0)
	v_add_f32_e32 v126, v126, v127
	ds_bpermute_b32 v127, v175, v126
	s_waitcnt lgkmcnt(0)
	v_add_f32_e32 v126, v126, v127
	v_fmamk_f32 v126, v126, 0x39800000, v176
	v_mul_f32_e32 v127, 0x4b800000, v126
	v_cmp_gt_f32_e32 vcc, s24, v126
	s_nop 1
	v_cndmask_b32_e32 v126, v126, v127, vcc
	v_rsq_f32_e32 v126, v126
	s_nop 0
	v_mul_f32_e32 v127, 0x45800000, v126
	v_cndmask_b32_e32 v126, v126, v127, vcc
	v_pk_mul_f32 v[148:149], v[148:149], v[126:127] op_sel_hi:[1,0]
	v_pk_mul_f32 v[64:65], v[64:65], v[126:127] op_sel_hi:[1,0]
	v_pk_mul_f32 v[68:69], v[68:69], v[126:127] op_sel_hi:[1,0]
	v_pk_mul_f32 v[150:151], v[66:67], v[126:127] op_sel_hi:[1,0]
	v_pk_mul_f32 v[152:153], v[70:71], v[126:127] op_sel_hi:[1,0]
	v_pk_mul_f32 v[72:73], v[72:73], v[126:127] op_sel_hi:[1,0]
	v_pk_mul_f32 v[76:77], v[76:77], v[126:127] op_sel_hi:[1,0]
	v_pk_mul_f32 v[154:155], v[74:75], v[126:127] op_sel_hi:[1,0]
	v_pk_mul_f32 v[156:157], v[78:79], v[126:127] op_sel_hi:[1,0]
	v_pk_mul_f32 v[80:81], v[80:81], v[126:127] op_sel_hi:[1,0]
	v_pk_mul_f32 v[66:67], v[6:7], v[64:65]
	v_pk_mul_f32 v[64:65], v[4:5], v[148:149]
	v_pk_mul_f32 v[84:85], v[84:85], v[126:127] op_sel_hi:[1,0]
	v_pk_mul_f32 v[166:167], v[82:83], v[126:127] op_sel_hi:[1,0]
	v_pk_mul_f32 v[168:169], v[86:87], v[126:127] op_sel_hi:[1,0]
	v_pk_mul_f32 v[88:89], v[88:89], v[126:127] op_sel_hi:[1,0]
	v_pk_mul_f32 v[92:93], v[92:93], v[126:127] op_sel_hi:[1,0]
	v_pk_mul_f32 v[178:179], v[90:91], v[126:127] op_sel_hi:[1,0]
	v_pk_mul_f32 v[180:181], v[94:95], v[126:127] op_sel_hi:[1,0]
	v_pk_mul_f32 v[96:97], v[96:97], v[126:127] op_sel_hi:[1,0]
	v_pk_mul_f32 v[70:71], v[2:3], v[150:151]
	v_pk_mul_f32 v[68:69], v[0:1], v[68:69]
	v_pk_mul_f32 v[74:75], v[14:15], v[72:73]
	v_pk_mul_f32 v[72:73], v[12:13], v[152:153]
	v_pk_mul_f32 v[78:79], v[10:11], v[154:155]
	v_pk_mul_f32 v[76:77], v[8:9], v[76:77]
	v_pk_mul_f32 v[82:83], v[22:23], v[80:81]
	v_pk_mul_f32 v[80:81], v[20:21], v[156:157]
	global_store_dwordx4 v[164:165], v[64:67], off nt
	global_store_dwordx4 v[164:165], v[68:71], off offset:16 nt
	global_store_dwordx4 v[164:165], v[72:75], off offset:2048 nt
	global_store_dwordx4 v[164:165], v[76:79], off offset:2064 nt
	v_pk_mul_f32 v[100:101], v[100:101], v[126:127] op_sel_hi:[1,0]
	v_pk_mul_f32 v[182:183], v[98:99], v[126:127] op_sel_hi:[1,0]
	v_pk_mul_f32 v[184:185], v[102:103], v[126:127] op_sel_hi:[1,0]
	v_pk_mul_f32 v[104:105], v[104:105], v[126:127] op_sel_hi:[1,0]
	v_pk_mul_f32 v[108:109], v[108:109], v[126:127] op_sel_hi:[1,0]
	v_pk_mul_f32 v[186:187], v[106:107], v[126:127] op_sel_hi:[1,0]
	v_pk_mul_f32 v[188:189], v[110:111], v[126:127] op_sel_hi:[1,0]
	v_pk_mul_f32 v[112:113], v[112:113], v[126:127] op_sel_hi:[1,0]
	v_pk_mul_f32 v[86:87], v[18:19], v[166:167]
	v_pk_mul_f32 v[84:85], v[16:17], v[84:85]
	v_pk_mul_f32 v[90:91], v[30:31], v[88:89]
	v_pk_mul_f32 v[88:89], v[28:29], v[168:169]
	v_pk_mul_f32 v[94:95], v[26:27], v[178:179]
	v_pk_mul_f32 v[92:93], v[24:25], v[92:93]
	v_pk_mul_f32 v[98:99], v[38:39], v[96:97]
	v_pk_mul_f32 v[96:97], v[36:37], v[180:181]
	global_store_dwordx4 v[162:163], v[80:83], off nt
	global_store_dwordx4 v[162:163], v[84:87], off offset:16 nt
	global_store_dwordx4 v[162:163], v[88:91], off offset:2048 nt
	global_store_dwordx4 v[162:163], v[92:95], off offset:2064 nt
	v_pk_mul_f32 v[120:121], v[120:121], v[126:127] op_sel_hi:[1,0]
	v_pk_mul_f32 v[190:191], v[114:115], v[126:127] op_sel_hi:[1,0]
	v_pk_mul_f32 v[192:193], v[122:123], v[126:127] op_sel_hi:[1,0]
	v_pk_mul_f32 v[122:123], v[116:117], v[126:127] op_sel_hi:[1,0]
	v_pk_mul_f32 v[124:125], v[124:125], v[126:127] op_sel_hi:[1,0]
	v_pk_mul_f32 v[126:127], v[118:119], v[126:127] op_sel_hi:[1,0]
	v_pk_mul_f32 v[102:103], v[34:35], v[182:183]
	v_pk_mul_f32 v[100:101], v[32:33], v[100:101]
	v_pk_mul_f32 v[106:107], v[46:47], v[104:105]
	v_pk_mul_f32 v[104:105], v[44:45], v[184:185]
	v_pk_mul_f32 v[110:111], v[42:43], v[186:187]
	v_pk_mul_f32 v[108:109], v[40:41], v[108:109]
	v_pk_mul_f32 v[114:115], v[54:55], v[112:113]
	v_pk_mul_f32 v[112:113], v[52:53], v[188:189]
	global_store_dwordx4 v[160:161], v[96:99], off nt
	global_store_dwordx4 v[160:161], v[100:103], off offset:16 nt
	global_store_dwordx4 v[160:161], v[104:107], off offset:2048 nt
	global_store_dwordx4 v[160:161], v[108:111], off offset:2064 nt
	v_pk_mul_f32 v[118:119], v[50:51], v[190:191]
	v_pk_mul_f32 v[116:117], v[48:49], v[120:121]
	v_pk_mul_f32 v[122:123], v[62:63], v[122:123]
	v_pk_mul_f32 v[120:121], v[60:61], v[192:193]
	v_pk_mul_f32 v[126:127], v[58:59], v[126:127]
	v_pk_mul_f32 v[124:125], v[56:57], v[124:125]
	global_store_dwordx4 v[158:159], v[112:115], off nt
	global_store_dwordx4 v[158:159], v[116:119], off offset:16 nt
	global_store_dwordx4 v[158:159], v[120:123], off offset:2048 nt
	global_store_dwordx4 v[158:159], v[124:127], off offset:2064 nt
	s_cbranch_scc0 .LBB0_985
	s_add_i32 s14, s14, s15
	s_add_i32 s20, s20, s21
	s_add_i32 s2, s2, s21
	s_cmpk_gt_i32 s14, 0x7ff
	s_cbranch_scc0 .LBB0_984
